# v12 + first LDS-DMA piece of each load segment issued before the segment's last ds_read group (TA starts earlier)
# baseline (speedup 1.0000x reference)
.LBB0_642:
	ds_read_b128 v[148:151], v139
	ds_read_b128 v[152:155], v139 offset:1024
	ds_read_b128 v[156:159], v139 offset:2048
	ds_read_b128 v[160:163], v139 offset:3072
	ds_read_b128 v[164:167], v140
	ds_read_b128 v[168:171], v140 offset:1024
	ds_read_b128 v[172:175], v140 offset:2048
	ds_read_b128 v[176:179], v140 offset:3072
	s_add_i32 s18, s71, 0xffe80080
	s_cmp_eq_u32 s58, s73
	s_cselect_b32 s74, s69, s18
	s_cselect_b32 s76, s70, s72
	s_or_b32 s75, s74, 0x80
	s_add_i32 s18, s71, 0xfff80000
	s_mov_b32 m0, s59
	s_nop 0
	buffer_load_dwordx4 v137, s[12:15], s18 offen lds
	ds_read_b128 v[180:183], v141
	ds_read_b128 v[184:187], v141 offset:1024
	ds_read_b128 v[188:191], v141 offset:2048
	ds_read_b128 v[192:195], v141 offset:3072
	ds_read_b128 v[196:199], v141 offset:4096
	ds_read_b128 v[200:203], v141 offset:5120
	ds_read_b128 v[204:207], v141 offset:6144
	ds_read_b128 v[208:211], v141 offset:7168
	s_mov_b32 m0, s60
	s_nop 0
	buffer_load_dwordx4 v137, s[12:15], s71 offen lds
	s_waitcnt vmcnt(8)
	s_waitcnt lgkmcnt(0)
	s_setprio 1
	v_mfma_f32_16x16x32_bf16 v[118:121], v[148:151], v[180:183], v[118:121]
	s_barrier
	v_mfma_f32_16x16x32_bf16 v[118:121], v[152:155], v[184:187], v[118:121]
	v_mfma_f32_16x16x32_bf16 v[114:117], v[156:159], v[180:183], v[114:117]
	v_mfma_f32_16x16x32_bf16 v[114:117], v[160:163], v[184:187], v[114:117]
	v_mfma_f32_16x16x32_bf16 v[126:129], v[164:167], v[180:183], v[126:129]
	v_mfma_f32_16x16x32_bf16 v[126:129], v[168:171], v[184:187], v[126:129]
	v_mfma_f32_16x16x32_bf16 v[122:125], v[172:175], v[180:183], v[122:125]
	v_mfma_f32_16x16x32_bf16 v[122:125], v[176:179], v[184:187], v[122:125]
	v_mfma_f32_16x16x32_bf16 v[98:101], v[172:175], v[188:191], v[98:101]
	v_mfma_f32_16x16x32_bf16 v[98:101], v[176:179], v[192:195], v[98:101]
	v_mfma_f32_16x16x32_bf16 v[106:109], v[164:167], v[188:191], v[106:109]
	v_mfma_f32_16x16x32_bf16 v[106:109], v[168:171], v[192:195], v[106:109]
	v_mfma_f32_16x16x32_bf16 v[102:105], v[156:159], v[188:191], v[102:105]
	v_mfma_f32_16x16x32_bf16 v[102:105], v[160:163], v[192:195], v[102:105]
	v_mfma_f32_16x16x32_bf16 v[110:113], v[148:151], v[188:191], v[110:113]
	v_mfma_f32_16x16x32_bf16 v[110:113], v[152:155], v[192:195], v[110:113]
	v_mfma_f32_16x16x32_bf16 v[94:97], v[148:151], v[196:199], v[94:97]
	v_mfma_f32_16x16x32_bf16 v[94:97], v[152:155], v[200:203], v[94:97]
	v_mfma_f32_16x16x32_bf16 v[86:89], v[156:159], v[196:199], v[86:89]
	v_mfma_f32_16x16x32_bf16 v[86:89], v[160:163], v[200:203], v[86:89]
	v_mfma_f32_16x16x32_bf16 v[90:93], v[164:167], v[196:199], v[90:93]
	v_mfma_f32_16x16x32_bf16 v[90:93], v[168:171], v[200:203], v[90:93]
	v_mfma_f32_16x16x32_bf16 v[82:85], v[172:175], v[196:199], v[82:85]
	v_mfma_f32_16x16x32_bf16 v[82:85], v[176:179], v[200:203], v[82:85]
	v_mfma_f32_16x16x32_bf16 v[70:73], v[172:175], v[204:207], v[70:73]
	v_mfma_f32_16x16x32_bf16 v[70:73], v[176:179], v[208:211], v[70:73]
	v_mfma_f32_16x16x32_bf16 v[74:77], v[164:167], v[204:207], v[74:77]
	v_mfma_f32_16x16x32_bf16 v[74:77], v[168:171], v[208:211], v[74:77]
	v_mfma_f32_16x16x32_bf16 v[66:69], v[156:159], v[204:207], v[66:69]
	v_mfma_f32_16x16x32_bf16 v[66:69], v[160:163], v[208:211], v[66:69]
	v_mfma_f32_16x16x32_bf16 v[78:81], v[148:151], v[204:207], v[78:81]
	v_mfma_f32_16x16x32_bf16 v[78:81], v[152:155], v[208:211], v[78:81]
	s_setprio 0
	s_barrier
	s_mov_b32 m0, s30
	s_mov_b32 s18, s14
	s_mov_b32 s19, s15
	buffer_load_dwordx4 v138, s[16:19], s76 offen lds
	ds_read_b128 v[180:183], v141 offset:16384
	ds_read_b128 v[184:187], v141 offset:17408
	ds_read_b128 v[188:191], v141 offset:18432
	ds_read_b128 v[192:195], v141 offset:19456
	ds_read_b128 v[196:199], v141 offset:20480
	ds_read_b128 v[200:203], v141 offset:21504
	ds_read_b128 v[204:207], v141 offset:22528
	ds_read_b128 v[208:211], v141 offset:23552
	s_add_i32 s77, s76, 0x80000
	s_mov_b32 m0, s31
	s_nop 0
	buffer_load_dwordx4 v138, s[16:19], s77 offen lds
	s_add_i32 s77, s76, 0x100000
	s_mov_b32 m0, s44
	s_nop 0
	buffer_load_dwordx4 v138, s[16:19], s77 offen lds
	s_add_i32 s77, s76, 0x180000
	s_mov_b32 m0, s45
	s_nop 0
	buffer_load_dwordx4 v138, s[16:19], s77 offen lds
	s_mov_b32 m0, s27
	s_add_i32 s77, s74, 0x80000
	buffer_load_dwordx4 v137, s[12:15], s74 offen lds
	s_mov_b32 m0, s46
	s_nop 0
	buffer_load_dwordx4 v137, s[12:15], s77 offen lds
	s_waitcnt vmcnt(8)
	s_waitcnt lgkmcnt(0)
	s_setprio 1
	v_mfma_f32_16x16x32_bf16 v[62:65], v[148:151], v[180:183], v[62:65]
	s_barrier
	v_mfma_f32_16x16x32_bf16 v[62:65], v[152:155], v[184:187], v[62:65]
	v_mfma_f32_16x16x32_bf16 v[54:57], v[156:159], v[180:183], v[54:57]
	v_mfma_f32_16x16x32_bf16 v[54:57], v[160:163], v[184:187], v[54:57]
	v_mfma_f32_16x16x32_bf16 v[58:61], v[164:167], v[180:183], v[58:61]
	v_mfma_f32_16x16x32_bf16 v[58:61], v[168:171], v[184:187], v[58:61]
	v_mfma_f32_16x16x32_bf16 v[50:53], v[172:175], v[180:183], v[50:53]
	v_mfma_f32_16x16x32_bf16 v[50:53], v[176:179], v[184:187], v[50:53]
	v_mfma_f32_16x16x32_bf16 v[34:37], v[172:175], v[188:191], v[34:37]
	v_mfma_f32_16x16x32_bf16 v[34:37], v[176:179], v[192:195], v[34:37]
	v_mfma_f32_16x16x32_bf16 v[42:45], v[164:167], v[188:191], v[42:45]
	v_mfma_f32_16x16x32_bf16 v[42:45], v[168:171], v[192:195], v[42:45]
	v_mfma_f32_16x16x32_bf16 v[38:41], v[156:159], v[188:191], v[38:41]
	v_mfma_f32_16x16x32_bf16 v[38:41], v[160:163], v[192:195], v[38:41]
	v_mfma_f32_16x16x32_bf16 v[46:49], v[148:151], v[188:191], v[46:49]
	v_mfma_f32_16x16x32_bf16 v[46:49], v[152:155], v[192:195], v[46:49]
	v_mfma_f32_16x16x32_bf16 v[30:33], v[148:151], v[196:199], v[30:33]
	v_mfma_f32_16x16x32_bf16 v[30:33], v[152:155], v[200:203], v[30:33]
	v_mfma_f32_16x16x32_bf16 v[22:25], v[156:159], v[196:199], v[22:25]
	v_mfma_f32_16x16x32_bf16 v[22:25], v[160:163], v[200:203], v[22:25]
	v_mfma_f32_16x16x32_bf16 v[26:29], v[164:167], v[196:199], v[26:29]
	v_mfma_f32_16x16x32_bf16 v[26:29], v[168:171], v[200:203], v[26:29]
	v_mfma_f32_16x16x32_bf16 v[18:21], v[172:175], v[196:199], v[18:21]
	v_mfma_f32_16x16x32_bf16 v[18:21], v[176:179], v[200:203], v[18:21]
	v_mfma_f32_16x16x32_bf16 v[2:5], v[172:175], v[204:207], v[2:5]
	v_mfma_f32_16x16x32_bf16 v[2:5], v[176:179], v[208:211], v[2:5]
	v_mfma_f32_16x16x32_bf16 v[10:13], v[164:167], v[204:207], v[10:13]
	v_mfma_f32_16x16x32_bf16 v[10:13], v[168:171], v[208:211], v[10:13]
	v_mfma_f32_16x16x32_bf16 v[6:9], v[156:159], v[204:207], v[6:9]
	v_mfma_f32_16x16x32_bf16 v[6:9], v[160:163], v[208:211], v[6:9]
	v_mfma_f32_16x16x32_bf16 v[14:17], v[148:151], v[204:207], v[14:17]
	v_mfma_f32_16x16x32_bf16 v[14:17], v[152:155], v[208:211], v[14:17]
	s_setprio 0
	s_barrier
	ds_read_b128 v[148:151], v142
	ds_read_b128 v[152:155], v142 offset:1024
	ds_read_b128 v[156:159], v142 offset:2048
	ds_read_b128 v[160:163], v142 offset:3072
	ds_read_b128 v[164:167], v143
	ds_read_b128 v[168:171], v143 offset:1024
	ds_read_b128 v[172:175], v143 offset:2048
	ds_read_b128 v[176:179], v143 offset:3072
	s_mov_b32 m0, s47
	s_add_i32 s77, s74, 0x100000
	buffer_load_dwordx4 v137, s[12:15], s77 offen lds
	ds_read_b128 v[180:183], v141 offset:32768
	ds_read_b128 v[184:187], v141 offset:33792
	ds_read_b128 v[188:191], v141 offset:34816
	ds_read_b128 v[192:195], v141 offset:35840
	ds_read_b128 v[196:199], v141 offset:36864
	ds_read_b128 v[200:203], v141 offset:37888
	ds_read_b128 v[204:207], v141 offset:38912
	ds_read_b128 v[208:211], v141 offset:39936
	s_add_i32 s77, s74, 0x180000
	s_mov_b32 m0, s48
	s_nop 0
	buffer_load_dwordx4 v137, s[12:15], s77 offen lds
	s_waitcnt vmcnt(8)
	s_waitcnt lgkmcnt(0)
	s_setprio 1
	v_mfma_f32_16x16x32_bf16 v[118:121], v[148:151], v[180:183], v[118:121]
	s_barrier
	v_mfma_f32_16x16x32_bf16 v[118:121], v[152:155], v[184:187], v[118:121]
	v_mfma_f32_16x16x32_bf16 v[114:117], v[156:159], v[180:183], v[114:117]
	v_mfma_f32_16x16x32_bf16 v[114:117], v[160:163], v[184:187], v[114:117]
	v_mfma_f32_16x16x32_bf16 v[126:129], v[164:167], v[180:183], v[126:129]
	v_mfma_f32_16x16x32_bf16 v[126:129], v[168:171], v[184:187], v[126:129]
	v_mfma_f32_16x16x32_bf16 v[122:125], v[172:175], v[180:183], v[122:125]
	v_mfma_f32_16x16x32_bf16 v[122:125], v[176:179], v[184:187], v[122:125]
	v_mfma_f32_16x16x32_bf16 v[98:101], v[172:175], v[188:191], v[98:101]
	v_mfma_f32_16x16x32_bf16 v[98:101], v[176:179], v[192:195], v[98:101]
	v_mfma_f32_16x16x32_bf16 v[106:109], v[164:167], v[188:191], v[106:109]
	v_mfma_f32_16x16x32_bf16 v[106:109], v[168:171], v[192:195], v[106:109]
	v_mfma_f32_16x16x32_bf16 v[102:105], v[156:159], v[188:191], v[102:105]
	v_mfma_f32_16x16x32_bf16 v[102:105], v[160:163], v[192:195], v[102:105]
	v_mfma_f32_16x16x32_bf16 v[110:113], v[148:151], v[188:191], v[110:113]
	v_mfma_f32_16x16x32_bf16 v[110:113], v[152:155], v[192:195], v[110:113]
	v_mfma_f32_16x16x32_bf16 v[94:97], v[148:151], v[196:199], v[94:97]
	v_mfma_f32_16x16x32_bf16 v[94:97], v[152:155], v[200:203], v[94:97]
	v_mfma_f32_16x16x32_bf16 v[86:89], v[156:159], v[196:199], v[86:89]
	v_mfma_f32_16x16x32_bf16 v[86:89], v[160:163], v[200:203], v[86:89]
	v_mfma_f32_16x16x32_bf16 v[90:93], v[164:167], v[196:199], v[90:93]
	v_mfma_f32_16x16x32_bf16 v[90:93], v[168:171], v[200:203], v[90:93]
	v_mfma_f32_16x16x32_bf16 v[82:85], v[172:175], v[196:199], v[82:85]
	v_mfma_f32_16x16x32_bf16 v[82:85], v[176:179], v[200:203], v[82:85]
	v_mfma_f32_16x16x32_bf16 v[70:73], v[172:175], v[204:207], v[70:73]
	v_mfma_f32_16x16x32_bf16 v[70:73], v[176:179], v[208:211], v[70:73]
	v_mfma_f32_16x16x32_bf16 v[74:77], v[164:167], v[204:207], v[74:77]
	v_mfma_f32_16x16x32_bf16 v[74:77], v[168:171], v[208:211], v[74:77]
	v_mfma_f32_16x16x32_bf16 v[66:69], v[156:159], v[204:207], v[66:69]
	v_mfma_f32_16x16x32_bf16 v[66:69], v[160:163], v[208:211], v[66:69]
	v_mfma_f32_16x16x32_bf16 v[78:81], v[148:151], v[204:207], v[78:81]
	v_mfma_f32_16x16x32_bf16 v[78:81], v[152:155], v[208:211], v[78:81]
	s_setprio 0
	s_barrier
	s_mov_b32 m0, s50
	s_or_b32 s77, s76, 0x80
	buffer_load_dwordx4 v138, s[16:19], s77 offen lds
	ds_read_b128 v[180:183], v141 offset:49152
	ds_read_b128 v[184:187], v141 offset:50176
	ds_read_b128 v[188:191], v141 offset:51200
	ds_read_b128 v[192:195], v141 offset:52224
	ds_read_b128 v[196:199], v141 offset:53248
	ds_read_b128 v[200:203], v141 offset:54272
	ds_read_b128 v[204:207], v141 offset:55296
	ds_read_b128 v[208:211], v141 offset:56320
	s_add_i32 s77, s76, 0x80080
	s_mov_b32 m0, s51
	s_add_i32 s74, s74, 0x80080
	buffer_load_dwordx4 v138, s[16:19], s77 offen lds
	s_add_i32 s77, s76, 0x100080
	s_mov_b32 m0, s54
	s_add_i32 s76, s76, 0x180080
	buffer_load_dwordx4 v138, s[16:19], s77 offen lds
	s_mov_b32 m0, s55
	s_nop 0
	buffer_load_dwordx4 v138, s[16:19], s76 offen lds
	s_mov_b32 m0, s52
	s_nop 0
	buffer_load_dwordx4 v137, s[12:15], s75 offen lds
	s_mov_b32 m0, s53
	s_nop 0
	buffer_load_dwordx4 v137, s[12:15], s74 offen lds
	s_waitcnt vmcnt(8)
	s_waitcnt lgkmcnt(0)
	s_setprio 1
	v_mfma_f32_16x16x32_bf16 v[62:65], v[148:151], v[180:183], v[62:65]
	s_barrier
	v_mfma_f32_16x16x32_bf16 v[62:65], v[152:155], v[184:187], v[62:65]
	v_mfma_f32_16x16x32_bf16 v[54:57], v[156:159], v[180:183], v[54:57]
	v_mfma_f32_16x16x32_bf16 v[54:57], v[160:163], v[184:187], v[54:57]
	v_mfma_f32_16x16x32_bf16 v[58:61], v[164:167], v[180:183], v[58:61]
	v_mfma_f32_16x16x32_bf16 v[58:61], v[168:171], v[184:187], v[58:61]
	v_mfma_f32_16x16x32_bf16 v[50:53], v[172:175], v[180:183], v[50:53]
	v_mfma_f32_16x16x32_bf16 v[50:53], v[176:179], v[184:187], v[50:53]
	v_mfma_f32_16x16x32_bf16 v[34:37], v[172:175], v[188:191], v[34:37]
	v_mfma_f32_16x16x32_bf16 v[34:37], v[176:179], v[192:195], v[34:37]
	v_mfma_f32_16x16x32_bf16 v[42:45], v[164:167], v[188:191], v[42:45]
	v_mfma_f32_16x16x32_bf16 v[42:45], v[168:171], v[192:195], v[42:45]
	v_mfma_f32_16x16x32_bf16 v[38:41], v[156:159], v[188:191], v[38:41]
	v_mfma_f32_16x16x32_bf16 v[38:41], v[160:163], v[192:195], v[38:41]
	v_mfma_f32_16x16x32_bf16 v[46:49], v[148:151], v[188:191], v[46:49]
	v_mfma_f32_16x16x32_bf16 v[46:49], v[152:155], v[192:195], v[46:49]
	v_mfma_f32_16x16x32_bf16 v[30:33], v[148:151], v[196:199], v[30:33]
	v_mfma_f32_16x16x32_bf16 v[30:33], v[152:155], v[200:203], v[30:33]
	v_mfma_f32_16x16x32_bf16 v[22:25], v[156:159], v[196:199], v[22:25]
	v_mfma_f32_16x16x32_bf16 v[22:25], v[160:163], v[200:203], v[22:25]
	v_mfma_f32_16x16x32_bf16 v[26:29], v[164:167], v[196:199], v[26:29]
	v_mfma_f32_16x16x32_bf16 v[26:29], v[168:171], v[200:203], v[26:29]
	v_mfma_f32_16x16x32_bf16 v[18:21], v[172:175], v[196:199], v[18:21]
	v_mfma_f32_16x16x32_bf16 v[18:21], v[176:179], v[200:203], v[18:21]
	v_mfma_f32_16x16x32_bf16 v[2:5], v[172:175], v[204:207], v[2:5]
	v_mfma_f32_16x16x32_bf16 v[2:5], v[176:179], v[208:211], v[2:5]
	v_mfma_f32_16x16x32_bf16 v[10:13], v[164:167], v[204:207], v[10:13]
	v_mfma_f32_16x16x32_bf16 v[10:13], v[168:171], v[208:211], v[10:13]
	v_mfma_f32_16x16x32_bf16 v[6:9], v[156:159], v[204:207], v[6:9]
	v_mfma_f32_16x16x32_bf16 v[6:9], v[160:163], v[208:211], v[6:9]
	v_mfma_f32_16x16x32_bf16 v[14:17], v[148:151], v[204:207], v[14:17]
	v_mfma_f32_16x16x32_bf16 v[14:17], v[152:155], v[208:211], v[14:17]
	s_setprio 0
	s_barrier
	s_add_i32 s73, s73, 2
	s_addk_i32 s71, 0x100
	s_addk_i32 s72, 0x100
	s_cmp_ge_i32 s73, s3
	s_cbranch_scc0 .LBB0_642
	s_and_b64 vcc, exec, s[42:43]
	s_cbranch_vccz .LBB0_645

.LBB0_799:
	ds_read_b128 v[134:137], v210
	ds_read_b128 v[138:141], v210 offset:1024
	ds_read_b128 v[142:145], v210 offset:2048
	ds_read_b128 v[148:151], v210 offset:3072
	ds_read_b128 v[152:155], v211
	ds_read_b128 v[156:159], v211 offset:1024
	ds_read_b128 v[160:163], v211 offset:2048
	ds_read_b128 v[164:167], v211 offset:3072
	s_add_i32 s18, s77, 0xffbf8080
	s_cmp_eq_u32 s62, s79
	s_cselect_b32 s80, s6, s18
	s_cselect_b32 s82, s7, s78
	s_or_b32 s81, s80, 0x80
	s_add_i32 s18, s77, 0xffea8000
	s_mov_b32 m0, s63
	s_nop 0
	buffer_load_dwordx4 v208, s[12:15], s18 offen lds
	ds_read_b128 v[168:171], v212
	ds_read_b128 v[172:175], v212 offset:1024
	ds_read_b128 v[176:179], v212 offset:2048
	ds_read_b128 v[180:183], v212 offset:3072
	ds_read_b128 v[184:187], v212 offset:4096
	ds_read_b128 v[188:191], v212 offset:5120
	ds_read_b128 v[192:195], v212 offset:6144
	ds_read_b128 v[196:199], v212 offset:7168
	s_mov_b32 m0, s66
	s_nop 0
	buffer_load_dwordx4 v208, s[12:15], s77 offen lds
	s_waitcnt vmcnt(8)
	s_waitcnt lgkmcnt(0)
	s_setprio 1
	v_mfma_f32_16x16x32_bf16 v[126:129], v[134:137], v[168:171], v[126:129]
	s_barrier
	v_mfma_f32_16x16x32_bf16 v[126:129], v[138:141], v[172:175], v[126:129]
	v_mfma_f32_16x16x32_bf16 v[122:125], v[142:145], v[168:171], v[122:125]
	v_mfma_f32_16x16x32_bf16 v[122:125], v[148:151], v[172:175], v[122:125]
	v_mfma_f32_16x16x32_bf16 v[110:113], v[152:155], v[168:171], v[110:113]
	v_mfma_f32_16x16x32_bf16 v[110:113], v[156:159], v[172:175], v[110:113]
	v_mfma_f32_16x16x32_bf16 v[102:105], v[160:163], v[168:171], v[102:105]
	v_mfma_f32_16x16x32_bf16 v[102:105], v[164:167], v[172:175], v[102:105]
	v_mfma_f32_16x16x32_bf16 v[86:89], v[160:163], v[176:179], v[86:89]
	v_mfma_f32_16x16x32_bf16 v[86:89], v[164:167], v[180:183], v[86:89]
	v_mfma_f32_16x16x32_bf16 v[94:97], v[152:155], v[176:179], v[94:97]
	v_mfma_f32_16x16x32_bf16 v[94:97], v[156:159], v[180:183], v[94:97]
	v_mfma_f32_16x16x32_bf16 v[114:117], v[142:145], v[176:179], v[114:117]
	v_mfma_f32_16x16x32_bf16 v[114:117], v[148:151], v[180:183], v[114:117]
	v_mfma_f32_16x16x32_bf16 v[118:121], v[134:137], v[176:179], v[118:121]
	v_mfma_f32_16x16x32_bf16 v[118:121], v[138:141], v[180:183], v[118:121]
	v_mfma_f32_16x16x32_bf16 v[106:109], v[134:137], v[184:187], v[106:109]
	v_mfma_f32_16x16x32_bf16 v[106:109], v[138:141], v[188:191], v[106:109]
	v_mfma_f32_16x16x32_bf16 v[98:101], v[142:145], v[184:187], v[98:101]
	v_mfma_f32_16x16x32_bf16 v[98:101], v[148:151], v[188:191], v[98:101]
	v_mfma_f32_16x16x32_bf16 v[78:81], v[152:155], v[184:187], v[78:81]
	v_mfma_f32_16x16x32_bf16 v[78:81], v[156:159], v[188:191], v[78:81]
	v_mfma_f32_16x16x32_bf16 v[74:77], v[160:163], v[184:187], v[74:77]
	v_mfma_f32_16x16x32_bf16 v[74:77], v[164:167], v[188:191], v[74:77]
	v_mfma_f32_16x16x32_bf16 v[66:69], v[160:163], v[192:195], v[66:69]
	v_mfma_f32_16x16x32_bf16 v[66:69], v[164:167], v[196:199], v[66:69]
	v_mfma_f32_16x16x32_bf16 v[70:73], v[152:155], v[192:195], v[70:73]
	v_mfma_f32_16x16x32_bf16 v[70:73], v[156:159], v[196:199], v[70:73]
	v_mfma_f32_16x16x32_bf16 v[82:85], v[142:145], v[192:195], v[82:85]
	v_mfma_f32_16x16x32_bf16 v[82:85], v[148:151], v[196:199], v[82:85]
	v_mfma_f32_16x16x32_bf16 v[90:93], v[134:137], v[192:195], v[90:93]
	v_mfma_f32_16x16x32_bf16 v[90:93], v[138:141], v[196:199], v[90:93]
	s_setprio 0
	s_barrier
	s_mov_b32 m0, s25
	s_mov_b32 s18, s14
	s_mov_b32 s19, s15
	buffer_load_dwordx4 v209, s[16:19], s82 offen lds
	ds_read_b128 v[168:171], v212 offset:16384
	ds_read_b128 v[172:175], v212 offset:17408
	ds_read_b128 v[176:179], v212 offset:18432
	ds_read_b128 v[180:183], v212 offset:19456
	ds_read_b128 v[184:187], v212 offset:20480
	ds_read_b128 v[188:191], v212 offset:21504
	ds_read_b128 v[192:195], v212 offset:22528
	ds_read_b128 v[196:199], v212 offset:23552
	s_add_i32 s83, s82, 0x158000
	s_mov_b32 m0, s27
	s_nop 0
	buffer_load_dwordx4 v209, s[16:19], s83 offen lds
	s_add_i32 s83, s82, 0x2b0000
	s_mov_b32 m0, s30
	s_nop 0
	buffer_load_dwordx4 v209, s[16:19], s83 offen lds
	s_add_i32 s83, s82, 0x408000
	s_mov_b32 m0, s31
	s_nop 0
	buffer_load_dwordx4 v209, s[16:19], s83 offen lds
	s_mov_b32 m0, s21
	s_add_i32 s83, s80, 0x158000
	buffer_load_dwordx4 v208, s[12:15], s80 offen lds
	s_mov_b32 m0, s48
	s_nop 0
	buffer_load_dwordx4 v208, s[12:15], s83 offen lds
	s_waitcnt vmcnt(8)
	s_waitcnt lgkmcnt(0)
	s_setprio 1
	v_mfma_f32_16x16x32_bf16 v[62:65], v[134:137], v[168:171], v[62:65]
	s_barrier
	v_mfma_f32_16x16x32_bf16 v[62:65], v[138:141], v[172:175], v[62:65]
	v_mfma_f32_16x16x32_bf16 v[58:61], v[142:145], v[168:171], v[58:61]
	v_mfma_f32_16x16x32_bf16 v[58:61], v[148:151], v[172:175], v[58:61]
	v_mfma_f32_16x16x32_bf16 v[46:49], v[152:155], v[168:171], v[46:49]
	v_mfma_f32_16x16x32_bf16 v[46:49], v[156:159], v[172:175], v[46:49]
	v_mfma_f32_16x16x32_bf16 v[38:41], v[160:163], v[168:171], v[38:41]
	v_mfma_f32_16x16x32_bf16 v[38:41], v[164:167], v[172:175], v[38:41]
	v_mfma_f32_16x16x32_bf16 v[22:25], v[160:163], v[176:179], v[22:25]
	v_mfma_f32_16x16x32_bf16 v[22:25], v[164:167], v[180:183], v[22:25]
	v_mfma_f32_16x16x32_bf16 v[30:33], v[152:155], v[176:179], v[30:33]
	v_mfma_f32_16x16x32_bf16 v[30:33], v[156:159], v[180:183], v[30:33]
	v_mfma_f32_16x16x32_bf16 v[50:53], v[142:145], v[176:179], v[50:53]
	v_mfma_f32_16x16x32_bf16 v[50:53], v[148:151], v[180:183], v[50:53]
	v_mfma_f32_16x16x32_bf16 v[54:57], v[134:137], v[176:179], v[54:57]
	v_mfma_f32_16x16x32_bf16 v[54:57], v[138:141], v[180:183], v[54:57]
	v_mfma_f32_16x16x32_bf16 v[42:45], v[134:137], v[184:187], v[42:45]
	v_mfma_f32_16x16x32_bf16 v[42:45], v[138:141], v[188:191], v[42:45]
	v_mfma_f32_16x16x32_bf16 v[34:37], v[142:145], v[184:187], v[34:37]
	v_mfma_f32_16x16x32_bf16 v[34:37], v[148:151], v[188:191], v[34:37]
	v_mfma_f32_16x16x32_bf16 v[14:17], v[152:155], v[184:187], v[14:17]
	v_mfma_f32_16x16x32_bf16 v[14:17], v[156:159], v[188:191], v[14:17]
	v_mfma_f32_16x16x32_bf16 v[10:13], v[160:163], v[184:187], v[10:13]
	v_mfma_f32_16x16x32_bf16 v[10:13], v[164:167], v[188:191], v[10:13]
	v_mfma_f32_16x16x32_bf16 v[2:5], v[160:163], v[192:195], v[2:5]
	v_mfma_f32_16x16x32_bf16 v[2:5], v[164:167], v[196:199], v[2:5]
	v_mfma_f32_16x16x32_bf16 v[6:9], v[152:155], v[192:195], v[6:9]
	v_mfma_f32_16x16x32_bf16 v[6:9], v[156:159], v[196:199], v[6:9]
	v_mfma_f32_16x16x32_bf16 v[18:21], v[142:145], v[192:195], v[18:21]
	v_mfma_f32_16x16x32_bf16 v[18:21], v[148:151], v[196:199], v[18:21]
	v_mfma_f32_16x16x32_bf16 v[26:29], v[134:137], v[192:195], v[26:29]
	v_mfma_f32_16x16x32_bf16 v[26:29], v[138:141], v[196:199], v[26:29]
	s_setprio 0
	s_barrier
	ds_read_b128 v[134:137], v213
	ds_read_b128 v[138:141], v213 offset:1024
	ds_read_b128 v[142:145], v213 offset:2048
	ds_read_b128 v[148:151], v213 offset:3072
	ds_read_b128 v[152:155], v214
	ds_read_b128 v[156:159], v214 offset:1024
	ds_read_b128 v[160:163], v214 offset:2048
	ds_read_b128 v[164:167], v214 offset:3072
	s_mov_b32 m0, s49
	s_add_i32 s83, s80, 0x2b0000
	buffer_load_dwordx4 v208, s[12:15], s83 offen lds
	ds_read_b128 v[168:171], v212 offset:32768
	ds_read_b128 v[172:175], v212 offset:33792
	ds_read_b128 v[176:179], v212 offset:34816
	ds_read_b128 v[180:183], v212 offset:35840
	ds_read_b128 v[184:187], v212 offset:36864
	ds_read_b128 v[188:191], v212 offset:37888
	ds_read_b128 v[192:195], v212 offset:38912
	ds_read_b128 v[196:199], v212 offset:39936
	s_add_i32 s83, s80, 0x408000
	s_mov_b32 m0, s50
	s_nop 0
	buffer_load_dwordx4 v208, s[12:15], s83 offen lds
	s_waitcnt vmcnt(8)
	s_waitcnt lgkmcnt(0)
	s_setprio 1
	v_mfma_f32_16x16x32_bf16 v[126:129], v[134:137], v[168:171], v[126:129]
	s_barrier
	v_mfma_f32_16x16x32_bf16 v[126:129], v[138:141], v[172:175], v[126:129]
	v_mfma_f32_16x16x32_bf16 v[122:125], v[142:145], v[168:171], v[122:125]
	v_mfma_f32_16x16x32_bf16 v[122:125], v[148:151], v[172:175], v[122:125]
	v_mfma_f32_16x16x32_bf16 v[110:113], v[152:155], v[168:171], v[110:113]
	v_mfma_f32_16x16x32_bf16 v[110:113], v[156:159], v[172:175], v[110:113]
	v_mfma_f32_16x16x32_bf16 v[102:105], v[160:163], v[168:171], v[102:105]
	v_mfma_f32_16x16x32_bf16 v[102:105], v[164:167], v[172:175], v[102:105]
	v_mfma_f32_16x16x32_bf16 v[86:89], v[160:163], v[176:179], v[86:89]
	v_mfma_f32_16x16x32_bf16 v[86:89], v[164:167], v[180:183], v[86:89]
	v_mfma_f32_16x16x32_bf16 v[94:97], v[152:155], v[176:179], v[94:97]
	v_mfma_f32_16x16x32_bf16 v[94:97], v[156:159], v[180:183], v[94:97]
	v_mfma_f32_16x16x32_bf16 v[114:117], v[142:145], v[176:179], v[114:117]
	v_mfma_f32_16x16x32_bf16 v[114:117], v[148:151], v[180:183], v[114:117]
	v_mfma_f32_16x16x32_bf16 v[118:121], v[134:137], v[176:179], v[118:121]
	v_mfma_f32_16x16x32_bf16 v[118:121], v[138:141], v[180:183], v[118:121]
	v_mfma_f32_16x16x32_bf16 v[106:109], v[134:137], v[184:187], v[106:109]
	v_mfma_f32_16x16x32_bf16 v[106:109], v[138:141], v[188:191], v[106:109]
	v_mfma_f32_16x16x32_bf16 v[98:101], v[142:145], v[184:187], v[98:101]
	v_mfma_f32_16x16x32_bf16 v[98:101], v[148:151], v[188:191], v[98:101]
	v_mfma_f32_16x16x32_bf16 v[78:81], v[152:155], v[184:187], v[78:81]
	v_mfma_f32_16x16x32_bf16 v[78:81], v[156:159], v[188:191], v[78:81]
	v_mfma_f32_16x16x32_bf16 v[74:77], v[160:163], v[184:187], v[74:77]
	v_mfma_f32_16x16x32_bf16 v[74:77], v[164:167], v[188:191], v[74:77]
	v_mfma_f32_16x16x32_bf16 v[66:69], v[160:163], v[192:195], v[66:69]
	v_mfma_f32_16x16x32_bf16 v[66:69], v[164:167], v[196:199], v[66:69]
	v_mfma_f32_16x16x32_bf16 v[70:73], v[152:155], v[192:195], v[70:73]
	v_mfma_f32_16x16x32_bf16 v[70:73], v[156:159], v[196:199], v[70:73]
	v_mfma_f32_16x16x32_bf16 v[82:85], v[142:145], v[192:195], v[82:85]
	v_mfma_f32_16x16x32_bf16 v[82:85], v[148:151], v[196:199], v[82:85]
	v_mfma_f32_16x16x32_bf16 v[90:93], v[134:137], v[192:195], v[90:93]
	v_mfma_f32_16x16x32_bf16 v[90:93], v[138:141], v[196:199], v[90:93]
	s_setprio 0
	s_barrier
	s_mov_b32 m0, s54
	s_or_b32 s83, s82, 0x80
	buffer_load_dwordx4 v209, s[16:19], s83 offen lds
	ds_read_b128 v[168:171], v212 offset:49152
	ds_read_b128 v[172:175], v212 offset:50176
	ds_read_b128 v[176:179], v212 offset:51200
	ds_read_b128 v[180:183], v212 offset:52224
	ds_read_b128 v[184:187], v212 offset:53248
	ds_read_b128 v[188:191], v212 offset:54272
	ds_read_b128 v[192:195], v212 offset:55296
	ds_read_b128 v[196:199], v212 offset:56320
	s_add_i32 s83, s82, 0x158080
	s_mov_b32 m0, s55
	s_add_i32 s80, s80, 0x158080
	buffer_load_dwordx4 v209, s[16:19], s83 offen lds
	s_add_i32 s83, s82, 0x2b0080
	s_mov_b32 m0, s58
	s_add_i32 s82, s82, 0x408080
	buffer_load_dwordx4 v209, s[16:19], s83 offen lds
	s_mov_b32 m0, s59
	s_nop 0
	buffer_load_dwordx4 v209, s[16:19], s82 offen lds
	s_mov_b32 m0, s56
	s_nop 0
	buffer_load_dwordx4 v208, s[12:15], s81 offen lds
	s_mov_b32 m0, s57
	s_nop 0
	buffer_load_dwordx4 v208, s[12:15], s80 offen lds
	s_waitcnt vmcnt(8)
	s_waitcnt lgkmcnt(0)
	s_setprio 1
	v_mfma_f32_16x16x32_bf16 v[62:65], v[134:137], v[168:171], v[62:65]
	s_barrier
	v_mfma_f32_16x16x32_bf16 v[62:65], v[138:141], v[172:175], v[62:65]
	v_mfma_f32_16x16x32_bf16 v[58:61], v[142:145], v[168:171], v[58:61]
	v_mfma_f32_16x16x32_bf16 v[58:61], v[148:151], v[172:175], v[58:61]
	v_mfma_f32_16x16x32_bf16 v[46:49], v[152:155], v[168:171], v[46:49]
	v_mfma_f32_16x16x32_bf16 v[46:49], v[156:159], v[172:175], v[46:49]
	v_mfma_f32_16x16x32_bf16 v[38:41], v[160:163], v[168:171], v[38:41]
	v_mfma_f32_16x16x32_bf16 v[38:41], v[164:167], v[172:175], v[38:41]
	v_mfma_f32_16x16x32_bf16 v[22:25], v[160:163], v[176:179], v[22:25]
	v_mfma_f32_16x16x32_bf16 v[22:25], v[164:167], v[180:183], v[22:25]
	v_mfma_f32_16x16x32_bf16 v[30:33], v[152:155], v[176:179], v[30:33]
	v_mfma_f32_16x16x32_bf16 v[30:33], v[156:159], v[180:183], v[30:33]
	v_mfma_f32_16x16x32_bf16 v[50:53], v[142:145], v[176:179], v[50:53]
	v_mfma_f32_16x16x32_bf16 v[50:53], v[148:151], v[180:183], v[50:53]
	v_mfma_f32_16x16x32_bf16 v[54:57], v[134:137], v[176:179], v[54:57]
	v_mfma_f32_16x16x32_bf16 v[54:57], v[138:141], v[180:183], v[54:57]
	v_mfma_f32_16x16x32_bf16 v[42:45], v[134:137], v[184:187], v[42:45]
	v_mfma_f32_16x16x32_bf16 v[42:45], v[138:141], v[188:191], v[42:45]
	v_mfma_f32_16x16x32_bf16 v[34:37], v[142:145], v[184:187], v[34:37]
	v_mfma_f32_16x16x32_bf16 v[34:37], v[148:151], v[188:191], v[34:37]
	v_mfma_f32_16x16x32_bf16 v[14:17], v[152:155], v[184:187], v[14:17]
	v_mfma_f32_16x16x32_bf16 v[14:17], v[156:159], v[188:191], v[14:17]
	v_mfma_f32_16x16x32_bf16 v[10:13], v[160:163], v[184:187], v[10:13]
	v_mfma_f32_16x16x32_bf16 v[10:13], v[164:167], v[188:191], v[10:13]
	v_mfma_f32_16x16x32_bf16 v[2:5], v[160:163], v[192:195], v[2:5]
	v_mfma_f32_16x16x32_bf16 v[2:5], v[164:167], v[196:199], v[2:5]
	v_mfma_f32_16x16x32_bf16 v[6:9], v[152:155], v[192:195], v[6:9]
	v_mfma_f32_16x16x32_bf16 v[6:9], v[156:159], v[196:199], v[6:9]
	v_mfma_f32_16x16x32_bf16 v[18:21], v[142:145], v[192:195], v[18:21]
	v_mfma_f32_16x16x32_bf16 v[18:21], v[148:151], v[196:199], v[18:21]
	v_mfma_f32_16x16x32_bf16 v[26:29], v[134:137], v[192:195], v[26:29]
	v_mfma_f32_16x16x32_bf16 v[26:29], v[138:141], v[196:199], v[26:29]
	s_setprio 0
	s_barrier
	s_add_i32 s79, s79, 2
	s_addk_i32 s77, 0x100
	s_addk_i32 s78, 0x100
	s_cmp_ge_i32 s79, s3
	s_cbranch_scc0 .LBB0_799
	v_pk_mul_f32 v[184:185], v[128:129], 0.5 op_sel_hi:[1,0]
	v_pk_mul_f32 v[186:187], v[126:127], 0.5 op_sel_hi:[1,0]
	v_pk_mul_f32 v[188:189], v[124:125], 0.5 op_sel_hi:[1,0]
	v_pk_mul_f32 v[190:191], v[122:123], 0.5 op_sel_hi:[1,0]
	v_pk_mul_f32 v[198:199], v[112:113], 0.5 op_sel_hi:[1,0]
	v_pk_mul_f32 v[196:197], v[110:111], 0.5 op_sel_hi:[1,0]
	v_pk_mul_f32 v[194:195], v[104:105], 0.5 op_sel_hi:[1,0]
	v_pk_mul_f32 v[192:193], v[102:103], 0.5 op_sel_hi:[1,0]
	v_pk_mul_f32 v[182:183], v[120:121], 0.5 op_sel_hi:[1,0]
	v_pk_mul_f32 v[180:181], v[118:119], 0.5 op_sel_hi:[1,0]
	v_pk_mul_f32 v[178:179], v[116:117], 0.5 op_sel_hi:[1,0]
	v_pk_mul_f32 v[176:177], v[114:115], 0.5 op_sel_hi:[1,0]
	v_pk_mul_f32 v[172:173], v[96:97], 0.5 op_sel_hi:[1,0]
	v_pk_mul_f32 v[170:171], v[94:95], 0.5 op_sel_hi:[1,0]
	v_pk_mul_f32 v[168:169], v[88:89], 0.5 op_sel_hi:[1,0]
	v_pk_mul_f32 v[166:167], v[86:87], 0.5 op_sel_hi:[1,0]
	v_pk_mul_f32 v[164:165], v[108:109], 0.5 op_sel_hi:[1,0]
	v_pk_mul_f32 v[162:163], v[106:107], 0.5 op_sel_hi:[1,0]
	v_pk_mul_f32 v[160:161], v[100:101], 0.5 op_sel_hi:[1,0]
	v_pk_mul_f32 v[158:159], v[98:99], 0.5 op_sel_hi:[1,0]
	v_pk_mul_f32 v[156:157], v[80:81], 0.5 op_sel_hi:[1,0]
	v_pk_mul_f32 v[154:155], v[78:79], 0.5 op_sel_hi:[1,0]
	v_pk_mul_f32 v[152:153], v[76:77], 0.5 op_sel_hi:[1,0]
	v_pk_mul_f32 v[150:151], v[74:75], 0.5 op_sel_hi:[1,0]
	v_pk_mul_f32 v[144:145], v[92:93], 0.5 op_sel_hi:[1,0]
	v_pk_mul_f32 v[142:143], v[90:91], 0.5 op_sel_hi:[1,0]
	v_pk_mul_f32 v[140:141], v[84:85], 0.5 op_sel_hi:[1,0]
	v_pk_mul_f32 v[138:139], v[82:83], 0.5 op_sel_hi:[1,0]
	v_pk_mul_f32 v[136:137], v[72:73], 0.5 op_sel_hi:[1,0]
	v_pk_mul_f32 v[134:135], v[70:71], 0.5 op_sel_hi:[1,0]
	v_pk_mul_f32 v[128:129], v[68:69], 0.5 op_sel_hi:[1,0]
	v_pk_mul_f32 v[126:127], v[66:67], 0.5 op_sel_hi:[1,0]
	v_pk_mul_f32 v[122:123], v[64:65], 0.5 op_sel_hi:[1,0]
	v_pk_mul_f32 v[120:121], v[62:63], 0.5 op_sel_hi:[1,0]
	v_pk_mul_f32 v[118:119], v[60:61], 0.5 op_sel_hi:[1,0]
	v_pk_mul_f32 v[116:117], v[58:59], 0.5 op_sel_hi:[1,0]
	v_pk_mul_f32 v[112:113], v[48:49], 0.5 op_sel_hi:[1,0]
	v_pk_mul_f32 v[110:111], v[46:47], 0.5 op_sel_hi:[1,0]
	v_pk_mul_f32 v[108:109], v[40:41], 0.5 op_sel_hi:[1,0]
	v_pk_mul_f32 v[106:107], v[38:39], 0.5 op_sel_hi:[1,0]
	v_pk_mul_f32 v[104:105], v[56:57], 0.5 op_sel_hi:[1,0]
	v_pk_mul_f32 v[102:103], v[54:55], 0.5 op_sel_hi:[1,0]
	v_pk_mul_f32 v[100:101], v[52:53], 0.5 op_sel_hi:[1,0]
	v_pk_mul_f32 v[98:99], v[50:51], 0.5 op_sel_hi:[1,0]
	v_pk_mul_f32 v[96:97], v[32:33], 0.5 op_sel_hi:[1,0]
	v_pk_mul_f32 v[94:95], v[30:31], 0.5 op_sel_hi:[1,0]
	v_pk_mul_f32 v[92:93], v[24:25], 0.5 op_sel_hi:[1,0]
	v_pk_mul_f32 v[90:91], v[22:23], 0.5 op_sel_hi:[1,0]
	v_pk_mul_f32 v[88:89], v[44:45], 0.5 op_sel_hi:[1,0]
	v_pk_mul_f32 v[86:87], v[42:43], 0.5 op_sel_hi:[1,0]
	v_pk_mul_f32 v[84:85], v[36:37], 0.5 op_sel_hi:[1,0]
	v_pk_mul_f32 v[82:83], v[34:35], 0.5 op_sel_hi:[1,0]
	v_pk_mul_f32 v[80:81], v[16:17], 0.5 op_sel_hi:[1,0]
	v_pk_mul_f32 v[78:79], v[14:15], 0.5 op_sel_hi:[1,0]
	v_pk_mul_f32 v[76:77], v[12:13], 0.5 op_sel_hi:[1,0]
	v_pk_mul_f32 v[74:75], v[10:11], 0.5 op_sel_hi:[1,0]
	v_pk_mul_f32 v[72:73], v[28:29], 0.5 op_sel_hi:[1,0]
	v_pk_mul_f32 v[70:71], v[26:27], 0.5 op_sel_hi:[1,0]
	v_pk_mul_f32 v[68:69], v[20:21], 0.5 op_sel_hi:[1,0]
	v_pk_mul_f32 v[66:67], v[18:19], 0.5 op_sel_hi:[1,0]
	v_pk_mul_f32 v[64:65], v[8:9], 0.5 op_sel_hi:[1,0]
	v_pk_mul_f32 v[62:63], v[6:7], 0.5 op_sel_hi:[1,0]
	v_pk_mul_f32 v[60:61], v[4:5], 0.5 op_sel_hi:[1,0]
	v_pk_mul_f32 v[58:59], v[2:3], 0.5 op_sel_hi:[1,0]
	s_and_b64 vcc, exec, s[38:39]
	s_cbranch_vccz .LBB0_802

.LBB0_892:
	ds_read_b128 v[130:133], v172
	ds_read_b128 v[134:137], v172 offset:1024
	ds_read_b128 v[148:151], v172 offset:2048
	ds_read_b128 v[152:155], v172 offset:3072
	ds_read_b128 v[156:159], v173
	ds_read_b128 v[160:163], v173 offset:1024
	ds_read_b128 v[164:167], v173 offset:2048
	ds_read_b128 v[180:183], v173 offset:3072
	s_add_i32 s18, s8, 0xffe80080
	s_cmp_eq_u32 s77, s52
	s_cselect_b32 s53, s6, s18
	s_cselect_b32 s58, s7, s9
	s_or_b32 s57, s53, 0x80
	s_add_i32 s18, s8, 0xfff80000
	s_mov_b32 m0, s78
	s_nop 0
	buffer_load_dwordx4 v170, s[12:15], s18 offen lds
	ds_read_b128 v[184:187], v174
	ds_read_b128 v[188:191], v174 offset:1024
	ds_read_b128 v[192:195], v174 offset:2048
	ds_read_b128 v[196:199], v174 offset:3072
	ds_read_b128 v[200:203], v174 offset:4096
	ds_read_b128 v[204:207], v174 offset:5120
	ds_read_b128 v[208:211], v174 offset:6144
	ds_read_b128 v[212:215], v174 offset:7168
	s_mov_b32 m0, s79
	s_nop 0
	buffer_load_dwordx4 v170, s[12:15], s8 offen lds
	s_waitcnt vmcnt(8)
	s_waitcnt lgkmcnt(0)
	s_setprio 1
	v_mfma_f32_16x16x32_bf16 v[126:129], v[130:133], v[184:187], v[126:129]
	s_barrier
	v_mfma_f32_16x16x32_bf16 v[126:129], v[134:137], v[188:191], v[126:129]
	v_mfma_f32_16x16x32_bf16 v[118:121], v[148:151], v[184:187], v[118:121]
	v_mfma_f32_16x16x32_bf16 v[118:121], v[152:155], v[188:191], v[118:121]
	v_mfma_f32_16x16x32_bf16 v[122:125], v[156:159], v[184:187], v[122:125]
	v_mfma_f32_16x16x32_bf16 v[122:125], v[160:163], v[188:191], v[122:125]
	v_mfma_f32_16x16x32_bf16 v[114:117], v[164:167], v[184:187], v[114:117]
	v_mfma_f32_16x16x32_bf16 v[114:117], v[180:183], v[188:191], v[114:117]
	v_mfma_f32_16x16x32_bf16 v[98:101], v[164:167], v[192:195], v[98:101]
	v_mfma_f32_16x16x32_bf16 v[98:101], v[180:183], v[196:199], v[98:101]
	v_mfma_f32_16x16x32_bf16 v[106:109], v[156:159], v[192:195], v[106:109]
	v_mfma_f32_16x16x32_bf16 v[106:109], v[160:163], v[196:199], v[106:109]
	v_mfma_f32_16x16x32_bf16 v[102:105], v[148:151], v[192:195], v[102:105]
	v_mfma_f32_16x16x32_bf16 v[102:105], v[152:155], v[196:199], v[102:105]
	v_mfma_f32_16x16x32_bf16 v[110:113], v[130:133], v[192:195], v[110:113]
	v_mfma_f32_16x16x32_bf16 v[110:113], v[134:137], v[196:199], v[110:113]
	v_mfma_f32_16x16x32_bf16 v[94:97], v[130:133], v[200:203], v[94:97]
	v_mfma_f32_16x16x32_bf16 v[94:97], v[134:137], v[204:207], v[94:97]
	v_mfma_f32_16x16x32_bf16 v[90:93], v[148:151], v[200:203], v[90:93]
	v_mfma_f32_16x16x32_bf16 v[90:93], v[152:155], v[204:207], v[90:93]
	v_mfma_f32_16x16x32_bf16 v[86:89], v[156:159], v[200:203], v[86:89]
	v_mfma_f32_16x16x32_bf16 v[86:89], v[160:163], v[204:207], v[86:89]
	v_mfma_f32_16x16x32_bf16 v[82:85], v[164:167], v[200:203], v[82:85]
	v_mfma_f32_16x16x32_bf16 v[82:85], v[180:183], v[204:207], v[82:85]
	v_mfma_f32_16x16x32_bf16 v[66:69], v[164:167], v[208:211], v[66:69]
	v_mfma_f32_16x16x32_bf16 v[66:69], v[180:183], v[212:215], v[66:69]
	v_mfma_f32_16x16x32_bf16 v[74:77], v[156:159], v[208:211], v[74:77]
	v_mfma_f32_16x16x32_bf16 v[74:77], v[160:163], v[212:215], v[74:77]
	v_mfma_f32_16x16x32_bf16 v[70:73], v[148:151], v[208:211], v[70:73]
	v_mfma_f32_16x16x32_bf16 v[70:73], v[152:155], v[212:215], v[70:73]
	v_mfma_f32_16x16x32_bf16 v[78:81], v[130:133], v[208:211], v[78:81]
	v_mfma_f32_16x16x32_bf16 v[78:81], v[134:137], v[212:215], v[78:81]
	s_setprio 0
	s_barrier
	s_mov_b32 m0, s27
	s_mov_b32 s18, s14
	s_mov_b32 s19, s15
	buffer_load_dwordx4 v171, s[16:19], s58 offen lds
	ds_read_b128 v[184:187], v174 offset:16384
	ds_read_b128 v[188:191], v174 offset:17408
	ds_read_b128 v[192:195], v174 offset:18432
	ds_read_b128 v[196:199], v174 offset:19456
	ds_read_b128 v[200:203], v174 offset:20480
	ds_read_b128 v[204:207], v174 offset:21504
	ds_read_b128 v[208:211], v174 offset:22528
	ds_read_b128 v[212:215], v174 offset:23552
	s_add_i32 s59, s58, 0x80000
	s_mov_b32 m0, s60
	s_nop 0
	buffer_load_dwordx4 v171, s[16:19], s59 offen lds
	s_add_i32 s59, s58, 0x100000
	s_mov_b32 m0, s61
	s_nop 0
	buffer_load_dwordx4 v171, s[16:19], s59 offen lds
	s_add_i32 s59, s58, 0x180000
	s_mov_b32 m0, s62
	s_nop 0
	buffer_load_dwordx4 v171, s[16:19], s59 offen lds
	s_mov_b32 m0, s25
	s_add_i32 s59, s53, 0x80000
	buffer_load_dwordx4 v170, s[12:15], s53 offen lds
	s_mov_b32 m0, s63
	s_nop 0
	buffer_load_dwordx4 v170, s[12:15], s59 offen lds
	s_waitcnt vmcnt(8)
	s_waitcnt lgkmcnt(0)
	s_setprio 1
	v_mfma_f32_16x16x32_bf16 v[62:65], v[130:133], v[184:187], v[62:65]
	s_barrier
	v_mfma_f32_16x16x32_bf16 v[62:65], v[134:137], v[188:191], v[62:65]
	v_mfma_f32_16x16x32_bf16 v[54:57], v[148:151], v[184:187], v[54:57]
	v_mfma_f32_16x16x32_bf16 v[54:57], v[152:155], v[188:191], v[54:57]
	v_mfma_f32_16x16x32_bf16 v[58:61], v[156:159], v[184:187], v[58:61]
	v_mfma_f32_16x16x32_bf16 v[58:61], v[160:163], v[188:191], v[58:61]
	v_mfma_f32_16x16x32_bf16 v[50:53], v[164:167], v[184:187], v[50:53]
	v_mfma_f32_16x16x32_bf16 v[50:53], v[180:183], v[188:191], v[50:53]
	v_mfma_f32_16x16x32_bf16 v[34:37], v[164:167], v[192:195], v[34:37]
	v_mfma_f32_16x16x32_bf16 v[34:37], v[180:183], v[196:199], v[34:37]
	v_mfma_f32_16x16x32_bf16 v[42:45], v[156:159], v[192:195], v[42:45]
	v_mfma_f32_16x16x32_bf16 v[42:45], v[160:163], v[196:199], v[42:45]
	v_mfma_f32_16x16x32_bf16 v[38:41], v[148:151], v[192:195], v[38:41]
	v_mfma_f32_16x16x32_bf16 v[38:41], v[152:155], v[196:199], v[38:41]
	v_mfma_f32_16x16x32_bf16 v[46:49], v[130:133], v[192:195], v[46:49]
	v_mfma_f32_16x16x32_bf16 v[46:49], v[134:137], v[196:199], v[46:49]
	v_mfma_f32_16x16x32_bf16 v[30:33], v[130:133], v[200:203], v[30:33]
	v_mfma_f32_16x16x32_bf16 v[30:33], v[134:137], v[204:207], v[30:33]
	v_mfma_f32_16x16x32_bf16 v[22:25], v[148:151], v[200:203], v[22:25]
	v_mfma_f32_16x16x32_bf16 v[22:25], v[152:155], v[204:207], v[22:25]
	v_mfma_f32_16x16x32_bf16 v[26:29], v[156:159], v[200:203], v[26:29]
	v_mfma_f32_16x16x32_bf16 v[26:29], v[160:163], v[204:207], v[26:29]
	v_mfma_f32_16x16x32_bf16 v[18:21], v[164:167], v[200:203], v[18:21]
	v_mfma_f32_16x16x32_bf16 v[18:21], v[180:183], v[204:207], v[18:21]
	v_mfma_f32_16x16x32_bf16 v[2:5], v[164:167], v[208:211], v[2:5]
	v_mfma_f32_16x16x32_bf16 v[2:5], v[180:183], v[212:215], v[2:5]
	v_mfma_f32_16x16x32_bf16 v[10:13], v[156:159], v[208:211], v[10:13]
	v_mfma_f32_16x16x32_bf16 v[10:13], v[160:163], v[212:215], v[10:13]
	v_mfma_f32_16x16x32_bf16 v[6:9], v[148:151], v[208:211], v[6:9]
	v_mfma_f32_16x16x32_bf16 v[6:9], v[152:155], v[212:215], v[6:9]
	v_mfma_f32_16x16x32_bf16 v[14:17], v[130:133], v[208:211], v[14:17]
	v_mfma_f32_16x16x32_bf16 v[14:17], v[134:137], v[212:215], v[14:17]
	s_setprio 0
	s_barrier
	ds_read_b128 v[130:133], v175
	ds_read_b128 v[134:137], v175 offset:1024
	ds_read_b128 v[148:151], v175 offset:2048
	ds_read_b128 v[152:155], v175 offset:3072
	ds_read_b128 v[156:159], v176
	ds_read_b128 v[160:163], v176 offset:1024
	ds_read_b128 v[164:167], v176 offset:2048
	ds_read_b128 v[180:183], v176 offset:3072
	s_mov_b32 m0, s64
	s_add_i32 s59, s53, 0x100000
	buffer_load_dwordx4 v170, s[12:15], s59 offen lds
	ds_read_b128 v[184:187], v174 offset:32768
	ds_read_b128 v[188:191], v174 offset:33792
	ds_read_b128 v[192:195], v174 offset:34816
	ds_read_b128 v[196:199], v174 offset:35840
	ds_read_b128 v[200:203], v174 offset:36864
	ds_read_b128 v[204:207], v174 offset:37888
	ds_read_b128 v[208:211], v174 offset:38912
	ds_read_b128 v[212:215], v174 offset:39936
	s_add_i32 s59, s53, 0x180000
	s_mov_b32 m0, s65
	s_nop 0
	buffer_load_dwordx4 v170, s[12:15], s59 offen lds
	s_waitcnt vmcnt(8)
	s_waitcnt lgkmcnt(0)
	s_setprio 1
	v_mfma_f32_16x16x32_bf16 v[126:129], v[130:133], v[184:187], v[126:129]
	s_barrier
	v_mfma_f32_16x16x32_bf16 v[126:129], v[134:137], v[188:191], v[126:129]
	v_mfma_f32_16x16x32_bf16 v[118:121], v[148:151], v[184:187], v[118:121]
	v_mfma_f32_16x16x32_bf16 v[118:121], v[152:155], v[188:191], v[118:121]
	v_mfma_f32_16x16x32_bf16 v[122:125], v[156:159], v[184:187], v[122:125]
	v_mfma_f32_16x16x32_bf16 v[122:125], v[160:163], v[188:191], v[122:125]
	v_mfma_f32_16x16x32_bf16 v[114:117], v[164:167], v[184:187], v[114:117]
	v_mfma_f32_16x16x32_bf16 v[114:117], v[180:183], v[188:191], v[114:117]
	v_mfma_f32_16x16x32_bf16 v[98:101], v[164:167], v[192:195], v[98:101]
	v_mfma_f32_16x16x32_bf16 v[98:101], v[180:183], v[196:199], v[98:101]
	v_mfma_f32_16x16x32_bf16 v[106:109], v[156:159], v[192:195], v[106:109]
	v_mfma_f32_16x16x32_bf16 v[106:109], v[160:163], v[196:199], v[106:109]
	v_mfma_f32_16x16x32_bf16 v[102:105], v[148:151], v[192:195], v[102:105]
	v_mfma_f32_16x16x32_bf16 v[102:105], v[152:155], v[196:199], v[102:105]
	v_mfma_f32_16x16x32_bf16 v[110:113], v[130:133], v[192:195], v[110:113]
	v_mfma_f32_16x16x32_bf16 v[110:113], v[134:137], v[196:199], v[110:113]
	v_mfma_f32_16x16x32_bf16 v[94:97], v[130:133], v[200:203], v[94:97]
	v_mfma_f32_16x16x32_bf16 v[94:97], v[134:137], v[204:207], v[94:97]
	v_mfma_f32_16x16x32_bf16 v[90:93], v[148:151], v[200:203], v[90:93]
	v_mfma_f32_16x16x32_bf16 v[90:93], v[152:155], v[204:207], v[90:93]
	v_mfma_f32_16x16x32_bf16 v[86:89], v[156:159], v[200:203], v[86:89]
	v_mfma_f32_16x16x32_bf16 v[86:89], v[160:163], v[204:207], v[86:89]
	v_mfma_f32_16x16x32_bf16 v[82:85], v[164:167], v[200:203], v[82:85]
	v_mfma_f32_16x16x32_bf16 v[82:85], v[180:183], v[204:207], v[82:85]
	v_mfma_f32_16x16x32_bf16 v[66:69], v[164:167], v[208:211], v[66:69]
	v_mfma_f32_16x16x32_bf16 v[66:69], v[180:183], v[212:215], v[66:69]
	v_mfma_f32_16x16x32_bf16 v[74:77], v[156:159], v[208:211], v[74:77]
	v_mfma_f32_16x16x32_bf16 v[74:77], v[160:163], v[212:215], v[74:77]
	v_mfma_f32_16x16x32_bf16 v[70:73], v[148:151], v[208:211], v[70:73]
	v_mfma_f32_16x16x32_bf16 v[70:73], v[152:155], v[212:215], v[70:73]
	v_mfma_f32_16x16x32_bf16 v[78:81], v[130:133], v[208:211], v[78:81]
	v_mfma_f32_16x16x32_bf16 v[78:81], v[134:137], v[212:215], v[78:81]
	s_setprio 0
	s_barrier
	s_mov_b32 m0, s70
	s_or_b32 s59, s58, 0x80
	buffer_load_dwordx4 v171, s[16:19], s59 offen lds
	ds_read_b128 v[184:187], v174 offset:49152
	ds_read_b128 v[188:191], v174 offset:50176
	ds_read_b128 v[192:195], v174 offset:51200
	ds_read_b128 v[196:199], v174 offset:52224
	ds_read_b128 v[200:203], v174 offset:53248
	ds_read_b128 v[204:207], v174 offset:54272
	ds_read_b128 v[208:211], v174 offset:55296
	ds_read_b128 v[212:215], v174 offset:56320
	s_add_i32 s59, s58, 0x80080
	s_mov_b32 m0, s71
	s_add_i32 s53, s53, 0x80080
	buffer_load_dwordx4 v171, s[16:19], s59 offen lds
	s_add_i32 s59, s58, 0x100080
	s_mov_b32 m0, s74
	s_add_i32 s58, s58, 0x180080
	buffer_load_dwordx4 v171, s[16:19], s59 offen lds
	s_mov_b32 m0, s75
	s_nop 0
	buffer_load_dwordx4 v171, s[16:19], s58 offen lds
	s_mov_b32 m0, s72
	s_nop 0
	buffer_load_dwordx4 v170, s[12:15], s57 offen lds
	s_mov_b32 m0, s73
	s_nop 0
	buffer_load_dwordx4 v170, s[12:15], s53 offen lds
	s_waitcnt vmcnt(8)
	s_waitcnt lgkmcnt(0)
	s_setprio 1
	v_mfma_f32_16x16x32_bf16 v[62:65], v[130:133], v[184:187], v[62:65]
	s_barrier
	v_mfma_f32_16x16x32_bf16 v[62:65], v[134:137], v[188:191], v[62:65]
	v_mfma_f32_16x16x32_bf16 v[54:57], v[148:151], v[184:187], v[54:57]
	v_mfma_f32_16x16x32_bf16 v[54:57], v[152:155], v[188:191], v[54:57]
	v_mfma_f32_16x16x32_bf16 v[58:61], v[156:159], v[184:187], v[58:61]
	v_mfma_f32_16x16x32_bf16 v[58:61], v[160:163], v[188:191], v[58:61]
	v_mfma_f32_16x16x32_bf16 v[50:53], v[164:167], v[184:187], v[50:53]
	v_mfma_f32_16x16x32_bf16 v[50:53], v[180:183], v[188:191], v[50:53]
	v_mfma_f32_16x16x32_bf16 v[34:37], v[164:167], v[192:195], v[34:37]
	v_mfma_f32_16x16x32_bf16 v[34:37], v[180:183], v[196:199], v[34:37]
	v_mfma_f32_16x16x32_bf16 v[42:45], v[156:159], v[192:195], v[42:45]
	v_mfma_f32_16x16x32_bf16 v[42:45], v[160:163], v[196:199], v[42:45]
	v_mfma_f32_16x16x32_bf16 v[38:41], v[148:151], v[192:195], v[38:41]
	v_mfma_f32_16x16x32_bf16 v[38:41], v[152:155], v[196:199], v[38:41]
	v_mfma_f32_16x16x32_bf16 v[46:49], v[130:133], v[192:195], v[46:49]
	v_mfma_f32_16x16x32_bf16 v[46:49], v[134:137], v[196:199], v[46:49]
	v_mfma_f32_16x16x32_bf16 v[30:33], v[130:133], v[200:203], v[30:33]
	v_mfma_f32_16x16x32_bf16 v[30:33], v[134:137], v[204:207], v[30:33]
	v_mfma_f32_16x16x32_bf16 v[22:25], v[148:151], v[200:203], v[22:25]
	v_mfma_f32_16x16x32_bf16 v[22:25], v[152:155], v[204:207], v[22:25]
	v_mfma_f32_16x16x32_bf16 v[26:29], v[156:159], v[200:203], v[26:29]
	v_mfma_f32_16x16x32_bf16 v[26:29], v[160:163], v[204:207], v[26:29]
	v_mfma_f32_16x16x32_bf16 v[18:21], v[164:167], v[200:203], v[18:21]
	v_mfma_f32_16x16x32_bf16 v[18:21], v[180:183], v[204:207], v[18:21]
	v_mfma_f32_16x16x32_bf16 v[2:5], v[164:167], v[208:211], v[2:5]
	v_mfma_f32_16x16x32_bf16 v[2:5], v[180:183], v[212:215], v[2:5]
	v_mfma_f32_16x16x32_bf16 v[10:13], v[156:159], v[208:211], v[10:13]
	v_mfma_f32_16x16x32_bf16 v[10:13], v[160:163], v[212:215], v[10:13]
	v_mfma_f32_16x16x32_bf16 v[6:9], v[148:151], v[208:211], v[6:9]
	v_mfma_f32_16x16x32_bf16 v[6:9], v[152:155], v[212:215], v[6:9]
	v_mfma_f32_16x16x32_bf16 v[14:17], v[130:133], v[208:211], v[14:17]
	v_mfma_f32_16x16x32_bf16 v[14:17], v[134:137], v[212:215], v[14:17]
	s_setprio 0
	s_barrier
	s_add_i32 s52, s52, 2
	s_addk_i32 s8, 0x100
	s_addk_i32 s9, 0x100
	s_cmp_ge_i32 s52, s21
	s_cbranch_scc0 .LBB0_892
	s_and_b64 vcc, exec, s[48:49]
	s_cbranch_vccz .LBB0_895

.LBB0_1020:
	v_add_u32_e32 v142, 0x10000, v162
	v_add_u32_e32 v150, 0x14000, v162
	ds_read_b128 v[130:133], v142
	ds_read_b128 v[134:137], v142 offset:1024
	ds_read_b128 v[138:141], v142 offset:2048
	ds_read_b128 v[142:145], v142 offset:3072
	ds_read_b128 v[154:157], v150
	ds_read_b128 v[164:167], v150 offset:1024
	ds_read_b128 v[168:171], v150 offset:2048
	ds_read_b128 v[172:175], v150 offset:3072
	s_add_i32 s90, s6, 0x100
	s_add_i32 s7, s88, s6
	s_cmp_eq_u32 s81, s89
	s_cselect_b32 s91, 0, s90
	s_cselect_b32 s93, s87, s7
	s_add_i32 s91, s91, s70
	s_or_b32 s92, s91, 0x80
	s_add_i32 s6, s3, s6
	s_mov_b32 m0, s82
	s_add_i32 s7, s6, 0x20080
	buffer_load_dwordx4 v161, s[12:15], s7 offen lds
	ds_read_b128 v[176:179], v163
	ds_read_b128 v[180:183], v163 offset:1024
	ds_read_b128 v[184:187], v163 offset:2048
	ds_read_b128 v[188:191], v163 offset:3072
	ds_read_b128 v[192:195], v163 offset:4096
	ds_read_b128 v[196:199], v163 offset:5120
	ds_read_b128 v[200:203], v163 offset:6144
	ds_read_b128 v[204:207], v163 offset:7168
	s_add_i32 s6, s6, 0x30080
	s_mov_b32 m0, s83
	s_nop 0
	buffer_load_dwordx4 v161, s[12:15], s6 offen lds
	s_waitcnt vmcnt(8)
	s_waitcnt lgkmcnt(0)
	s_setprio 1
	v_mfma_f32_16x16x32_bf16 v[126:129], v[130:133], v[176:179], v[126:129]
	s_barrier
	v_mfma_f32_16x16x32_bf16 v[126:129], v[134:137], v[180:183], v[126:129]
	v_mfma_f32_16x16x32_bf16 v[122:125], v[138:141], v[176:179], v[122:125]
	v_mfma_f32_16x16x32_bf16 v[122:125], v[142:145], v[180:183], v[122:125]
	v_mfma_f32_16x16x32_bf16 v[118:121], v[154:157], v[176:179], v[118:121]
	v_mfma_f32_16x16x32_bf16 v[118:121], v[164:167], v[180:183], v[118:121]
	v_mfma_f32_16x16x32_bf16 v[114:117], v[168:171], v[176:179], v[114:117]
	v_mfma_f32_16x16x32_bf16 v[114:117], v[172:175], v[180:183], v[114:117]
	v_mfma_f32_16x16x32_bf16 v[98:101], v[168:171], v[184:187], v[98:101]
	v_mfma_f32_16x16x32_bf16 v[98:101], v[172:175], v[188:191], v[98:101]
	v_mfma_f32_16x16x32_bf16 v[102:105], v[154:157], v[184:187], v[102:105]
	v_mfma_f32_16x16x32_bf16 v[102:105], v[164:167], v[188:191], v[102:105]
	v_mfma_f32_16x16x32_bf16 v[106:109], v[138:141], v[184:187], v[106:109]
	v_mfma_f32_16x16x32_bf16 v[106:109], v[142:145], v[188:191], v[106:109]
	v_mfma_f32_16x16x32_bf16 v[110:113], v[130:133], v[184:187], v[110:113]
	v_mfma_f32_16x16x32_bf16 v[110:113], v[134:137], v[188:191], v[110:113]
	v_mfma_f32_16x16x32_bf16 v[94:97], v[130:133], v[192:195], v[94:97]
	v_mfma_f32_16x16x32_bf16 v[94:97], v[134:137], v[196:199], v[94:97]
	v_mfma_f32_16x16x32_bf16 v[90:93], v[138:141], v[192:195], v[90:93]
	v_mfma_f32_16x16x32_bf16 v[90:93], v[142:145], v[196:199], v[90:93]
	v_mfma_f32_16x16x32_bf16 v[86:89], v[154:157], v[192:195], v[86:89]
	v_mfma_f32_16x16x32_bf16 v[86:89], v[164:167], v[196:199], v[86:89]
	v_mfma_f32_16x16x32_bf16 v[82:85], v[168:171], v[192:195], v[82:85]
	v_mfma_f32_16x16x32_bf16 v[82:85], v[172:175], v[196:199], v[82:85]
	v_mfma_f32_16x16x32_bf16 v[66:69], v[168:171], v[200:203], v[66:69]
	v_mfma_f32_16x16x32_bf16 v[66:69], v[172:175], v[204:207], v[66:69]
	v_mfma_f32_16x16x32_bf16 v[70:73], v[154:157], v[200:203], v[70:73]
	v_mfma_f32_16x16x32_bf16 v[70:73], v[164:167], v[204:207], v[70:73]
	v_mfma_f32_16x16x32_bf16 v[74:77], v[138:141], v[200:203], v[74:77]
	v_mfma_f32_16x16x32_bf16 v[74:77], v[142:145], v[204:207], v[74:77]
	v_mfma_f32_16x16x32_bf16 v[78:81], v[130:133], v[200:203], v[78:81]
	v_mfma_f32_16x16x32_bf16 v[78:81], v[134:137], v[204:207], v[78:81]
	s_setprio 0
	s_barrier
	s_mov_b32 m0, s66
	s_mov_b32 s6, s14
	s_mov_b32 s7, s15
	buffer_load_dwordx4 v160, s[4:7], s93 offen lds
	ds_read_b128 v[176:179], v163 offset:16384
	ds_read_b128 v[180:183], v163 offset:17408
	ds_read_b128 v[184:187], v163 offset:18432
	ds_read_b128 v[188:191], v163 offset:19456
	ds_read_b128 v[192:195], v163 offset:20480
	ds_read_b128 v[196:199], v163 offset:21504
	ds_read_b128 v[200:203], v163 offset:22528
	ds_read_b128 v[204:207], v163 offset:23552
	s_add_i32 s94, s93, 0x10000
	s_mov_b32 m0, s67
	s_nop 0
	buffer_load_dwordx4 v160, s[4:7], s94 offen lds
	s_add_i32 s94, s93, 0x20000
	s_mov_b32 m0, s68
	s_nop 0
	buffer_load_dwordx4 v160, s[4:7], s94 offen lds
	s_add_i32 s94, s93, 0x30000
	s_mov_b32 m0, s69
	s_nop 0
	buffer_load_dwordx4 v160, s[4:7], s94 offen lds
	s_mov_b32 m0, s65
	s_add_i32 s94, s91, 0x10000
	buffer_load_dwordx4 v161, s[12:15], s91 offen lds
	s_mov_b32 m0, s71
	s_nop 0
	buffer_load_dwordx4 v161, s[12:15], s94 offen lds
	s_waitcnt vmcnt(8)
	s_waitcnt lgkmcnt(0)
	s_setprio 1
	v_mfma_f32_16x16x32_bf16 v[62:65], v[130:133], v[176:179], v[62:65]
	s_barrier
	v_mfma_f32_16x16x32_bf16 v[62:65], v[134:137], v[180:183], v[62:65]
	v_mfma_f32_16x16x32_bf16 v[58:61], v[138:141], v[176:179], v[58:61]
	v_mfma_f32_16x16x32_bf16 v[58:61], v[142:145], v[180:183], v[58:61]
	v_mfma_f32_16x16x32_bf16 v[54:57], v[154:157], v[176:179], v[54:57]
	v_mfma_f32_16x16x32_bf16 v[54:57], v[164:167], v[180:183], v[54:57]
	v_mfma_f32_16x16x32_bf16 v[50:53], v[168:171], v[176:179], v[50:53]
	v_mfma_f32_16x16x32_bf16 v[50:53], v[172:175], v[180:183], v[50:53]
	v_mfma_f32_16x16x32_bf16 v[34:37], v[168:171], v[184:187], v[34:37]
	v_mfma_f32_16x16x32_bf16 v[34:37], v[172:175], v[188:191], v[34:37]
	v_mfma_f32_16x16x32_bf16 v[38:41], v[154:157], v[184:187], v[38:41]
	v_mfma_f32_16x16x32_bf16 v[38:41], v[164:167], v[188:191], v[38:41]
	v_mfma_f32_16x16x32_bf16 v[42:45], v[138:141], v[184:187], v[42:45]
	v_mfma_f32_16x16x32_bf16 v[42:45], v[142:145], v[188:191], v[42:45]
	v_mfma_f32_16x16x32_bf16 v[46:49], v[130:133], v[184:187], v[46:49]
	v_mfma_f32_16x16x32_bf16 v[46:49], v[134:137], v[188:191], v[46:49]
	v_mfma_f32_16x16x32_bf16 v[30:33], v[130:133], v[192:195], v[30:33]
	v_mfma_f32_16x16x32_bf16 v[30:33], v[134:137], v[196:199], v[30:33]
	v_mfma_f32_16x16x32_bf16 v[26:29], v[138:141], v[192:195], v[26:29]
	v_mfma_f32_16x16x32_bf16 v[26:29], v[142:145], v[196:199], v[26:29]
	v_mfma_f32_16x16x32_bf16 v[22:25], v[154:157], v[192:195], v[22:25]
	v_mfma_f32_16x16x32_bf16 v[22:25], v[164:167], v[196:199], v[22:25]
	v_mfma_f32_16x16x32_bf16 v[18:21], v[168:171], v[192:195], v[18:21]
	v_mfma_f32_16x16x32_bf16 v[18:21], v[172:175], v[196:199], v[18:21]
	v_mfma_f32_16x16x32_bf16 v[2:5], v[168:171], v[200:203], v[2:5]
	v_mfma_f32_16x16x32_bf16 v[2:5], v[172:175], v[204:207], v[2:5]
	v_mfma_f32_16x16x32_bf16 v[6:9], v[154:157], v[200:203], v[6:9]
	v_mfma_f32_16x16x32_bf16 v[6:9], v[164:167], v[204:207], v[6:9]
	v_mfma_f32_16x16x32_bf16 v[10:13], v[138:141], v[200:203], v[10:13]
	v_mfma_f32_16x16x32_bf16 v[10:13], v[142:145], v[204:207], v[10:13]
	v_mfma_f32_16x16x32_bf16 v[14:17], v[130:133], v[200:203], v[14:17]
	v_mfma_f32_16x16x32_bf16 v[14:17], v[134:137], v[204:207], v[14:17]
	s_setprio 0
	s_barrier
	v_add_u32_e32 v142, 0x18000, v162
	v_add_u32_e32 v150, 0x1c000, v162
	ds_read_b128 v[130:133], v142
	ds_read_b128 v[134:137], v142 offset:1024
	ds_read_b128 v[138:141], v142 offset:2048
	ds_read_b128 v[142:145], v142 offset:3072
	ds_read_b128 v[154:157], v150
	ds_read_b128 v[164:167], v150 offset:1024
	ds_read_b128 v[168:171], v150 offset:2048
	ds_read_b128 v[172:175], v150 offset:3072
	s_mov_b32 m0, s72
	s_add_i32 s94, s91, 0x20000
	buffer_load_dwordx4 v161, s[12:15], s94 offen lds
	ds_read_b128 v[176:179], v163 offset:32768
	ds_read_b128 v[180:183], v163 offset:33792
	ds_read_b128 v[184:187], v163 offset:34816
	ds_read_b128 v[188:191], v163 offset:35840
	ds_read_b128 v[192:195], v163 offset:36864
	ds_read_b128 v[196:199], v163 offset:37888
	ds_read_b128 v[200:203], v163 offset:38912
	ds_read_b128 v[204:207], v163 offset:39936
	s_add_i32 s94, s91, 0x30000
	s_mov_b32 m0, s73
	s_nop 0
	buffer_load_dwordx4 v161, s[12:15], s94 offen lds
	s_waitcnt vmcnt(8)
	s_waitcnt lgkmcnt(0)
	s_setprio 1
	v_mfma_f32_16x16x32_bf16 v[126:129], v[130:133], v[176:179], v[126:129]
	s_barrier
	v_mfma_f32_16x16x32_bf16 v[126:129], v[134:137], v[180:183], v[126:129]
	v_mfma_f32_16x16x32_bf16 v[122:125], v[138:141], v[176:179], v[122:125]
	v_mfma_f32_16x16x32_bf16 v[122:125], v[142:145], v[180:183], v[122:125]
	v_mfma_f32_16x16x32_bf16 v[118:121], v[154:157], v[176:179], v[118:121]
	v_mfma_f32_16x16x32_bf16 v[118:121], v[164:167], v[180:183], v[118:121]
	v_mfma_f32_16x16x32_bf16 v[114:117], v[168:171], v[176:179], v[114:117]
	v_mfma_f32_16x16x32_bf16 v[114:117], v[172:175], v[180:183], v[114:117]
	v_mfma_f32_16x16x32_bf16 v[98:101], v[168:171], v[184:187], v[98:101]
	v_mfma_f32_16x16x32_bf16 v[98:101], v[172:175], v[188:191], v[98:101]
	v_mfma_f32_16x16x32_bf16 v[102:105], v[154:157], v[184:187], v[102:105]
	v_mfma_f32_16x16x32_bf16 v[102:105], v[164:167], v[188:191], v[102:105]
	v_mfma_f32_16x16x32_bf16 v[106:109], v[138:141], v[184:187], v[106:109]
	v_mfma_f32_16x16x32_bf16 v[106:109], v[142:145], v[188:191], v[106:109]
	v_mfma_f32_16x16x32_bf16 v[110:113], v[130:133], v[184:187], v[110:113]
	v_mfma_f32_16x16x32_bf16 v[110:113], v[134:137], v[188:191], v[110:113]
	v_mfma_f32_16x16x32_bf16 v[94:97], v[130:133], v[192:195], v[94:97]
	v_mfma_f32_16x16x32_bf16 v[94:97], v[134:137], v[196:199], v[94:97]
	v_mfma_f32_16x16x32_bf16 v[90:93], v[138:141], v[192:195], v[90:93]
	v_mfma_f32_16x16x32_bf16 v[90:93], v[142:145], v[196:199], v[90:93]
	v_mfma_f32_16x16x32_bf16 v[86:89], v[154:157], v[192:195], v[86:89]
	v_mfma_f32_16x16x32_bf16 v[86:89], v[164:167], v[196:199], v[86:89]
	v_mfma_f32_16x16x32_bf16 v[82:85], v[168:171], v[192:195], v[82:85]
	v_mfma_f32_16x16x32_bf16 v[82:85], v[172:175], v[196:199], v[82:85]
	v_mfma_f32_16x16x32_bf16 v[66:69], v[168:171], v[200:203], v[66:69]
	v_mfma_f32_16x16x32_bf16 v[66:69], v[172:175], v[204:207], v[66:69]
	v_mfma_f32_16x16x32_bf16 v[70:73], v[154:157], v[200:203], v[70:73]
	v_mfma_f32_16x16x32_bf16 v[70:73], v[164:167], v[204:207], v[70:73]
	v_mfma_f32_16x16x32_bf16 v[74:77], v[138:141], v[200:203], v[74:77]
	v_mfma_f32_16x16x32_bf16 v[74:77], v[142:145], v[204:207], v[74:77]
	v_mfma_f32_16x16x32_bf16 v[78:81], v[130:133], v[200:203], v[78:81]
	v_mfma_f32_16x16x32_bf16 v[78:81], v[134:137], v[204:207], v[78:81]
	s_setprio 0
	s_barrier
	s_mov_b32 m0, s74
	s_or_b32 s94, s93, 0x80
	buffer_load_dwordx4 v160, s[4:7], s94 offen lds
	ds_read_b128 v[176:179], v163 offset:49152
	ds_read_b128 v[180:183], v163 offset:50176
	ds_read_b128 v[184:187], v163 offset:51200
	ds_read_b128 v[188:191], v163 offset:52224
	ds_read_b128 v[192:195], v163 offset:53248
	ds_read_b128 v[196:199], v163 offset:54272
	ds_read_b128 v[200:203], v163 offset:55296
	ds_read_b128 v[204:207], v163 offset:56320
	s_add_i32 s94, s93, 0x10080
	s_mov_b32 m0, s75
	s_add_i32 s91, s91, 0x10080
	buffer_load_dwordx4 v160, s[4:7], s94 offen lds
	s_add_i32 s94, s93, 0x20080
	s_mov_b32 m0, s78
	s_add_i32 s93, s93, 0x30080
	buffer_load_dwordx4 v160, s[4:7], s94 offen lds
	s_mov_b32 m0, s79
	s_nop 0
	buffer_load_dwordx4 v160, s[4:7], s93 offen lds
	s_mov_b32 m0, s76
	s_nop 0
	buffer_load_dwordx4 v161, s[12:15], s92 offen lds
	s_mov_b32 m0, s77
	s_nop 0
	buffer_load_dwordx4 v161, s[12:15], s91 offen lds
	s_waitcnt vmcnt(8)
	s_waitcnt lgkmcnt(0)
	s_setprio 1
	v_mfma_f32_16x16x32_bf16 v[62:65], v[130:133], v[176:179], v[62:65]
	s_barrier
	v_mfma_f32_16x16x32_bf16 v[62:65], v[134:137], v[180:183], v[62:65]
	v_mfma_f32_16x16x32_bf16 v[58:61], v[138:141], v[176:179], v[58:61]
	v_mfma_f32_16x16x32_bf16 v[58:61], v[142:145], v[180:183], v[58:61]
	v_mfma_f32_16x16x32_bf16 v[54:57], v[154:157], v[176:179], v[54:57]
	v_mfma_f32_16x16x32_bf16 v[54:57], v[164:167], v[180:183], v[54:57]
	v_mfma_f32_16x16x32_bf16 v[50:53], v[168:171], v[176:179], v[50:53]
	v_mfma_f32_16x16x32_bf16 v[50:53], v[172:175], v[180:183], v[50:53]
	v_mfma_f32_16x16x32_bf16 v[34:37], v[168:171], v[184:187], v[34:37]
	v_mfma_f32_16x16x32_bf16 v[34:37], v[172:175], v[188:191], v[34:37]
	v_mfma_f32_16x16x32_bf16 v[38:41], v[154:157], v[184:187], v[38:41]
	v_mfma_f32_16x16x32_bf16 v[38:41], v[164:167], v[188:191], v[38:41]
	v_mfma_f32_16x16x32_bf16 v[42:45], v[138:141], v[184:187], v[42:45]
	v_mfma_f32_16x16x32_bf16 v[42:45], v[142:145], v[188:191], v[42:45]
	v_mfma_f32_16x16x32_bf16 v[46:49], v[130:133], v[184:187], v[46:49]
	v_mfma_f32_16x16x32_bf16 v[46:49], v[134:137], v[188:191], v[46:49]
	v_mfma_f32_16x16x32_bf16 v[30:33], v[130:133], v[192:195], v[30:33]
	v_mfma_f32_16x16x32_bf16 v[30:33], v[134:137], v[196:199], v[30:33]
	v_mfma_f32_16x16x32_bf16 v[26:29], v[138:141], v[192:195], v[26:29]
	v_mfma_f32_16x16x32_bf16 v[26:29], v[142:145], v[196:199], v[26:29]
	v_mfma_f32_16x16x32_bf16 v[22:25], v[154:157], v[192:195], v[22:25]
	v_mfma_f32_16x16x32_bf16 v[22:25], v[164:167], v[196:199], v[22:25]
	v_mfma_f32_16x16x32_bf16 v[18:21], v[168:171], v[192:195], v[18:21]
	v_mfma_f32_16x16x32_bf16 v[18:21], v[172:175], v[196:199], v[18:21]
	v_mfma_f32_16x16x32_bf16 v[2:5], v[168:171], v[200:203], v[2:5]
	v_mfma_f32_16x16x32_bf16 v[2:5], v[172:175], v[204:207], v[2:5]
	v_mfma_f32_16x16x32_bf16 v[6:9], v[154:157], v[200:203], v[6:9]
	v_mfma_f32_16x16x32_bf16 v[6:9], v[164:167], v[204:207], v[6:9]
	v_mfma_f32_16x16x32_bf16 v[10:13], v[138:141], v[200:203], v[10:13]
	v_mfma_f32_16x16x32_bf16 v[10:13], v[142:145], v[204:207], v[10:13]
	v_mfma_f32_16x16x32_bf16 v[14:17], v[130:133], v[200:203], v[14:17]
	v_mfma_f32_16x16x32_bf16 v[14:17], v[134:137], v[204:207], v[14:17]
	s_setprio 0
	s_barrier
	s_add_i32 s89, s89, 2
	s_cmp_ge_i32 s89, s63
	s_mov_b32 s6, s90
	s_cbranch_scc0 .LBB0_1020
	s_and_b64 vcc, exec, s[54:55]
	s_cbranch_vccz .LBB0_1023

.LBB0_1035:
	ds_read_b128 v[140:143], v134
	ds_read_b128 v[148:151], v134 offset:1024
	ds_read_b128 v[152:155], v134 offset:2048
	ds_read_b128 v[156:159], v134 offset:3072
	ds_read_b128 v[160:163], v135
	ds_read_b128 v[164:167], v135 offset:1024
	ds_read_b128 v[168:171], v135 offset:2048
	ds_read_b128 v[172:175], v135 offset:3072
	s_add_i32 s73, s70, 0xfffb8080
	s_cmp_eq_u32 s53, s72
	s_cselect_b32 s73, s68, s73
	s_cselect_b32 s75, s69, s71
	s_add_i32 s74, s73, 0x80
	s_add_i32 s76, s70, 0xfffe8000
	s_mov_b32 m0, s54
	s_nop 0
	buffer_load_dwordx4 v132, s[12:15], s76 offen lds
	ds_read_b128 v[176:179], v136
	ds_read_b128 v[180:183], v136 offset:1024
	ds_read_b128 v[184:187], v136 offset:2048
	ds_read_b128 v[188:191], v136 offset:3072
	ds_read_b128 v[192:195], v136 offset:4096
	ds_read_b128 v[196:199], v136 offset:5120
	ds_read_b128 v[200:203], v136 offset:6144
	ds_read_b128 v[204:207], v136 offset:7168
	s_mov_b32 m0, s55
	s_nop 0
	buffer_load_dwordx4 v132, s[12:15], s70 offen lds
	s_waitcnt vmcnt(8)
	s_waitcnt lgkmcnt(0)
	s_setprio 1
	v_mfma_f32_16x16x32_bf16 v[126:129], v[140:143], v[176:179], v[126:129]
	s_barrier
	v_mfma_f32_16x16x32_bf16 v[126:129], v[148:151], v[180:183], v[126:129]
	v_mfma_f32_16x16x32_bf16 v[122:125], v[152:155], v[176:179], v[122:125]
	v_mfma_f32_16x16x32_bf16 v[122:125], v[156:159], v[180:183], v[122:125]
	v_mfma_f32_16x16x32_bf16 v[118:121], v[160:163], v[176:179], v[118:121]
	v_mfma_f32_16x16x32_bf16 v[118:121], v[164:167], v[180:183], v[118:121]
	v_mfma_f32_16x16x32_bf16 v[114:117], v[168:171], v[176:179], v[114:117]
	v_mfma_f32_16x16x32_bf16 v[114:117], v[172:175], v[180:183], v[114:117]
	v_mfma_f32_16x16x32_bf16 v[98:101], v[168:171], v[184:187], v[98:101]
	v_mfma_f32_16x16x32_bf16 v[98:101], v[172:175], v[188:191], v[98:101]
	v_mfma_f32_16x16x32_bf16 v[102:105], v[160:163], v[184:187], v[102:105]
	v_mfma_f32_16x16x32_bf16 v[102:105], v[164:167], v[188:191], v[102:105]
	v_mfma_f32_16x16x32_bf16 v[106:109], v[152:155], v[184:187], v[106:109]
	v_mfma_f32_16x16x32_bf16 v[106:109], v[156:159], v[188:191], v[106:109]
	v_mfma_f32_16x16x32_bf16 v[110:113], v[140:143], v[184:187], v[110:113]
	v_mfma_f32_16x16x32_bf16 v[110:113], v[148:151], v[188:191], v[110:113]
	v_mfma_f32_16x16x32_bf16 v[94:97], v[140:143], v[192:195], v[94:97]
	v_mfma_f32_16x16x32_bf16 v[94:97], v[148:151], v[196:199], v[94:97]
	v_mfma_f32_16x16x32_bf16 v[90:93], v[152:155], v[192:195], v[90:93]
	v_mfma_f32_16x16x32_bf16 v[90:93], v[156:159], v[196:199], v[90:93]
	v_mfma_f32_16x16x32_bf16 v[86:89], v[160:163], v[192:195], v[86:89]
	v_mfma_f32_16x16x32_bf16 v[86:89], v[164:167], v[196:199], v[86:89]
	v_mfma_f32_16x16x32_bf16 v[82:85], v[168:171], v[192:195], v[82:85]
	v_mfma_f32_16x16x32_bf16 v[82:85], v[172:175], v[196:199], v[82:85]
	v_mfma_f32_16x16x32_bf16 v[66:69], v[168:171], v[200:203], v[66:69]
	v_mfma_f32_16x16x32_bf16 v[66:69], v[172:175], v[204:207], v[66:69]
	v_mfma_f32_16x16x32_bf16 v[70:73], v[160:163], v[200:203], v[70:73]
	v_mfma_f32_16x16x32_bf16 v[70:73], v[164:167], v[204:207], v[70:73]
	v_mfma_f32_16x16x32_bf16 v[74:77], v[152:155], v[200:203], v[74:77]
	v_mfma_f32_16x16x32_bf16 v[74:77], v[156:159], v[204:207], v[74:77]
	v_mfma_f32_16x16x32_bf16 v[78:81], v[140:143], v[200:203], v[78:81]
	v_mfma_f32_16x16x32_bf16 v[78:81], v[148:151], v[204:207], v[78:81]
	s_setprio 0
	s_barrier
	s_mov_b32 m0, s30
	s_nop 0
	buffer_load_dwordx4 v133, s[16:19], s75 offen lds
	ds_read_b128 v[176:179], v136 offset:16384
	ds_read_b128 v[180:183], v136 offset:17408
	ds_read_b128 v[184:187], v136 offset:18432
	ds_read_b128 v[188:191], v136 offset:19456
	ds_read_b128 v[192:195], v136 offset:20480
	ds_read_b128 v[196:199], v136 offset:21504
	ds_read_b128 v[200:203], v136 offset:22528
	ds_read_b128 v[204:207], v136 offset:23552
	s_add_i32 s76, s75, 0x200000
	s_mov_b32 m0, s31
	s_nop 0
	buffer_load_dwordx4 v133, s[16:19], s76 offen lds
	s_add_i32 s76, s75, 0x400000
	s_mov_b32 m0, s35
	s_nop 0
	buffer_load_dwordx4 v133, s[16:19], s76 offen lds
	s_add_i32 s76, s75, 0x600000
	s_mov_b32 m0, s42
	s_nop 0
	buffer_load_dwordx4 v133, s[16:19], s76 offen lds
	s_mov_b32 m0, s27
	s_add_i32 s76, s73, 0x18000
	buffer_load_dwordx4 v132, s[12:15], s73 offen lds
	s_mov_b32 m0, s43
	s_nop 0
	buffer_load_dwordx4 v132, s[12:15], s76 offen lds
	s_waitcnt vmcnt(8)
	s_waitcnt lgkmcnt(0)
	s_setprio 1
	v_mfma_f32_16x16x32_bf16 v[62:65], v[140:143], v[176:179], v[62:65]
	s_barrier
	v_mfma_f32_16x16x32_bf16 v[62:65], v[148:151], v[180:183], v[62:65]
	v_mfma_f32_16x16x32_bf16 v[58:61], v[152:155], v[176:179], v[58:61]
	v_mfma_f32_16x16x32_bf16 v[58:61], v[156:159], v[180:183], v[58:61]
	v_mfma_f32_16x16x32_bf16 v[54:57], v[160:163], v[176:179], v[54:57]
	v_mfma_f32_16x16x32_bf16 v[54:57], v[164:167], v[180:183], v[54:57]
	v_mfma_f32_16x16x32_bf16 v[50:53], v[168:171], v[176:179], v[50:53]
	v_mfma_f32_16x16x32_bf16 v[50:53], v[172:175], v[180:183], v[50:53]
	v_mfma_f32_16x16x32_bf16 v[34:37], v[168:171], v[184:187], v[34:37]
	v_mfma_f32_16x16x32_bf16 v[34:37], v[172:175], v[188:191], v[34:37]
	v_mfma_f32_16x16x32_bf16 v[38:41], v[160:163], v[184:187], v[38:41]
	v_mfma_f32_16x16x32_bf16 v[38:41], v[164:167], v[188:191], v[38:41]
	v_mfma_f32_16x16x32_bf16 v[42:45], v[152:155], v[184:187], v[42:45]
	v_mfma_f32_16x16x32_bf16 v[42:45], v[156:159], v[188:191], v[42:45]
	v_mfma_f32_16x16x32_bf16 v[46:49], v[140:143], v[184:187], v[46:49]
	v_mfma_f32_16x16x32_bf16 v[46:49], v[148:151], v[188:191], v[46:49]
	v_mfma_f32_16x16x32_bf16 v[30:33], v[140:143], v[192:195], v[30:33]
	v_mfma_f32_16x16x32_bf16 v[30:33], v[148:151], v[196:199], v[30:33]
	v_mfma_f32_16x16x32_bf16 v[26:29], v[152:155], v[192:195], v[26:29]
	v_mfma_f32_16x16x32_bf16 v[26:29], v[156:159], v[196:199], v[26:29]
	v_mfma_f32_16x16x32_bf16 v[22:25], v[160:163], v[192:195], v[22:25]
	v_mfma_f32_16x16x32_bf16 v[22:25], v[164:167], v[196:199], v[22:25]
	v_mfma_f32_16x16x32_bf16 v[18:21], v[168:171], v[192:195], v[18:21]
	v_mfma_f32_16x16x32_bf16 v[18:21], v[172:175], v[196:199], v[18:21]
	v_mfma_f32_16x16x32_bf16 v[2:5], v[168:171], v[200:203], v[2:5]
	v_mfma_f32_16x16x32_bf16 v[2:5], v[172:175], v[204:207], v[2:5]
	v_mfma_f32_16x16x32_bf16 v[6:9], v[160:163], v[200:203], v[6:9]
	v_mfma_f32_16x16x32_bf16 v[6:9], v[164:167], v[204:207], v[6:9]
	v_mfma_f32_16x16x32_bf16 v[10:13], v[152:155], v[200:203], v[10:13]
	v_mfma_f32_16x16x32_bf16 v[10:13], v[156:159], v[204:207], v[10:13]
	v_mfma_f32_16x16x32_bf16 v[14:17], v[140:143], v[200:203], v[14:17]
	v_mfma_f32_16x16x32_bf16 v[14:17], v[148:151], v[204:207], v[14:17]
	s_setprio 0
	s_barrier
	ds_read_b128 v[140:143], v137
	ds_read_b128 v[148:151], v137 offset:1024
	ds_read_b128 v[152:155], v137 offset:2048
	ds_read_b128 v[156:159], v137 offset:3072
	ds_read_b128 v[160:163], v138
	ds_read_b128 v[164:167], v138 offset:1024
	ds_read_b128 v[168:171], v138 offset:2048
	ds_read_b128 v[172:175], v138 offset:3072
	s_mov_b32 m0, s44
	s_add_i32 s76, s73, 0x30000
	buffer_load_dwordx4 v132, s[12:15], s76 offen lds
	ds_read_b128 v[176:179], v136 offset:32768
	ds_read_b128 v[180:183], v136 offset:33792
	ds_read_b128 v[184:187], v136 offset:34816
	ds_read_b128 v[188:191], v136 offset:35840
	ds_read_b128 v[192:195], v136 offset:36864
	ds_read_b128 v[196:199], v136 offset:37888
	ds_read_b128 v[200:203], v136 offset:38912
	ds_read_b128 v[204:207], v136 offset:39936
	s_add_i32 s76, s73, 0x48000
	s_mov_b32 m0, s45
	s_nop 0
	buffer_load_dwordx4 v132, s[12:15], s76 offen lds
	s_waitcnt vmcnt(8)
	s_waitcnt lgkmcnt(0)
	s_setprio 1
	v_mfma_f32_16x16x32_bf16 v[126:129], v[140:143], v[176:179], v[126:129]
	s_barrier
	v_mfma_f32_16x16x32_bf16 v[126:129], v[148:151], v[180:183], v[126:129]
	v_mfma_f32_16x16x32_bf16 v[122:125], v[152:155], v[176:179], v[122:125]
	v_mfma_f32_16x16x32_bf16 v[122:125], v[156:159], v[180:183], v[122:125]
	v_mfma_f32_16x16x32_bf16 v[118:121], v[160:163], v[176:179], v[118:121]
	v_mfma_f32_16x16x32_bf16 v[118:121], v[164:167], v[180:183], v[118:121]
	v_mfma_f32_16x16x32_bf16 v[114:117], v[168:171], v[176:179], v[114:117]
	v_mfma_f32_16x16x32_bf16 v[114:117], v[172:175], v[180:183], v[114:117]
	v_mfma_f32_16x16x32_bf16 v[98:101], v[168:171], v[184:187], v[98:101]
	v_mfma_f32_16x16x32_bf16 v[98:101], v[172:175], v[188:191], v[98:101]
	v_mfma_f32_16x16x32_bf16 v[102:105], v[160:163], v[184:187], v[102:105]
	v_mfma_f32_16x16x32_bf16 v[102:105], v[164:167], v[188:191], v[102:105]
	v_mfma_f32_16x16x32_bf16 v[106:109], v[152:155], v[184:187], v[106:109]
	v_mfma_f32_16x16x32_bf16 v[106:109], v[156:159], v[188:191], v[106:109]
	v_mfma_f32_16x16x32_bf16 v[110:113], v[140:143], v[184:187], v[110:113]
	v_mfma_f32_16x16x32_bf16 v[110:113], v[148:151], v[188:191], v[110:113]
	v_mfma_f32_16x16x32_bf16 v[94:97], v[140:143], v[192:195], v[94:97]
	v_mfma_f32_16x16x32_bf16 v[94:97], v[148:151], v[196:199], v[94:97]
	v_mfma_f32_16x16x32_bf16 v[90:93], v[152:155], v[192:195], v[90:93]
	v_mfma_f32_16x16x32_bf16 v[90:93], v[156:159], v[196:199], v[90:93]
	v_mfma_f32_16x16x32_bf16 v[86:89], v[160:163], v[192:195], v[86:89]
	v_mfma_f32_16x16x32_bf16 v[86:89], v[164:167], v[196:199], v[86:89]
	v_mfma_f32_16x16x32_bf16 v[82:85], v[168:171], v[192:195], v[82:85]
	v_mfma_f32_16x16x32_bf16 v[82:85], v[172:175], v[196:199], v[82:85]
	v_mfma_f32_16x16x32_bf16 v[66:69], v[168:171], v[200:203], v[66:69]
	v_mfma_f32_16x16x32_bf16 v[66:69], v[172:175], v[204:207], v[66:69]
	v_mfma_f32_16x16x32_bf16 v[70:73], v[160:163], v[200:203], v[70:73]
	v_mfma_f32_16x16x32_bf16 v[70:73], v[164:167], v[204:207], v[70:73]
	v_mfma_f32_16x16x32_bf16 v[74:77], v[152:155], v[200:203], v[74:77]
	v_mfma_f32_16x16x32_bf16 v[74:77], v[156:159], v[204:207], v[74:77]
	v_mfma_f32_16x16x32_bf16 v[78:81], v[140:143], v[200:203], v[78:81]
	v_mfma_f32_16x16x32_bf16 v[78:81], v[148:151], v[204:207], v[78:81]
	s_setprio 0
	s_barrier
	s_mov_b32 m0, s46
	s_add_i32 s76, s75, 0x80
	buffer_load_dwordx4 v133, s[16:19], s76 offen lds
	ds_read_b128 v[176:179], v136 offset:49152
	ds_read_b128 v[180:183], v136 offset:50176
	ds_read_b128 v[184:187], v136 offset:51200
	ds_read_b128 v[188:191], v136 offset:52224
	ds_read_b128 v[192:195], v136 offset:53248
	ds_read_b128 v[196:199], v136 offset:54272
	ds_read_b128 v[200:203], v136 offset:55296
	ds_read_b128 v[204:207], v136 offset:56320
	s_add_i32 s76, s75, 0x200080
	s_mov_b32 m0, s47
	s_add_i32 s73, s73, 0x18080
	buffer_load_dwordx4 v133, s[16:19], s76 offen lds
	s_add_i32 s76, s75, 0x400080
	s_mov_b32 m0, s50
	s_add_i32 s75, s75, 0x600080
	buffer_load_dwordx4 v133, s[16:19], s76 offen lds
	s_mov_b32 m0, s51
	s_nop 0
	buffer_load_dwordx4 v133, s[16:19], s75 offen lds
	s_mov_b32 m0, s48
	s_nop 0
	buffer_load_dwordx4 v132, s[12:15], s74 offen lds
	s_mov_b32 m0, s49
	s_nop 0
	buffer_load_dwordx4 v132, s[12:15], s73 offen lds
	s_waitcnt vmcnt(8)
	s_waitcnt lgkmcnt(0)
	s_setprio 1
	v_mfma_f32_16x16x32_bf16 v[62:65], v[140:143], v[176:179], v[62:65]
	s_barrier
	v_mfma_f32_16x16x32_bf16 v[62:65], v[148:151], v[180:183], v[62:65]
	v_mfma_f32_16x16x32_bf16 v[58:61], v[152:155], v[176:179], v[58:61]
	v_mfma_f32_16x16x32_bf16 v[58:61], v[156:159], v[180:183], v[58:61]
	v_mfma_f32_16x16x32_bf16 v[54:57], v[160:163], v[176:179], v[54:57]
	v_mfma_f32_16x16x32_bf16 v[54:57], v[164:167], v[180:183], v[54:57]
	v_mfma_f32_16x16x32_bf16 v[50:53], v[168:171], v[176:179], v[50:53]
	v_mfma_f32_16x16x32_bf16 v[50:53], v[172:175], v[180:183], v[50:53]
	v_mfma_f32_16x16x32_bf16 v[34:37], v[168:171], v[184:187], v[34:37]
	v_mfma_f32_16x16x32_bf16 v[34:37], v[172:175], v[188:191], v[34:37]
	v_mfma_f32_16x16x32_bf16 v[38:41], v[160:163], v[184:187], v[38:41]
	v_mfma_f32_16x16x32_bf16 v[38:41], v[164:167], v[188:191], v[38:41]
	v_mfma_f32_16x16x32_bf16 v[42:45], v[152:155], v[184:187], v[42:45]
	v_mfma_f32_16x16x32_bf16 v[42:45], v[156:159], v[188:191], v[42:45]
	v_mfma_f32_16x16x32_bf16 v[46:49], v[140:143], v[184:187], v[46:49]
	v_mfma_f32_16x16x32_bf16 v[46:49], v[148:151], v[188:191], v[46:49]
	v_mfma_f32_16x16x32_bf16 v[30:33], v[140:143], v[192:195], v[30:33]
	v_mfma_f32_16x16x32_bf16 v[30:33], v[148:151], v[196:199], v[30:33]
	v_mfma_f32_16x16x32_bf16 v[26:29], v[152:155], v[192:195], v[26:29]
	v_mfma_f32_16x16x32_bf16 v[26:29], v[156:159], v[196:199], v[26:29]
	v_mfma_f32_16x16x32_bf16 v[22:25], v[160:163], v[192:195], v[22:25]
	v_mfma_f32_16x16x32_bf16 v[22:25], v[164:167], v[196:199], v[22:25]
	v_mfma_f32_16x16x32_bf16 v[18:21], v[168:171], v[192:195], v[18:21]
	v_mfma_f32_16x16x32_bf16 v[18:21], v[172:175], v[196:199], v[18:21]
	v_mfma_f32_16x16x32_bf16 v[2:5], v[168:171], v[200:203], v[2:5]
	v_mfma_f32_16x16x32_bf16 v[2:5], v[172:175], v[204:207], v[2:5]
	v_mfma_f32_16x16x32_bf16 v[6:9], v[160:163], v[200:203], v[6:9]
	v_mfma_f32_16x16x32_bf16 v[6:9], v[164:167], v[204:207], v[6:9]
	v_mfma_f32_16x16x32_bf16 v[10:13], v[152:155], v[200:203], v[10:13]
	v_mfma_f32_16x16x32_bf16 v[10:13], v[156:159], v[204:207], v[10:13]
	v_mfma_f32_16x16x32_bf16 v[14:17], v[140:143], v[200:203], v[14:17]
	v_mfma_f32_16x16x32_bf16 v[14:17], v[148:151], v[204:207], v[14:17]
	s_setprio 0
	s_barrier
	s_add_i32 s72, s72, 2
	s_addk_i32 s70, 0x100
	s_addk_i32 s71, 0x100
	s_cmp_ge_i32 s72, s21
	s_cbranch_scc0 .LBB0_1035

.LBB0_1050:
	ds_read_b128 v[132:135], v142
	ds_read_b128 v[136:139], v142 offset:1024
	ds_read_b128 v[148:151], v142 offset:2048
	ds_read_b128 v[152:155], v142 offset:3072
	ds_read_b128 v[156:159], v143
	ds_read_b128 v[160:163], v143 offset:1024
	ds_read_b128 v[164:167], v143 offset:2048
	ds_read_b128 v[168:171], v143 offset:3072
	s_add_i32 s18, s61, 0xfff40080
	s_cmp_eq_u32 s54, s62
	s_cselect_b32 s64, s35, s18
	s_add_i32 s63, s64, 0x80
	s_add_i32 s18, s61, 0xfffc0000
	s_mov_b32 m0, s55
	s_nop 0
	buffer_load_dwordx4 v140, s[12:15], s18 offen lds
	ds_read_b128 v[172:175], v144
	ds_read_b128 v[176:179], v144 offset:1024
	ds_read_b128 v[180:183], v144 offset:2048
	ds_read_b128 v[184:187], v144 offset:3072
	ds_read_b128 v[188:191], v144 offset:4096
	ds_read_b128 v[192:195], v144 offset:5120
	ds_read_b128 v[196:199], v144 offset:6144
	ds_read_b128 v[200:203], v144 offset:7168
	s_mov_b32 m0, s56
	s_nop 0
	buffer_load_dwordx4 v140, s[12:15], s61 offen lds
	s_waitcnt vmcnt(8)
	s_waitcnt lgkmcnt(0)
	s_setprio 1
	v_mfma_f32_16x16x32_bf16 v[126:129], v[132:135], v[172:175], v[126:129]
	s_barrier
	v_mfma_f32_16x16x32_bf16 v[126:129], v[136:139], v[176:179], v[126:129]
	v_mfma_f32_16x16x32_bf16 v[122:125], v[148:151], v[172:175], v[122:125]
	v_mfma_f32_16x16x32_bf16 v[122:125], v[152:155], v[176:179], v[122:125]
	v_mfma_f32_16x16x32_bf16 v[118:121], v[156:159], v[172:175], v[118:121]
	v_mfma_f32_16x16x32_bf16 v[118:121], v[160:163], v[176:179], v[118:121]
	v_mfma_f32_16x16x32_bf16 v[114:117], v[164:167], v[172:175], v[114:117]
	v_mfma_f32_16x16x32_bf16 v[114:117], v[168:171], v[176:179], v[114:117]
	v_mfma_f32_16x16x32_bf16 v[98:101], v[164:167], v[180:183], v[98:101]
	v_mfma_f32_16x16x32_bf16 v[98:101], v[168:171], v[184:187], v[98:101]
	v_mfma_f32_16x16x32_bf16 v[102:105], v[156:159], v[180:183], v[102:105]
	v_mfma_f32_16x16x32_bf16 v[102:105], v[160:163], v[184:187], v[102:105]
	v_mfma_f32_16x16x32_bf16 v[106:109], v[148:151], v[180:183], v[106:109]
	v_mfma_f32_16x16x32_bf16 v[106:109], v[152:155], v[184:187], v[106:109]
	v_mfma_f32_16x16x32_bf16 v[110:113], v[132:135], v[180:183], v[110:113]
	v_mfma_f32_16x16x32_bf16 v[110:113], v[136:139], v[184:187], v[110:113]
	v_mfma_f32_16x16x32_bf16 v[94:97], v[132:135], v[188:191], v[94:97]
	v_mfma_f32_16x16x32_bf16 v[94:97], v[136:139], v[192:195], v[94:97]
	v_mfma_f32_16x16x32_bf16 v[90:93], v[148:151], v[188:191], v[90:93]
	v_mfma_f32_16x16x32_bf16 v[90:93], v[152:155], v[192:195], v[90:93]
	v_mfma_f32_16x16x32_bf16 v[86:89], v[156:159], v[188:191], v[86:89]
	v_mfma_f32_16x16x32_bf16 v[86:89], v[160:163], v[192:195], v[86:89]
	v_mfma_f32_16x16x32_bf16 v[82:85], v[164:167], v[188:191], v[82:85]
	v_mfma_f32_16x16x32_bf16 v[82:85], v[168:171], v[192:195], v[82:85]
	v_mfma_f32_16x16x32_bf16 v[66:69], v[164:167], v[196:199], v[66:69]
	v_mfma_f32_16x16x32_bf16 v[66:69], v[168:171], v[200:203], v[66:69]
	v_mfma_f32_16x16x32_bf16 v[70:73], v[156:159], v[196:199], v[70:73]
	v_mfma_f32_16x16x32_bf16 v[70:73], v[160:163], v[200:203], v[70:73]
	v_mfma_f32_16x16x32_bf16 v[74:77], v[148:151], v[196:199], v[74:77]
	v_mfma_f32_16x16x32_bf16 v[74:77], v[152:155], v[200:203], v[74:77]
	v_mfma_f32_16x16x32_bf16 v[78:81], v[132:135], v[196:199], v[78:81]
	v_mfma_f32_16x16x32_bf16 v[78:81], v[136:139], v[200:203], v[78:81]
	s_setprio 0
	s_barrier
	s_mov_b32 m0, s25
	s_mov_b32 s18, s14
	s_mov_b32 s19, s15
	buffer_load_dwordx4 v141, s[16:19], s64 offen lds
	ds_read_b128 v[172:175], v144 offset:16384
	ds_read_b128 v[176:179], v144 offset:17408
	ds_read_b128 v[180:183], v144 offset:18432
	ds_read_b128 v[184:187], v144 offset:19456
	ds_read_b128 v[188:191], v144 offset:20480
	ds_read_b128 v[192:195], v144 offset:21504
	ds_read_b128 v[196:199], v144 offset:22528
	ds_read_b128 v[200:203], v144 offset:23552
	s_add_i32 s65, s64, 0x40000
	s_mov_b32 m0, s27
	s_add_i32 s66, s64, 0x80000
	buffer_load_dwordx4 v141, s[16:19], s65 offen lds
	s_mov_b32 m0, s30
	s_add_i32 s67, s64, 0xc0000
	buffer_load_dwordx4 v141, s[16:19], s66 offen lds
	s_mov_b32 m0, s31
	s_nop 0
	buffer_load_dwordx4 v141, s[16:19], s67 offen lds
	s_mov_b32 m0, s21
	s_nop 0
	buffer_load_dwordx4 v140, s[12:15], s64 offen lds
	s_mov_b32 m0, s38
	s_nop 0
	buffer_load_dwordx4 v140, s[12:15], s65 offen lds
	s_waitcnt vmcnt(8)
	s_waitcnt lgkmcnt(0)
	s_setprio 1
	v_mfma_f32_16x16x32_bf16 v[62:65], v[132:135], v[172:175], v[62:65]
	s_barrier
	v_mfma_f32_16x16x32_bf16 v[62:65], v[136:139], v[176:179], v[62:65]
	v_mfma_f32_16x16x32_bf16 v[58:61], v[148:151], v[172:175], v[58:61]
	v_mfma_f32_16x16x32_bf16 v[58:61], v[152:155], v[176:179], v[58:61]
	v_mfma_f32_16x16x32_bf16 v[54:57], v[156:159], v[172:175], v[54:57]
	v_mfma_f32_16x16x32_bf16 v[54:57], v[160:163], v[176:179], v[54:57]
	v_mfma_f32_16x16x32_bf16 v[50:53], v[164:167], v[172:175], v[50:53]
	v_mfma_f32_16x16x32_bf16 v[50:53], v[168:171], v[176:179], v[50:53]
	v_mfma_f32_16x16x32_bf16 v[34:37], v[164:167], v[180:183], v[34:37]
	v_mfma_f32_16x16x32_bf16 v[34:37], v[168:171], v[184:187], v[34:37]
	v_mfma_f32_16x16x32_bf16 v[38:41], v[156:159], v[180:183], v[38:41]
	v_mfma_f32_16x16x32_bf16 v[38:41], v[160:163], v[184:187], v[38:41]
	v_mfma_f32_16x16x32_bf16 v[42:45], v[148:151], v[180:183], v[42:45]
	v_mfma_f32_16x16x32_bf16 v[42:45], v[152:155], v[184:187], v[42:45]
	v_mfma_f32_16x16x32_bf16 v[46:49], v[132:135], v[180:183], v[46:49]
	v_mfma_f32_16x16x32_bf16 v[46:49], v[136:139], v[184:187], v[46:49]
	v_mfma_f32_16x16x32_bf16 v[30:33], v[132:135], v[188:191], v[30:33]
	v_mfma_f32_16x16x32_bf16 v[30:33], v[136:139], v[192:195], v[30:33]
	v_mfma_f32_16x16x32_bf16 v[26:29], v[148:151], v[188:191], v[26:29]
	v_mfma_f32_16x16x32_bf16 v[26:29], v[152:155], v[192:195], v[26:29]
	v_mfma_f32_16x16x32_bf16 v[22:25], v[156:159], v[188:191], v[22:25]
	v_mfma_f32_16x16x32_bf16 v[22:25], v[160:163], v[192:195], v[22:25]
	v_mfma_f32_16x16x32_bf16 v[18:21], v[164:167], v[188:191], v[18:21]
	v_mfma_f32_16x16x32_bf16 v[18:21], v[168:171], v[192:195], v[18:21]
	v_mfma_f32_16x16x32_bf16 v[2:5], v[164:167], v[196:199], v[2:5]
	v_mfma_f32_16x16x32_bf16 v[2:5], v[168:171], v[200:203], v[2:5]
	v_mfma_f32_16x16x32_bf16 v[6:9], v[156:159], v[196:199], v[6:9]
	v_mfma_f32_16x16x32_bf16 v[6:9], v[160:163], v[200:203], v[6:9]
	v_mfma_f32_16x16x32_bf16 v[10:13], v[148:151], v[196:199], v[10:13]
	v_mfma_f32_16x16x32_bf16 v[10:13], v[152:155], v[200:203], v[10:13]
	v_mfma_f32_16x16x32_bf16 v[14:17], v[132:135], v[196:199], v[14:17]
	v_mfma_f32_16x16x32_bf16 v[14:17], v[136:139], v[200:203], v[14:17]
	s_setprio 0
	s_barrier
	ds_read_b128 v[132:135], v145
	ds_read_b128 v[136:139], v145 offset:1024
	ds_read_b128 v[148:151], v145 offset:2048
	ds_read_b128 v[152:155], v145 offset:3072
	ds_read_b128 v[156:159], v147
	ds_read_b128 v[160:163], v147 offset:1024
	ds_read_b128 v[164:167], v147 offset:2048
	ds_read_b128 v[168:171], v147 offset:3072
	s_mov_b32 m0, s39
	s_nop 0
	buffer_load_dwordx4 v140, s[12:15], s66 offen lds
	ds_read_b128 v[172:175], v144 offset:32768
	ds_read_b128 v[176:179], v144 offset:33792
	ds_read_b128 v[180:183], v144 offset:34816
	ds_read_b128 v[184:187], v144 offset:35840
	ds_read_b128 v[188:191], v144 offset:36864
	ds_read_b128 v[192:195], v144 offset:37888
	ds_read_b128 v[196:199], v144 offset:38912
	ds_read_b128 v[200:203], v144 offset:39936
	s_mov_b32 m0, s40
	s_nop 0
	buffer_load_dwordx4 v140, s[12:15], s67 offen lds
	s_waitcnt vmcnt(8)
	s_waitcnt lgkmcnt(0)
	s_setprio 1
	v_mfma_f32_16x16x32_bf16 v[126:129], v[132:135], v[172:175], v[126:129]
	s_barrier
	v_mfma_f32_16x16x32_bf16 v[126:129], v[136:139], v[176:179], v[126:129]
	v_mfma_f32_16x16x32_bf16 v[122:125], v[148:151], v[172:175], v[122:125]
	v_mfma_f32_16x16x32_bf16 v[122:125], v[152:155], v[176:179], v[122:125]
	v_mfma_f32_16x16x32_bf16 v[118:121], v[156:159], v[172:175], v[118:121]
	v_mfma_f32_16x16x32_bf16 v[118:121], v[160:163], v[176:179], v[118:121]
	v_mfma_f32_16x16x32_bf16 v[114:117], v[164:167], v[172:175], v[114:117]
	v_mfma_f32_16x16x32_bf16 v[114:117], v[168:171], v[176:179], v[114:117]
	v_mfma_f32_16x16x32_bf16 v[98:101], v[164:167], v[180:183], v[98:101]
	v_mfma_f32_16x16x32_bf16 v[98:101], v[168:171], v[184:187], v[98:101]
	v_mfma_f32_16x16x32_bf16 v[102:105], v[156:159], v[180:183], v[102:105]
	v_mfma_f32_16x16x32_bf16 v[102:105], v[160:163], v[184:187], v[102:105]
	v_mfma_f32_16x16x32_bf16 v[106:109], v[148:151], v[180:183], v[106:109]
	v_mfma_f32_16x16x32_bf16 v[106:109], v[152:155], v[184:187], v[106:109]
	v_mfma_f32_16x16x32_bf16 v[110:113], v[132:135], v[180:183], v[110:113]
	v_mfma_f32_16x16x32_bf16 v[110:113], v[136:139], v[184:187], v[110:113]
	v_mfma_f32_16x16x32_bf16 v[94:97], v[132:135], v[188:191], v[94:97]
	v_mfma_f32_16x16x32_bf16 v[94:97], v[136:139], v[192:195], v[94:97]
	v_mfma_f32_16x16x32_bf16 v[90:93], v[148:151], v[188:191], v[90:93]
	v_mfma_f32_16x16x32_bf16 v[90:93], v[152:155], v[192:195], v[90:93]
	v_mfma_f32_16x16x32_bf16 v[86:89], v[156:159], v[188:191], v[86:89]
	v_mfma_f32_16x16x32_bf16 v[86:89], v[160:163], v[192:195], v[86:89]
	v_mfma_f32_16x16x32_bf16 v[82:85], v[164:167], v[188:191], v[82:85]
	v_mfma_f32_16x16x32_bf16 v[82:85], v[168:171], v[192:195], v[82:85]
	v_mfma_f32_16x16x32_bf16 v[66:69], v[164:167], v[196:199], v[66:69]
	v_mfma_f32_16x16x32_bf16 v[66:69], v[168:171], v[200:203], v[66:69]
	v_mfma_f32_16x16x32_bf16 v[70:73], v[156:159], v[196:199], v[70:73]
	v_mfma_f32_16x16x32_bf16 v[70:73], v[160:163], v[200:203], v[70:73]
	v_mfma_f32_16x16x32_bf16 v[74:77], v[148:151], v[196:199], v[74:77]
	v_mfma_f32_16x16x32_bf16 v[74:77], v[152:155], v[200:203], v[74:77]
	v_mfma_f32_16x16x32_bf16 v[78:81], v[132:135], v[196:199], v[78:81]
	v_mfma_f32_16x16x32_bf16 v[78:81], v[136:139], v[200:203], v[78:81]
	s_setprio 0
	s_barrier
	s_mov_b32 m0, s48
	s_nop 0
	buffer_load_dwordx4 v141, s[16:19], s63 offen lds
	ds_read_b128 v[172:175], v144 offset:49152
	ds_read_b128 v[176:179], v144 offset:50176
	ds_read_b128 v[180:183], v144 offset:51200
	ds_read_b128 v[184:187], v144 offset:52224
	ds_read_b128 v[188:191], v144 offset:53248
	ds_read_b128 v[192:195], v144 offset:54272
	ds_read_b128 v[196:199], v144 offset:55296
	ds_read_b128 v[200:203], v144 offset:56320
	s_add_i32 s65, s64, 0x40080
	s_mov_b32 m0, s49
	s_add_i32 s66, s64, 0x80080
	buffer_load_dwordx4 v141, s[16:19], s65 offen lds
	s_mov_b32 m0, s52
	s_add_i32 s64, s64, 0xc0080
	buffer_load_dwordx4 v141, s[16:19], s66 offen lds
	s_mov_b32 m0, s53
	s_nop 0
	buffer_load_dwordx4 v141, s[16:19], s64 offen lds
	s_mov_b32 m0, s50
	s_nop 0
	buffer_load_dwordx4 v140, s[12:15], s63 offen lds
	s_mov_b32 m0, s51
	s_nop 0
	buffer_load_dwordx4 v140, s[12:15], s65 offen lds
	s_waitcnt vmcnt(8)
	s_waitcnt lgkmcnt(0)
	s_setprio 1
	v_mfma_f32_16x16x32_bf16 v[62:65], v[132:135], v[172:175], v[62:65]
	s_barrier
	v_mfma_f32_16x16x32_bf16 v[62:65], v[136:139], v[176:179], v[62:65]
	v_mfma_f32_16x16x32_bf16 v[58:61], v[148:151], v[172:175], v[58:61]
	v_mfma_f32_16x16x32_bf16 v[58:61], v[152:155], v[176:179], v[58:61]
	v_mfma_f32_16x16x32_bf16 v[54:57], v[156:159], v[172:175], v[54:57]
	v_mfma_f32_16x16x32_bf16 v[54:57], v[160:163], v[176:179], v[54:57]
	v_mfma_f32_16x16x32_bf16 v[50:53], v[164:167], v[172:175], v[50:53]
	v_mfma_f32_16x16x32_bf16 v[50:53], v[168:171], v[176:179], v[50:53]
	v_mfma_f32_16x16x32_bf16 v[34:37], v[164:167], v[180:183], v[34:37]
	v_mfma_f32_16x16x32_bf16 v[34:37], v[168:171], v[184:187], v[34:37]
	v_mfma_f32_16x16x32_bf16 v[38:41], v[156:159], v[180:183], v[38:41]
	v_mfma_f32_16x16x32_bf16 v[38:41], v[160:163], v[184:187], v[38:41]
	v_mfma_f32_16x16x32_bf16 v[42:45], v[148:151], v[180:183], v[42:45]
	v_mfma_f32_16x16x32_bf16 v[42:45], v[152:155], v[184:187], v[42:45]
	v_mfma_f32_16x16x32_bf16 v[46:49], v[132:135], v[180:183], v[46:49]
	v_mfma_f32_16x16x32_bf16 v[46:49], v[136:139], v[184:187], v[46:49]
	v_mfma_f32_16x16x32_bf16 v[30:33], v[132:135], v[188:191], v[30:33]
	v_mfma_f32_16x16x32_bf16 v[30:33], v[136:139], v[192:195], v[30:33]
	v_mfma_f32_16x16x32_bf16 v[26:29], v[148:151], v[188:191], v[26:29]
	v_mfma_f32_16x16x32_bf16 v[26:29], v[152:155], v[192:195], v[26:29]
	v_mfma_f32_16x16x32_bf16 v[22:25], v[156:159], v[188:191], v[22:25]
	v_mfma_f32_16x16x32_bf16 v[22:25], v[160:163], v[192:195], v[22:25]
	v_mfma_f32_16x16x32_bf16 v[18:21], v[164:167], v[188:191], v[18:21]
	v_mfma_f32_16x16x32_bf16 v[18:21], v[168:171], v[192:195], v[18:21]
	v_mfma_f32_16x16x32_bf16 v[2:5], v[164:167], v[196:199], v[2:5]
	v_mfma_f32_16x16x32_bf16 v[2:5], v[168:171], v[200:203], v[2:5]
	v_mfma_f32_16x16x32_bf16 v[6:9], v[156:159], v[196:199], v[6:9]
	v_mfma_f32_16x16x32_bf16 v[6:9], v[160:163], v[200:203], v[6:9]
	v_mfma_f32_16x16x32_bf16 v[10:13], v[148:151], v[196:199], v[10:13]
	v_mfma_f32_16x16x32_bf16 v[10:13], v[152:155], v[200:203], v[10:13]
	v_mfma_f32_16x16x32_bf16 v[14:17], v[132:135], v[196:199], v[14:17]
	v_mfma_f32_16x16x32_bf16 v[14:17], v[136:139], v[200:203], v[14:17]
	s_setprio 0
	s_barrier
	s_add_i32 s62, s62, 2
	s_addk_i32 s61, 0x100
	s_cmp_ge_i32 s62, s3
	s_cbranch_scc0 .LBB0_1050

.LBB0_1181:
	v_add_u32_e32 v2, 0x10000, v232
	ds_read_b128 v[134:137], v2
	ds_read_b128 v[138:141], v2 offset:1024
	ds_read_b128 v[142:145], v2 offset:2048
	ds_read_b128 v[146:149], v2 offset:3072
	v_add_u32_e32 v2, 0x14000, v232
	ds_read_b128 v[150:153], v2
	ds_read_b128 v[154:157], v2 offset:1024
	ds_read_b128 v[158:161], v2 offset:2048
	ds_read_b128 v[162:165], v2 offset:3072
	s_add_i32 s50, s47, s90
	s_and_b64 s[18:19], exec, s[18:19]
	s_cselect_b32 s51, s88, s50
	s_add_i32 s50, s92, 0x80
	s_or_b32 s52, s51, 0x80
	s_add_i32 s18, s89, s93
	s_add_i32 s94, s94, 0x1bfffc80
	s_cmp_lt_u32 s91, 8
	s_cselect_b32 s18, s18, s94
	s_mov_b32 m0, s74
	s_add_i32 s19, s18, 0x80000
	buffer_load_dwordx4 v230, s[12:15], s19 offen lds
	ds_read_b128 v[166:169], v233
	ds_read_b128 v[170:173], v233 offset:1024
	ds_read_b128 v[174:177], v233 offset:2048
	ds_read_b128 v[178:181], v233 offset:3072
	ds_read_b128 v[182:185], v233 offset:4096
	ds_read_b128 v[186:189], v233 offset:5120
	ds_read_b128 v[190:193], v233 offset:6144
	ds_read_b128 v[194:197], v233 offset:7168
	s_add_i32 s18, s18, 0xc0000
	s_mov_b32 m0, s75
	s_nop 0
	buffer_load_dwordx4 v230, s[12:15], s18 offen lds
	s_waitcnt vmcnt(8)
	s_waitcnt lgkmcnt(0)
	s_setprio 1
	v_mfma_f32_16x16x32_bf16 v[130:133], v[134:137], v[166:169], v[130:133]
	s_barrier
	v_mfma_f32_16x16x32_bf16 v[130:133], v[138:141], v[170:173], v[130:133]
	v_mfma_f32_16x16x32_bf16 v[126:129], v[142:145], v[166:169], v[126:129]
	v_mfma_f32_16x16x32_bf16 v[126:129], v[146:149], v[170:173], v[126:129]
	v_mfma_f32_16x16x32_bf16 v[122:125], v[150:153], v[166:169], v[122:125]
	v_mfma_f32_16x16x32_bf16 v[122:125], v[154:157], v[170:173], v[122:125]
	v_mfma_f32_16x16x32_bf16 v[118:121], v[158:161], v[166:169], v[118:121]
	v_mfma_f32_16x16x32_bf16 v[118:121], v[162:165], v[170:173], v[118:121]
	v_mfma_f32_16x16x32_bf16 v[102:105], v[158:161], v[174:177], v[102:105]
	v_mfma_f32_16x16x32_bf16 v[102:105], v[162:165], v[178:181], v[102:105]
	v_mfma_f32_16x16x32_bf16 v[106:109], v[150:153], v[174:177], v[106:109]
	v_mfma_f32_16x16x32_bf16 v[106:109], v[154:157], v[178:181], v[106:109]
	v_mfma_f32_16x16x32_bf16 v[110:113], v[142:145], v[174:177], v[110:113]
	v_mfma_f32_16x16x32_bf16 v[110:113], v[146:149], v[178:181], v[110:113]
	v_mfma_f32_16x16x32_bf16 v[114:117], v[134:137], v[174:177], v[114:117]
	v_mfma_f32_16x16x32_bf16 v[114:117], v[138:141], v[178:181], v[114:117]
	v_mfma_f32_16x16x32_bf16 v[98:101], v[134:137], v[182:185], v[98:101]
	v_mfma_f32_16x16x32_bf16 v[98:101], v[138:141], v[186:189], v[98:101]
	v_mfma_f32_16x16x32_bf16 v[94:97], v[142:145], v[182:185], v[94:97]
	v_mfma_f32_16x16x32_bf16 v[94:97], v[146:149], v[186:189], v[94:97]
	v_mfma_f32_16x16x32_bf16 v[90:93], v[150:153], v[182:185], v[90:93]
	v_mfma_f32_16x16x32_bf16 v[90:93], v[154:157], v[186:189], v[90:93]
	v_mfma_f32_16x16x32_bf16 v[86:89], v[158:161], v[182:185], v[86:89]
	v_mfma_f32_16x16x32_bf16 v[86:89], v[162:165], v[186:189], v[86:89]
	v_mfma_f32_16x16x32_bf16 v[70:73], v[158:161], v[190:193], v[70:73]
	v_mfma_f32_16x16x32_bf16 v[70:73], v[162:165], v[194:197], v[70:73]
	v_mfma_f32_16x16x32_bf16 v[74:77], v[150:153], v[190:193], v[74:77]
	v_mfma_f32_16x16x32_bf16 v[74:77], v[154:157], v[194:197], v[74:77]
	v_mfma_f32_16x16x32_bf16 v[78:81], v[142:145], v[190:193], v[78:81]
	v_mfma_f32_16x16x32_bf16 v[78:81], v[146:149], v[194:197], v[78:81]
	v_mfma_f32_16x16x32_bf16 v[82:85], v[134:137], v[190:193], v[82:85]
	v_mfma_f32_16x16x32_bf16 v[82:85], v[138:141], v[194:197], v[82:85]
	s_setprio 0
	s_barrier
	s_mov_b32 m0, s27
	s_mov_b32 s18, s14
	s_mov_b32 s19, s15
	buffer_load_dwordx4 v231, s[16:19], s51 offen lds
	ds_read_b128 v[166:169], v233 offset:16384
	ds_read_b128 v[170:173], v233 offset:17408
	ds_read_b128 v[174:177], v233 offset:18432
	ds_read_b128 v[178:181], v233 offset:19456
	ds_read_b128 v[182:185], v233 offset:20480
	ds_read_b128 v[186:189], v233 offset:21504
	ds_read_b128 v[190:193], v233 offset:22528
	ds_read_b128 v[194:197], v233 offset:23552
	s_add_i32 s53, s51, 0x18000
	s_mov_b32 m0, s30
	s_nop 0
	buffer_load_dwordx4 v231, s[16:19], s53 offen lds
	s_add_i32 s53, s51, 0x30000
	s_mov_b32 m0, s31
	s_nop 0
	buffer_load_dwordx4 v231, s[16:19], s53 offen lds
	s_add_i32 s53, s51, 0x48000
	s_mov_b32 m0, s54
	s_nop 0
	buffer_load_dwordx4 v231, s[16:19], s53 offen lds
	s_mov_b32 m0, s25
	s_add_i32 s53, s92, 0x40000
	buffer_load_dwordx4 v230, s[12:15], s92 offen lds
	s_mov_b32 m0, s55
	s_nop 0
	buffer_load_dwordx4 v230, s[12:15], s53 offen lds
	s_waitcnt vmcnt(8)
	s_waitcnt lgkmcnt(0)
	s_setprio 1
	v_mfma_f32_16x16x32_bf16 v[66:69], v[134:137], v[166:169], v[66:69]
	s_barrier
	v_mfma_f32_16x16x32_bf16 v[62:65], v[142:145], v[166:169], v[62:65]
	v_mfma_f32_16x16x32_bf16 v[50:53], v[134:137], v[174:177], v[50:53]
	v_mfma_f32_16x16x32_bf16 v[46:49], v[142:145], v[174:177], v[46:49]
	v_mfma_f32_16x16x32_bf16 v[34:37], v[134:137], v[182:185], v[34:37]
	v_mfma_f32_16x16x32_bf16 v[30:33], v[142:145], v[182:185], v[30:33]
	v_mfma_f32_16x16x32_bf16 v[18:21], v[134:137], v[190:193], v[18:21]
	v_mfma_f32_16x16x32_bf16 v[14:17], v[142:145], v[190:193], v[14:17]
	v_mfma_f32_16x16x32_bf16 v[58:61], v[150:153], v[166:169], v[58:61]
	v_mfma_f32_16x16x32_bf16 v[54:57], v[158:161], v[166:169], v[54:57]
	v_mfma_f32_16x16x32_bf16 v[42:45], v[150:153], v[174:177], v[42:45]
	v_mfma_f32_16x16x32_bf16 v[38:41], v[158:161], v[174:177], v[38:41]
	v_mfma_f32_16x16x32_bf16 v[26:29], v[150:153], v[182:185], v[26:29]
	v_mfma_f32_16x16x32_bf16 v[22:25], v[158:161], v[182:185], v[22:25]
	v_mfma_f32_16x16x32_bf16 v[10:13], v[150:153], v[190:193], v[10:13]
	v_mfma_f32_16x16x32_bf16 v[4:7], v[158:161], v[190:193], v[6:9]
	v_mfma_f32_16x16x32_bf16 v[66:69], v[138:141], v[170:173], v[66:69]
	v_mfma_f32_16x16x32_bf16 v[62:65], v[146:149], v[170:173], v[62:65]
	v_mfma_f32_16x16x32_bf16 v[50:53], v[138:141], v[178:181], v[50:53]
	v_mfma_f32_16x16x32_bf16 v[46:49], v[146:149], v[178:181], v[46:49]
	v_mfma_f32_16x16x32_bf16 v[34:37], v[138:141], v[186:189], v[34:37]
	v_mfma_f32_16x16x32_bf16 v[30:33], v[146:149], v[186:189], v[30:33]
	v_mfma_f32_16x16x32_bf16 v[18:21], v[138:141], v[194:197], v[18:21]
	v_mfma_f32_16x16x32_bf16 v[14:17], v[146:149], v[194:197], v[14:17]
	v_mfma_f32_16x16x32_bf16 v[58:61], v[154:157], v[170:173], v[58:61]
	v_mfma_f32_16x16x32_bf16 v[54:57], v[162:165], v[170:173], v[54:57]
	v_mfma_f32_16x16x32_bf16 v[42:45], v[154:157], v[178:181], v[42:45]
	v_mfma_f32_16x16x32_bf16 v[38:41], v[162:165], v[178:181], v[38:41]
	v_mfma_f32_16x16x32_bf16 v[26:29], v[154:157], v[186:189], v[26:29]
	v_mfma_f32_16x16x32_bf16 v[22:25], v[162:165], v[186:189], v[22:25]
	v_mfma_f32_16x16x32_bf16 v[10:13], v[154:157], v[194:197], v[10:13]
	v_mfma_f32_16x16x32_bf16 v[4:7], v[162:165], v[194:197], v[4:7]
	s_setprio 0
	s_barrier
	v_add_u32_e32 v2, 0x18000, v232
	ds_read_b128 v[134:137], v2
	ds_read_b128 v[138:141], v2 offset:1024
	ds_read_b128 v[142:145], v2 offset:2048
	ds_read_b128 v[146:149], v2 offset:3072
	v_add_u32_e32 v2, 0x1c000, v232
	ds_read_b128 v[150:153], v2
	ds_read_b128 v[154:157], v2 offset:1024
	ds_read_b128 v[158:161], v2 offset:2048
	ds_read_b128 v[162:165], v2 offset:3072
	s_mov_b32 m0, s56
	s_add_i32 s53, s92, 0x80000
	buffer_load_dwordx4 v230, s[12:15], s53 offen lds
	ds_read_b128 v[166:169], v233 offset:32768
	ds_read_b128 v[170:173], v233 offset:33792
	ds_read_b128 v[174:177], v233 offset:34816
	ds_read_b128 v[178:181], v233 offset:35840
	ds_read_b128 v[182:185], v233 offset:36864
	ds_read_b128 v[186:189], v233 offset:37888
	ds_read_b128 v[190:193], v233 offset:38912
	ds_read_b128 v[194:197], v233 offset:39936
	s_add_i32 s53, s92, 0xc0000
	s_mov_b32 m0, s57
	s_nop 0
	buffer_load_dwordx4 v230, s[12:15], s53 offen lds
	s_waitcnt vmcnt(8)
	s_waitcnt lgkmcnt(0)
	s_setprio 1
	v_mfma_f32_16x16x32_bf16 v[130:133], v[134:137], v[166:169], v[130:133]
	s_barrier
	v_mfma_f32_16x16x32_bf16 v[130:133], v[138:141], v[170:173], v[130:133]
	v_mfma_f32_16x16x32_bf16 v[126:129], v[142:145], v[166:169], v[126:129]
	v_mfma_f32_16x16x32_bf16 v[126:129], v[146:149], v[170:173], v[126:129]
	v_mfma_f32_16x16x32_bf16 v[122:125], v[150:153], v[166:169], v[122:125]
	v_mfma_f32_16x16x32_bf16 v[122:125], v[154:157], v[170:173], v[122:125]
	v_mfma_f32_16x16x32_bf16 v[118:121], v[158:161], v[166:169], v[118:121]
	v_mfma_f32_16x16x32_bf16 v[118:121], v[162:165], v[170:173], v[118:121]
	v_mfma_f32_16x16x32_bf16 v[102:105], v[158:161], v[174:177], v[102:105]
	v_mfma_f32_16x16x32_bf16 v[102:105], v[162:165], v[178:181], v[102:105]
	v_mfma_f32_16x16x32_bf16 v[106:109], v[150:153], v[174:177], v[106:109]
	v_mfma_f32_16x16x32_bf16 v[106:109], v[154:157], v[178:181], v[106:109]
	v_mfma_f32_16x16x32_bf16 v[110:113], v[142:145], v[174:177], v[110:113]
	v_mfma_f32_16x16x32_bf16 v[110:113], v[146:149], v[178:181], v[110:113]
	v_mfma_f32_16x16x32_bf16 v[114:117], v[134:137], v[174:177], v[114:117]
	v_mfma_f32_16x16x32_bf16 v[114:117], v[138:141], v[178:181], v[114:117]
	v_mfma_f32_16x16x32_bf16 v[98:101], v[134:137], v[182:185], v[98:101]
	v_mfma_f32_16x16x32_bf16 v[98:101], v[138:141], v[186:189], v[98:101]
	v_mfma_f32_16x16x32_bf16 v[94:97], v[142:145], v[182:185], v[94:97]
	v_mfma_f32_16x16x32_bf16 v[94:97], v[146:149], v[186:189], v[94:97]
	v_mfma_f32_16x16x32_bf16 v[90:93], v[150:153], v[182:185], v[90:93]
	v_mfma_f32_16x16x32_bf16 v[90:93], v[154:157], v[186:189], v[90:93]
	v_mfma_f32_16x16x32_bf16 v[86:89], v[158:161], v[182:185], v[86:89]
	v_mfma_f32_16x16x32_bf16 v[86:89], v[162:165], v[186:189], v[86:89]
	v_mfma_f32_16x16x32_bf16 v[70:73], v[158:161], v[190:193], v[70:73]
	v_mfma_f32_16x16x32_bf16 v[70:73], v[162:165], v[194:197], v[70:73]
	v_mfma_f32_16x16x32_bf16 v[74:77], v[150:153], v[190:193], v[74:77]
	v_mfma_f32_16x16x32_bf16 v[74:77], v[154:157], v[194:197], v[74:77]
	v_mfma_f32_16x16x32_bf16 v[78:81], v[142:145], v[190:193], v[78:81]
	v_mfma_f32_16x16x32_bf16 v[78:81], v[146:149], v[194:197], v[78:81]
	v_mfma_f32_16x16x32_bf16 v[82:85], v[134:137], v[190:193], v[82:85]
	v_mfma_f32_16x16x32_bf16 v[82:85], v[138:141], v[194:197], v[82:85]
	s_setprio 0
	s_barrier
	s_mov_b32 m0, s64
	s_nop 0
	buffer_load_dwordx4 v231, s[16:19], s52 offen lds
	ds_read_b128 v[166:169], v233 offset:49152
	ds_read_b128 v[170:173], v233 offset:50176
	ds_read_b128 v[174:177], v233 offset:51200
	ds_read_b128 v[178:181], v233 offset:52224
	ds_read_b128 v[182:185], v233 offset:53248
	ds_read_b128 v[186:189], v233 offset:54272
	ds_read_b128 v[190:193], v233 offset:55296
	ds_read_b128 v[194:197], v233 offset:56320
	s_add_i32 s52, s51, 0x18080
	s_mov_b32 m0, s65
	s_nop 0
	buffer_load_dwordx4 v231, s[16:19], s52 offen lds
	s_add_i32 s52, s51, 0x30080
	s_mov_b32 m0, s68
	s_add_i32 s51, s51, 0x48080
	buffer_load_dwordx4 v231, s[16:19], s52 offen lds
	s_mov_b32 m0, s69
	s_nop 0
	buffer_load_dwordx4 v231, s[16:19], s51 offen lds
	s_mov_b32 m0, s66
	s_add_i32 s18, s92, 0x40080
	buffer_load_dwordx4 v230, s[12:15], s50 offen lds
	s_mov_b32 m0, s67
	s_nop 0
	buffer_load_dwordx4 v230, s[12:15], s18 offen lds
	s_waitcnt vmcnt(8)
	s_waitcnt lgkmcnt(0)
	s_setprio 1
	v_mfma_f32_16x16x32_bf16 v[66:69], v[134:137], v[166:169], v[66:69]
	s_barrier
	v_mfma_f32_16x16x32_bf16 v[62:65], v[142:145], v[166:169], v[62:65]
	v_mfma_f32_16x16x32_bf16 v[50:53], v[134:137], v[174:177], v[50:53]
	v_mfma_f32_16x16x32_bf16 v[46:49], v[142:145], v[174:177], v[46:49]
	v_mfma_f32_16x16x32_bf16 v[34:37], v[134:137], v[182:185], v[34:37]
	v_mfma_f32_16x16x32_bf16 v[30:33], v[142:145], v[182:185], v[30:33]
	v_mfma_f32_16x16x32_bf16 v[18:21], v[134:137], v[190:193], v[18:21]
	v_mfma_f32_16x16x32_bf16 v[14:17], v[142:145], v[190:193], v[14:17]
	v_mfma_f32_16x16x32_bf16 v[58:61], v[150:153], v[166:169], v[58:61]
	v_mfma_f32_16x16x32_bf16 v[54:57], v[158:161], v[166:169], v[54:57]
	v_mfma_f32_16x16x32_bf16 v[42:45], v[150:153], v[174:177], v[42:45]
	v_mfma_f32_16x16x32_bf16 v[38:41], v[158:161], v[174:177], v[38:41]
	v_mfma_f32_16x16x32_bf16 v[26:29], v[150:153], v[182:185], v[26:29]
	v_mfma_f32_16x16x32_bf16 v[22:25], v[158:161], v[182:185], v[22:25]
	v_mfma_f32_16x16x32_bf16 v[8:11], v[150:153], v[190:193], v[10:13]
	v_mfma_f32_16x16x32_bf16 v[4:7], v[158:161], v[190:193], v[4:7]
	v_mfma_f32_16x16x32_bf16 v[66:69], v[138:141], v[170:173], v[66:69]
	v_mfma_f32_16x16x32_bf16 v[62:65], v[146:149], v[170:173], v[62:65]
	v_mfma_f32_16x16x32_bf16 v[50:53], v[138:141], v[178:181], v[50:53]
	v_mfma_f32_16x16x32_bf16 v[46:49], v[146:149], v[178:181], v[46:49]
	v_mfma_f32_16x16x32_bf16 v[34:37], v[138:141], v[186:189], v[34:37]
	v_mfma_f32_16x16x32_bf16 v[30:33], v[146:149], v[186:189], v[30:33]
	v_mfma_f32_16x16x32_bf16 v[18:21], v[138:141], v[194:197], v[18:21]
	v_mfma_f32_16x16x32_bf16 v[14:17], v[146:149], v[194:197], v[14:17]
	v_mfma_f32_16x16x32_bf16 v[58:61], v[154:157], v[170:173], v[58:61]
	v_mfma_f32_16x16x32_bf16 v[54:57], v[162:165], v[170:173], v[54:57]
	v_mfma_f32_16x16x32_bf16 v[42:45], v[154:157], v[178:181], v[42:45]
	v_mfma_f32_16x16x32_bf16 v[38:41], v[162:165], v[178:181], v[38:41]
	v_mfma_f32_16x16x32_bf16 v[26:29], v[154:157], v[186:189], v[26:29]
	v_mfma_f32_16x16x32_bf16 v[22:25], v[162:165], v[186:189], v[22:25]
	v_mfma_f32_16x16x32_bf16 v[10:13], v[154:157], v[194:197], v[8:11]
	v_mfma_f32_16x16x32_bf16 v[6:9], v[162:165], v[194:197], v[4:7]
	s_setprio 0
	s_barrier
	s_add_i32 s91, s91, 2
	s_addk_i32 s90, 0x100
	s_cmp_ge_i32 s91, s3
	s_cbranch_scc1 .LBB0_1193

.LBB0_1290:
	ds_read_b128 v[106:109], v224
	ds_read_b128 v[118:121], v224 offset:1024
	ds_read_b128 v[130:133], v224 offset:2048
	ds_read_b128 v[138:141], v224 offset:3072
	ds_read_b128 v[146:149], v225
	ds_read_b128 v[150:153], v225 offset:1024
	ds_read_b128 v[154:157], v225 offset:2048
	ds_read_b128 v[158:161], v225 offset:3072
	s_add_i32 s18, s72, 0xffe80080
	s_cmp_eq_u32 s56, s74
	s_cselect_b32 s75, s6, s18
	s_cselect_b32 s77, s7, s73
	s_or_b32 s76, s75, 0x80
	s_add_i32 s18, s72, 0xfff80000
	s_mov_b32 m0, s57
	s_nop 0
	buffer_load_dwordx4 v222, s[12:15], s18 offen lds
	ds_read_b128 v[162:165], v226
	ds_read_b128 v[166:169], v226 offset:1024
	ds_read_b128 v[170:173], v226 offset:2048
	ds_read_b128 v[174:177], v226 offset:3072
	ds_read_b128 v[178:181], v226 offset:4096
	ds_read_b128 v[182:185], v226 offset:5120
	ds_read_b128 v[190:193], v226 offset:6144
	ds_read_b128 v[194:197], v226 offset:7168
	s_mov_b32 m0, s60
	s_nop 0
	buffer_load_dwordx4 v222, s[12:15], s72 offen lds
	s_waitcnt vmcnt(8)
	s_waitcnt lgkmcnt(0)
	s_setprio 1
	v_mfma_f32_16x16x32_bf16 v[142:145], v[106:109], v[162:165], v[142:145]
	s_barrier
	v_mfma_f32_16x16x32_bf16 v[142:145], v[118:121], v[166:169], v[142:145]
	v_mfma_f32_16x16x32_bf16 v[134:137], v[130:133], v[162:165], v[134:137]
	v_mfma_f32_16x16x32_bf16 v[134:137], v[138:141], v[166:169], v[134:137]
	v_mfma_f32_16x16x32_bf16 v[126:129], v[146:149], v[162:165], v[126:129]
	v_mfma_f32_16x16x32_bf16 v[126:129], v[150:153], v[166:169], v[126:129]
	v_mfma_f32_16x16x32_bf16 v[122:125], v[154:157], v[162:165], v[122:125]
	v_mfma_f32_16x16x32_bf16 v[122:125], v[158:161], v[166:169], v[122:125]
	v_mfma_f32_16x16x32_bf16 v[98:101], v[154:157], v[170:173], v[98:101]
	v_mfma_f32_16x16x32_bf16 v[98:101], v[158:161], v[174:177], v[98:101]
	v_mfma_f32_16x16x32_bf16 v[102:105], v[146:149], v[170:173], v[102:105]
	v_mfma_f32_16x16x32_bf16 v[102:105], v[150:153], v[174:177], v[102:105]
	v_mfma_f32_16x16x32_bf16 v[110:113], v[130:133], v[170:173], v[110:113]
	v_mfma_f32_16x16x32_bf16 v[110:113], v[138:141], v[174:177], v[110:113]
	v_mfma_f32_16x16x32_bf16 v[114:117], v[106:109], v[170:173], v[114:117]
	v_mfma_f32_16x16x32_bf16 v[114:117], v[118:121], v[174:177], v[114:117]
	v_mfma_f32_16x16x32_bf16 v[94:97], v[106:109], v[178:181], v[94:97]
	v_mfma_f32_16x16x32_bf16 v[94:97], v[118:121], v[182:185], v[94:97]
	v_mfma_f32_16x16x32_bf16 v[90:93], v[130:133], v[178:181], v[90:93]
	v_mfma_f32_16x16x32_bf16 v[90:93], v[138:141], v[182:185], v[90:93]
	v_mfma_f32_16x16x32_bf16 v[86:89], v[146:149], v[178:181], v[86:89]
	v_mfma_f32_16x16x32_bf16 v[86:89], v[150:153], v[182:185], v[86:89]
	v_mfma_f32_16x16x32_bf16 v[82:85], v[154:157], v[178:181], v[82:85]
	v_mfma_f32_16x16x32_bf16 v[82:85], v[158:161], v[182:185], v[82:85]
	v_mfma_f32_16x16x32_bf16 v[66:69], v[154:157], v[190:193], v[66:69]
	v_mfma_f32_16x16x32_bf16 v[66:69], v[158:161], v[194:197], v[66:69]
	v_mfma_f32_16x16x32_bf16 v[70:73], v[146:149], v[190:193], v[70:73]
	v_mfma_f32_16x16x32_bf16 v[70:73], v[150:153], v[194:197], v[70:73]
	v_mfma_f32_16x16x32_bf16 v[74:77], v[130:133], v[190:193], v[74:77]
	v_mfma_f32_16x16x32_bf16 v[74:77], v[138:141], v[194:197], v[74:77]
	v_mfma_f32_16x16x32_bf16 v[78:81], v[106:109], v[190:193], v[78:81]
	v_mfma_f32_16x16x32_bf16 v[78:81], v[118:121], v[194:197], v[78:81]
	s_setprio 0
	s_barrier
	s_mov_b32 m0, s27
	s_mov_b32 s18, s14
	s_mov_b32 s19, s15
	buffer_load_dwordx4 v223, s[16:19], s77 offen lds
	ds_read_b128 v[162:165], v226 offset:16384
	ds_read_b128 v[166:169], v226 offset:17408
	ds_read_b128 v[170:173], v226 offset:18432
	ds_read_b128 v[174:177], v226 offset:19456
	ds_read_b128 v[178:181], v226 offset:20480
	ds_read_b128 v[182:185], v226 offset:21504
	ds_read_b128 v[190:193], v226 offset:22528
	ds_read_b128 v[194:197], v226 offset:23552
	s_add_i32 s78, s77, 0x80000
	s_mov_b32 m0, s30
	s_nop 0
	buffer_load_dwordx4 v223, s[16:19], s78 offen lds
	s_add_i32 s78, s77, 0x100000
	s_mov_b32 m0, s31
	s_nop 0
	buffer_load_dwordx4 v223, s[16:19], s78 offen lds
	s_add_i32 s78, s77, 0x180000
	s_mov_b32 m0, s41
	s_nop 0
	buffer_load_dwordx4 v223, s[16:19], s78 offen lds
	s_mov_b32 m0, s25
	s_add_i32 s78, s75, 0x80000
	buffer_load_dwordx4 v222, s[12:15], s75 offen lds
	s_mov_b32 m0, s42
	s_nop 0
	buffer_load_dwordx4 v222, s[12:15], s78 offen lds
	s_waitcnt vmcnt(8)
	s_waitcnt lgkmcnt(0)
	s_setprio 1
	v_mfma_f32_16x16x32_bf16 v[62:65], v[106:109], v[162:165], v[62:65]
	s_barrier
	v_mfma_f32_16x16x32_bf16 v[62:65], v[118:121], v[166:169], v[62:65]
	v_mfma_f32_16x16x32_bf16 v[58:61], v[130:133], v[162:165], v[58:61]
	v_mfma_f32_16x16x32_bf16 v[58:61], v[138:141], v[166:169], v[58:61]
	v_mfma_f32_16x16x32_bf16 v[54:57], v[146:149], v[162:165], v[54:57]
	v_mfma_f32_16x16x32_bf16 v[54:57], v[150:153], v[166:169], v[54:57]
	v_mfma_f32_16x16x32_bf16 v[50:53], v[154:157], v[162:165], v[50:53]
	v_mfma_f32_16x16x32_bf16 v[50:53], v[158:161], v[166:169], v[50:53]
	v_mfma_f32_16x16x32_bf16 v[34:37], v[154:157], v[170:173], v[34:37]
	v_mfma_f32_16x16x32_bf16 v[34:37], v[158:161], v[174:177], v[34:37]
	v_mfma_f32_16x16x32_bf16 v[38:41], v[146:149], v[170:173], v[38:41]
	v_mfma_f32_16x16x32_bf16 v[38:41], v[150:153], v[174:177], v[38:41]
	v_mfma_f32_16x16x32_bf16 v[42:45], v[130:133], v[170:173], v[42:45]
	v_mfma_f32_16x16x32_bf16 v[42:45], v[138:141], v[174:177], v[42:45]
	v_mfma_f32_16x16x32_bf16 v[46:49], v[106:109], v[170:173], v[46:49]
	v_mfma_f32_16x16x32_bf16 v[46:49], v[118:121], v[174:177], v[46:49]
	v_mfma_f32_16x16x32_bf16 v[30:33], v[106:109], v[178:181], v[30:33]
	v_mfma_f32_16x16x32_bf16 v[30:33], v[118:121], v[182:185], v[30:33]
	v_mfma_f32_16x16x32_bf16 v[26:29], v[130:133], v[178:181], v[26:29]
	v_mfma_f32_16x16x32_bf16 v[26:29], v[138:141], v[182:185], v[26:29]
	v_mfma_f32_16x16x32_bf16 v[22:25], v[146:149], v[178:181], v[22:25]
	v_mfma_f32_16x16x32_bf16 v[22:25], v[150:153], v[182:185], v[22:25]
	v_mfma_f32_16x16x32_bf16 v[18:21], v[154:157], v[178:181], v[18:21]
	v_mfma_f32_16x16x32_bf16 v[18:21], v[158:161], v[182:185], v[18:21]
	v_mfma_f32_16x16x32_bf16 v[2:5], v[154:157], v[190:193], v[2:5]
	v_mfma_f32_16x16x32_bf16 v[2:5], v[158:161], v[194:197], v[2:5]
	v_mfma_f32_16x16x32_bf16 v[6:9], v[146:149], v[190:193], v[6:9]
	v_mfma_f32_16x16x32_bf16 v[6:9], v[150:153], v[194:197], v[6:9]
	v_mfma_f32_16x16x32_bf16 v[10:13], v[130:133], v[190:193], v[10:13]
	v_mfma_f32_16x16x32_bf16 v[10:13], v[138:141], v[194:197], v[10:13]
	v_mfma_f32_16x16x32_bf16 v[14:17], v[106:109], v[190:193], v[14:17]
	v_mfma_f32_16x16x32_bf16 v[14:17], v[118:121], v[194:197], v[14:17]
	s_setprio 0
	s_barrier
	ds_read_b128 v[106:109], v227
	ds_read_b128 v[118:121], v227 offset:1024
	ds_read_b128 v[130:133], v227 offset:2048
	ds_read_b128 v[138:141], v227 offset:3072
	ds_read_b128 v[146:149], v228
	ds_read_b128 v[150:153], v228 offset:1024
	ds_read_b128 v[154:157], v228 offset:2048
	ds_read_b128 v[158:161], v228 offset:3072
	s_mov_b32 m0, s43
	s_add_i32 s78, s75, 0x100000
	buffer_load_dwordx4 v222, s[12:15], s78 offen lds
	ds_read_b128 v[162:165], v226 offset:32768
	ds_read_b128 v[166:169], v226 offset:33792
	ds_read_b128 v[170:173], v226 offset:34816
	ds_read_b128 v[174:177], v226 offset:35840
	ds_read_b128 v[178:181], v226 offset:36864
	ds_read_b128 v[182:185], v226 offset:37888
	ds_read_b128 v[190:193], v226 offset:38912
	ds_read_b128 v[194:197], v226 offset:39936
	s_add_i32 s78, s75, 0x180000
	s_mov_b32 m0, s44
	s_nop 0
	buffer_load_dwordx4 v222, s[12:15], s78 offen lds
	s_waitcnt vmcnt(8)
	s_waitcnt lgkmcnt(0)
	s_setprio 1
	v_mfma_f32_16x16x32_bf16 v[142:145], v[106:109], v[162:165], v[142:145]
	s_barrier
	v_mfma_f32_16x16x32_bf16 v[142:145], v[118:121], v[166:169], v[142:145]
	v_mfma_f32_16x16x32_bf16 v[134:137], v[130:133], v[162:165], v[134:137]
	v_mfma_f32_16x16x32_bf16 v[134:137], v[138:141], v[166:169], v[134:137]
	v_mfma_f32_16x16x32_bf16 v[126:129], v[146:149], v[162:165], v[126:129]
	v_mfma_f32_16x16x32_bf16 v[126:129], v[150:153], v[166:169], v[126:129]
	v_mfma_f32_16x16x32_bf16 v[122:125], v[154:157], v[162:165], v[122:125]
	v_mfma_f32_16x16x32_bf16 v[122:125], v[158:161], v[166:169], v[122:125]
	v_mfma_f32_16x16x32_bf16 v[98:101], v[154:157], v[170:173], v[98:101]
	v_mfma_f32_16x16x32_bf16 v[98:101], v[158:161], v[174:177], v[98:101]
	v_mfma_f32_16x16x32_bf16 v[102:105], v[146:149], v[170:173], v[102:105]
	v_mfma_f32_16x16x32_bf16 v[102:105], v[150:153], v[174:177], v[102:105]
	v_mfma_f32_16x16x32_bf16 v[110:113], v[130:133], v[170:173], v[110:113]
	v_mfma_f32_16x16x32_bf16 v[110:113], v[138:141], v[174:177], v[110:113]
	v_mfma_f32_16x16x32_bf16 v[114:117], v[106:109], v[170:173], v[114:117]
	v_mfma_f32_16x16x32_bf16 v[114:117], v[118:121], v[174:177], v[114:117]
	v_mfma_f32_16x16x32_bf16 v[94:97], v[106:109], v[178:181], v[94:97]
	v_mfma_f32_16x16x32_bf16 v[94:97], v[118:121], v[182:185], v[94:97]
	v_mfma_f32_16x16x32_bf16 v[90:93], v[130:133], v[178:181], v[90:93]
	v_mfma_f32_16x16x32_bf16 v[90:93], v[138:141], v[182:185], v[90:93]
	v_mfma_f32_16x16x32_bf16 v[86:89], v[146:149], v[178:181], v[86:89]
	v_mfma_f32_16x16x32_bf16 v[86:89], v[150:153], v[182:185], v[86:89]
	v_mfma_f32_16x16x32_bf16 v[82:85], v[154:157], v[178:181], v[82:85]
	v_mfma_f32_16x16x32_bf16 v[82:85], v[158:161], v[182:185], v[82:85]
	v_mfma_f32_16x16x32_bf16 v[66:69], v[154:157], v[190:193], v[66:69]
	v_mfma_f32_16x16x32_bf16 v[66:69], v[158:161], v[194:197], v[66:69]
	v_mfma_f32_16x16x32_bf16 v[70:73], v[146:149], v[190:193], v[70:73]
	v_mfma_f32_16x16x32_bf16 v[70:73], v[150:153], v[194:197], v[70:73]
	v_mfma_f32_16x16x32_bf16 v[74:77], v[130:133], v[190:193], v[74:77]
	v_mfma_f32_16x16x32_bf16 v[74:77], v[138:141], v[194:197], v[74:77]
	v_mfma_f32_16x16x32_bf16 v[78:81], v[106:109], v[190:193], v[78:81]
	v_mfma_f32_16x16x32_bf16 v[78:81], v[118:121], v[194:197], v[78:81]
	s_setprio 0
	s_barrier
	s_mov_b32 m0, s48
	s_or_b32 s78, s77, 0x80
	buffer_load_dwordx4 v223, s[16:19], s78 offen lds
	ds_read_b128 v[162:165], v226 offset:49152
	ds_read_b128 v[166:169], v226 offset:50176
	ds_read_b128 v[170:173], v226 offset:51200
	ds_read_b128 v[174:177], v226 offset:52224
	ds_read_b128 v[178:181], v226 offset:53248
	ds_read_b128 v[182:185], v226 offset:54272
	ds_read_b128 v[190:193], v226 offset:55296
	ds_read_b128 v[194:197], v226 offset:56320
	s_add_i32 s78, s77, 0x80080
	s_mov_b32 m0, s49
	s_add_i32 s75, s75, 0x80080
	buffer_load_dwordx4 v223, s[16:19], s78 offen lds
	s_add_i32 s78, s77, 0x100080
	s_mov_b32 m0, s52
	s_add_i32 s77, s77, 0x180080
	buffer_load_dwordx4 v223, s[16:19], s78 offen lds
	s_mov_b32 m0, s53
	s_nop 0
	buffer_load_dwordx4 v223, s[16:19], s77 offen lds
	s_mov_b32 m0, s50
	s_nop 0
	buffer_load_dwordx4 v222, s[12:15], s76 offen lds
	s_mov_b32 m0, s51
	s_nop 0
	buffer_load_dwordx4 v222, s[12:15], s75 offen lds
	s_waitcnt vmcnt(8)
	s_waitcnt lgkmcnt(0)
	s_setprio 1
	v_mfma_f32_16x16x32_bf16 v[62:65], v[106:109], v[162:165], v[62:65]
	s_barrier
	v_mfma_f32_16x16x32_bf16 v[62:65], v[118:121], v[166:169], v[62:65]
	v_mfma_f32_16x16x32_bf16 v[58:61], v[130:133], v[162:165], v[58:61]
	v_mfma_f32_16x16x32_bf16 v[58:61], v[138:141], v[166:169], v[58:61]
	v_mfma_f32_16x16x32_bf16 v[54:57], v[146:149], v[162:165], v[54:57]
	v_mfma_f32_16x16x32_bf16 v[54:57], v[150:153], v[166:169], v[54:57]
	v_mfma_f32_16x16x32_bf16 v[50:53], v[154:157], v[162:165], v[50:53]
	v_mfma_f32_16x16x32_bf16 v[50:53], v[158:161], v[166:169], v[50:53]
	v_mfma_f32_16x16x32_bf16 v[34:37], v[154:157], v[170:173], v[34:37]
	v_mfma_f32_16x16x32_bf16 v[34:37], v[158:161], v[174:177], v[34:37]
	v_mfma_f32_16x16x32_bf16 v[38:41], v[146:149], v[170:173], v[38:41]
	v_mfma_f32_16x16x32_bf16 v[38:41], v[150:153], v[174:177], v[38:41]
	v_mfma_f32_16x16x32_bf16 v[42:45], v[130:133], v[170:173], v[42:45]
	v_mfma_f32_16x16x32_bf16 v[42:45], v[138:141], v[174:177], v[42:45]
	v_mfma_f32_16x16x32_bf16 v[46:49], v[106:109], v[170:173], v[46:49]
	v_mfma_f32_16x16x32_bf16 v[46:49], v[118:121], v[174:177], v[46:49]
	v_mfma_f32_16x16x32_bf16 v[30:33], v[106:109], v[178:181], v[30:33]
	v_mfma_f32_16x16x32_bf16 v[30:33], v[118:121], v[182:185], v[30:33]
	v_mfma_f32_16x16x32_bf16 v[26:29], v[130:133], v[178:181], v[26:29]
	v_mfma_f32_16x16x32_bf16 v[26:29], v[138:141], v[182:185], v[26:29]
	v_mfma_f32_16x16x32_bf16 v[22:25], v[146:149], v[178:181], v[22:25]
	v_mfma_f32_16x16x32_bf16 v[22:25], v[150:153], v[182:185], v[22:25]
	v_mfma_f32_16x16x32_bf16 v[18:21], v[154:157], v[178:181], v[18:21]
	v_mfma_f32_16x16x32_bf16 v[18:21], v[158:161], v[182:185], v[18:21]
	v_mfma_f32_16x16x32_bf16 v[2:5], v[154:157], v[190:193], v[2:5]
	v_mfma_f32_16x16x32_bf16 v[2:5], v[158:161], v[194:197], v[2:5]
	v_mfma_f32_16x16x32_bf16 v[6:9], v[146:149], v[190:193], v[6:9]
	v_mfma_f32_16x16x32_bf16 v[6:9], v[150:153], v[194:197], v[6:9]
	v_mfma_f32_16x16x32_bf16 v[10:13], v[130:133], v[190:193], v[10:13]
	v_mfma_f32_16x16x32_bf16 v[10:13], v[138:141], v[194:197], v[10:13]
	v_mfma_f32_16x16x32_bf16 v[14:17], v[106:109], v[190:193], v[14:17]
	v_mfma_f32_16x16x32_bf16 v[14:17], v[118:121], v[194:197], v[14:17]
	s_setprio 0
	s_barrier
	s_add_i32 s74, s74, 2
	s_addk_i32 s72, 0x100
	s_addk_i32 s73, 0x100
	s_cmp_ge_i32 s74, s3
	s_cbranch_scc0 .LBB0_1290
	s_and_b64 vcc, exec, s[38:39]
	s_cbranch_vccz .LBB0_1293

.LBB0_1382:
	ds_read_b128 v[144:147], v138
	ds_read_b128 v[148:151], v138 offset:1024
	ds_read_b128 v[152:155], v138 offset:2048
	ds_read_b128 v[156:159], v138 offset:3072
	ds_read_b128 v[160:163], v139
	ds_read_b128 v[164:167], v139 offset:1024
	ds_read_b128 v[168:171], v139 offset:2048
	ds_read_b128 v[172:175], v139 offset:3072
	s_add_i32 s14, s74, 0xffe80080
	s_cmp_eq_u32 s61, s76
	s_cselect_b32 s77, s72, s14
	s_cselect_b32 s79, s73, s75
	s_or_b32 s78, s77, 0x80
	s_add_i32 s14, s74, 0xfff80000
	s_mov_b32 m0, s62
	s_nop 0
	buffer_load_dwordx4 v136, s[16:19], s14 offen lds
	ds_read_b128 v[176:179], v140
	ds_read_b128 v[180:183], v140 offset:1024
	ds_read_b128 v[184:187], v140 offset:2048
	ds_read_b128 v[188:191], v140 offset:3072
	ds_read_b128 v[192:195], v140 offset:4096
	ds_read_b128 v[196:199], v140 offset:5120
	ds_read_b128 v[200:203], v140 offset:6144
	ds_read_b128 v[204:207], v140 offset:7168
	s_mov_b32 m0, s63
	s_nop 0
	buffer_load_dwordx4 v136, s[16:19], s74 offen lds
	s_waitcnt vmcnt(8)
	s_waitcnt lgkmcnt(0)
	s_setprio 1
	v_mfma_f32_16x16x32_bf16 v[118:121], v[144:147], v[176:179], v[118:121]
	s_barrier
	v_mfma_f32_16x16x32_bf16 v[118:121], v[148:151], v[180:183], v[118:121]
	v_mfma_f32_16x16x32_bf16 v[114:117], v[152:155], v[176:179], v[114:117]
	v_mfma_f32_16x16x32_bf16 v[114:117], v[156:159], v[180:183], v[114:117]
	v_mfma_f32_16x16x32_bf16 v[126:129], v[160:163], v[176:179], v[126:129]
	v_mfma_f32_16x16x32_bf16 v[126:129], v[164:167], v[180:183], v[126:129]
	v_mfma_f32_16x16x32_bf16 v[122:125], v[168:171], v[176:179], v[122:125]
	v_mfma_f32_16x16x32_bf16 v[122:125], v[172:175], v[180:183], v[122:125]
	v_mfma_f32_16x16x32_bf16 v[98:101], v[168:171], v[184:187], v[98:101]
	v_mfma_f32_16x16x32_bf16 v[98:101], v[172:175], v[188:191], v[98:101]
	v_mfma_f32_16x16x32_bf16 v[106:109], v[160:163], v[184:187], v[106:109]
	v_mfma_f32_16x16x32_bf16 v[106:109], v[164:167], v[188:191], v[106:109]
	v_mfma_f32_16x16x32_bf16 v[102:105], v[152:155], v[184:187], v[102:105]
	v_mfma_f32_16x16x32_bf16 v[102:105], v[156:159], v[188:191], v[102:105]
	v_mfma_f32_16x16x32_bf16 v[110:113], v[144:147], v[184:187], v[110:113]
	v_mfma_f32_16x16x32_bf16 v[110:113], v[148:151], v[188:191], v[110:113]
	v_mfma_f32_16x16x32_bf16 v[94:97], v[144:147], v[192:195], v[94:97]
	v_mfma_f32_16x16x32_bf16 v[94:97], v[148:151], v[196:199], v[94:97]
	v_mfma_f32_16x16x32_bf16 v[86:89], v[152:155], v[192:195], v[86:89]
	v_mfma_f32_16x16x32_bf16 v[86:89], v[156:159], v[196:199], v[86:89]
	v_mfma_f32_16x16x32_bf16 v[90:93], v[160:163], v[192:195], v[90:93]
	v_mfma_f32_16x16x32_bf16 v[90:93], v[164:167], v[196:199], v[90:93]
	v_mfma_f32_16x16x32_bf16 v[82:85], v[168:171], v[192:195], v[82:85]
	v_mfma_f32_16x16x32_bf16 v[82:85], v[172:175], v[196:199], v[82:85]
	v_mfma_f32_16x16x32_bf16 v[70:73], v[168:171], v[200:203], v[70:73]
	v_mfma_f32_16x16x32_bf16 v[70:73], v[172:175], v[204:207], v[70:73]
	v_mfma_f32_16x16x32_bf16 v[74:77], v[160:163], v[200:203], v[74:77]
	v_mfma_f32_16x16x32_bf16 v[74:77], v[164:167], v[204:207], v[74:77]
	v_mfma_f32_16x16x32_bf16 v[66:69], v[152:155], v[200:203], v[66:69]
	v_mfma_f32_16x16x32_bf16 v[66:69], v[156:159], v[204:207], v[66:69]
	v_mfma_f32_16x16x32_bf16 v[78:81], v[144:147], v[200:203], v[78:81]
	v_mfma_f32_16x16x32_bf16 v[78:81], v[148:151], v[204:207], v[78:81]
	s_setprio 0
	s_barrier
	s_mov_b32 m0, s45
	s_mov_b32 s14, s18
	s_mov_b32 s15, s19
	buffer_load_dwordx4 v137, s[12:15], s79 offen lds
	ds_read_b128 v[176:179], v140 offset:16384
	ds_read_b128 v[180:183], v140 offset:17408
	ds_read_b128 v[184:187], v140 offset:18432
	ds_read_b128 v[188:191], v140 offset:19456
	ds_read_b128 v[192:195], v140 offset:20480
	ds_read_b128 v[196:199], v140 offset:21504
	ds_read_b128 v[200:203], v140 offset:22528
	ds_read_b128 v[204:207], v140 offset:23552
	s_add_i32 s80, s79, 0x80000
	s_mov_b32 m0, s46
	s_nop 0
	buffer_load_dwordx4 v137, s[12:15], s80 offen lds
	s_add_i32 s80, s79, 0x100000
	s_mov_b32 m0, s47
	s_nop 0
	buffer_load_dwordx4 v137, s[12:15], s80 offen lds
	s_add_i32 s80, s79, 0x180000
	s_mov_b32 m0, s48
	s_nop 0
	buffer_load_dwordx4 v137, s[12:15], s80 offen lds
	s_mov_b32 m0, s44
	s_add_i32 s80, s77, 0x80000
	buffer_load_dwordx4 v136, s[16:19], s77 offen lds
	s_mov_b32 m0, s49
	s_nop 0
	buffer_load_dwordx4 v136, s[16:19], s80 offen lds
	s_waitcnt vmcnt(8)
	s_waitcnt lgkmcnt(0)
	s_setprio 1
	v_mfma_f32_16x16x32_bf16 v[62:65], v[144:147], v[176:179], v[62:65]
	s_barrier
	v_mfma_f32_16x16x32_bf16 v[62:65], v[148:151], v[180:183], v[62:65]
	v_mfma_f32_16x16x32_bf16 v[54:57], v[152:155], v[176:179], v[54:57]
	v_mfma_f32_16x16x32_bf16 v[54:57], v[156:159], v[180:183], v[54:57]
	v_mfma_f32_16x16x32_bf16 v[58:61], v[160:163], v[176:179], v[58:61]
	v_mfma_f32_16x16x32_bf16 v[58:61], v[164:167], v[180:183], v[58:61]
	v_mfma_f32_16x16x32_bf16 v[50:53], v[168:171], v[176:179], v[50:53]
	v_mfma_f32_16x16x32_bf16 v[50:53], v[172:175], v[180:183], v[50:53]
	v_mfma_f32_16x16x32_bf16 v[34:37], v[168:171], v[184:187], v[34:37]
	v_mfma_f32_16x16x32_bf16 v[34:37], v[172:175], v[188:191], v[34:37]
	v_mfma_f32_16x16x32_bf16 v[42:45], v[160:163], v[184:187], v[42:45]
	v_mfma_f32_16x16x32_bf16 v[42:45], v[164:167], v[188:191], v[42:45]
	v_mfma_f32_16x16x32_bf16 v[38:41], v[152:155], v[184:187], v[38:41]
	v_mfma_f32_16x16x32_bf16 v[38:41], v[156:159], v[188:191], v[38:41]
	v_mfma_f32_16x16x32_bf16 v[46:49], v[144:147], v[184:187], v[46:49]
	v_mfma_f32_16x16x32_bf16 v[46:49], v[148:151], v[188:191], v[46:49]
	v_mfma_f32_16x16x32_bf16 v[30:33], v[144:147], v[192:195], v[30:33]
	v_mfma_f32_16x16x32_bf16 v[30:33], v[148:151], v[196:199], v[30:33]
	v_mfma_f32_16x16x32_bf16 v[22:25], v[152:155], v[192:195], v[22:25]
	v_mfma_f32_16x16x32_bf16 v[22:25], v[156:159], v[196:199], v[22:25]
	v_mfma_f32_16x16x32_bf16 v[26:29], v[160:163], v[192:195], v[26:29]
	v_mfma_f32_16x16x32_bf16 v[26:29], v[164:167], v[196:199], v[26:29]
	v_mfma_f32_16x16x32_bf16 v[18:21], v[168:171], v[192:195], v[18:21]
	v_mfma_f32_16x16x32_bf16 v[18:21], v[172:175], v[196:199], v[18:21]
	v_mfma_f32_16x16x32_bf16 v[2:5], v[168:171], v[200:203], v[2:5]
	v_mfma_f32_16x16x32_bf16 v[2:5], v[172:175], v[204:207], v[2:5]
	v_mfma_f32_16x16x32_bf16 v[10:13], v[160:163], v[200:203], v[10:13]
	v_mfma_f32_16x16x32_bf16 v[10:13], v[164:167], v[204:207], v[10:13]
	v_mfma_f32_16x16x32_bf16 v[6:9], v[152:155], v[200:203], v[6:9]
	v_mfma_f32_16x16x32_bf16 v[6:9], v[156:159], v[204:207], v[6:9]
	v_mfma_f32_16x16x32_bf16 v[14:17], v[144:147], v[200:203], v[14:17]
	v_mfma_f32_16x16x32_bf16 v[14:17], v[148:151], v[204:207], v[14:17]
	s_setprio 0
	s_barrier
	ds_read_b128 v[144:147], v141
	ds_read_b128 v[148:151], v141 offset:1024
	ds_read_b128 v[152:155], v141 offset:2048
	ds_read_b128 v[156:159], v141 offset:3072
	ds_read_b128 v[160:163], v142
	ds_read_b128 v[164:167], v142 offset:1024
	ds_read_b128 v[168:171], v142 offset:2048
	ds_read_b128 v[172:175], v142 offset:3072
	s_mov_b32 m0, s50
	s_add_i32 s80, s77, 0x100000
	buffer_load_dwordx4 v136, s[16:19], s80 offen lds
	ds_read_b128 v[176:179], v140 offset:32768
	ds_read_b128 v[180:183], v140 offset:33792
	ds_read_b128 v[184:187], v140 offset:34816
	ds_read_b128 v[188:191], v140 offset:35840
	ds_read_b128 v[192:195], v140 offset:36864
	ds_read_b128 v[196:199], v140 offset:37888
	ds_read_b128 v[200:203], v140 offset:38912
	ds_read_b128 v[204:207], v140 offset:39936
	s_add_i32 s80, s77, 0x180000
	s_mov_b32 m0, s51
	s_nop 0
	buffer_load_dwordx4 v136, s[16:19], s80 offen lds
	s_waitcnt vmcnt(8)
	s_waitcnt lgkmcnt(0)
	s_setprio 1
	v_mfma_f32_16x16x32_bf16 v[118:121], v[144:147], v[176:179], v[118:121]
	s_barrier
	v_mfma_f32_16x16x32_bf16 v[118:121], v[148:151], v[180:183], v[118:121]
	v_mfma_f32_16x16x32_bf16 v[114:117], v[152:155], v[176:179], v[114:117]
	v_mfma_f32_16x16x32_bf16 v[114:117], v[156:159], v[180:183], v[114:117]
	v_mfma_f32_16x16x32_bf16 v[126:129], v[160:163], v[176:179], v[126:129]
	v_mfma_f32_16x16x32_bf16 v[126:129], v[164:167], v[180:183], v[126:129]
	v_mfma_f32_16x16x32_bf16 v[122:125], v[168:171], v[176:179], v[122:125]
	v_mfma_f32_16x16x32_bf16 v[122:125], v[172:175], v[180:183], v[122:125]
	v_mfma_f32_16x16x32_bf16 v[98:101], v[168:171], v[184:187], v[98:101]
	v_mfma_f32_16x16x32_bf16 v[98:101], v[172:175], v[188:191], v[98:101]
	v_mfma_f32_16x16x32_bf16 v[106:109], v[160:163], v[184:187], v[106:109]
	v_mfma_f32_16x16x32_bf16 v[106:109], v[164:167], v[188:191], v[106:109]
	v_mfma_f32_16x16x32_bf16 v[102:105], v[152:155], v[184:187], v[102:105]
	v_mfma_f32_16x16x32_bf16 v[102:105], v[156:159], v[188:191], v[102:105]
	v_mfma_f32_16x16x32_bf16 v[110:113], v[144:147], v[184:187], v[110:113]
	v_mfma_f32_16x16x32_bf16 v[110:113], v[148:151], v[188:191], v[110:113]
	v_mfma_f32_16x16x32_bf16 v[94:97], v[144:147], v[192:195], v[94:97]
	v_mfma_f32_16x16x32_bf16 v[94:97], v[148:151], v[196:199], v[94:97]
	v_mfma_f32_16x16x32_bf16 v[86:89], v[152:155], v[192:195], v[86:89]
	v_mfma_f32_16x16x32_bf16 v[86:89], v[156:159], v[196:199], v[86:89]
	v_mfma_f32_16x16x32_bf16 v[90:93], v[160:163], v[192:195], v[90:93]
	v_mfma_f32_16x16x32_bf16 v[90:93], v[164:167], v[196:199], v[90:93]
	v_mfma_f32_16x16x32_bf16 v[82:85], v[168:171], v[192:195], v[82:85]
	v_mfma_f32_16x16x32_bf16 v[82:85], v[172:175], v[196:199], v[82:85]
	v_mfma_f32_16x16x32_bf16 v[70:73], v[168:171], v[200:203], v[70:73]
	v_mfma_f32_16x16x32_bf16 v[70:73], v[172:175], v[204:207], v[70:73]
	v_mfma_f32_16x16x32_bf16 v[74:77], v[160:163], v[200:203], v[74:77]
	v_mfma_f32_16x16x32_bf16 v[74:77], v[164:167], v[204:207], v[74:77]
	v_mfma_f32_16x16x32_bf16 v[66:69], v[152:155], v[200:203], v[66:69]
	v_mfma_f32_16x16x32_bf16 v[66:69], v[156:159], v[204:207], v[66:69]
	v_mfma_f32_16x16x32_bf16 v[78:81], v[144:147], v[200:203], v[78:81]
	v_mfma_f32_16x16x32_bf16 v[78:81], v[148:151], v[204:207], v[78:81]
	s_setprio 0
	s_barrier
	s_mov_b32 m0, s53
	s_or_b32 s80, s79, 0x80
	buffer_load_dwordx4 v137, s[12:15], s80 offen lds
	ds_read_b128 v[176:179], v140 offset:49152
	ds_read_b128 v[180:183], v140 offset:50176
	ds_read_b128 v[184:187], v140 offset:51200
	ds_read_b128 v[188:191], v140 offset:52224
	ds_read_b128 v[192:195], v140 offset:53248
	ds_read_b128 v[196:199], v140 offset:54272
	ds_read_b128 v[200:203], v140 offset:55296
	ds_read_b128 v[204:207], v140 offset:56320
	s_add_i32 s80, s79, 0x80080
	s_mov_b32 m0, s54
	s_add_i32 s77, s77, 0x80080
	buffer_load_dwordx4 v137, s[12:15], s80 offen lds
	s_add_i32 s80, s79, 0x100080
	s_mov_b32 m0, s57
	s_add_i32 s79, s79, 0x180080
	buffer_load_dwordx4 v137, s[12:15], s80 offen lds
	s_mov_b32 m0, s58
	s_nop 0
	buffer_load_dwordx4 v137, s[12:15], s79 offen lds
	s_mov_b32 m0, s55
	s_nop 0
	buffer_load_dwordx4 v136, s[16:19], s78 offen lds
	s_mov_b32 m0, s56
	s_nop 0
	buffer_load_dwordx4 v136, s[16:19], s77 offen lds
	s_waitcnt vmcnt(8)
	s_waitcnt lgkmcnt(0)
	s_setprio 1
	v_mfma_f32_16x16x32_bf16 v[62:65], v[144:147], v[176:179], v[62:65]
	s_barrier
	v_mfma_f32_16x16x32_bf16 v[62:65], v[148:151], v[180:183], v[62:65]
	v_mfma_f32_16x16x32_bf16 v[54:57], v[152:155], v[176:179], v[54:57]
	v_mfma_f32_16x16x32_bf16 v[54:57], v[156:159], v[180:183], v[54:57]
	v_mfma_f32_16x16x32_bf16 v[58:61], v[160:163], v[176:179], v[58:61]
	v_mfma_f32_16x16x32_bf16 v[58:61], v[164:167], v[180:183], v[58:61]
	v_mfma_f32_16x16x32_bf16 v[50:53], v[168:171], v[176:179], v[50:53]
	v_mfma_f32_16x16x32_bf16 v[50:53], v[172:175], v[180:183], v[50:53]
	v_mfma_f32_16x16x32_bf16 v[34:37], v[168:171], v[184:187], v[34:37]
	v_mfma_f32_16x16x32_bf16 v[34:37], v[172:175], v[188:191], v[34:37]
	v_mfma_f32_16x16x32_bf16 v[42:45], v[160:163], v[184:187], v[42:45]
	v_mfma_f32_16x16x32_bf16 v[42:45], v[164:167], v[188:191], v[42:45]
	v_mfma_f32_16x16x32_bf16 v[38:41], v[152:155], v[184:187], v[38:41]
	v_mfma_f32_16x16x32_bf16 v[38:41], v[156:159], v[188:191], v[38:41]
	v_mfma_f32_16x16x32_bf16 v[46:49], v[144:147], v[184:187], v[46:49]
	v_mfma_f32_16x16x32_bf16 v[46:49], v[148:151], v[188:191], v[46:49]
	v_mfma_f32_16x16x32_bf16 v[30:33], v[144:147], v[192:195], v[30:33]
	v_mfma_f32_16x16x32_bf16 v[30:33], v[148:151], v[196:199], v[30:33]
	v_mfma_f32_16x16x32_bf16 v[22:25], v[152:155], v[192:195], v[22:25]
	v_mfma_f32_16x16x32_bf16 v[22:25], v[156:159], v[196:199], v[22:25]
	v_mfma_f32_16x16x32_bf16 v[26:29], v[160:163], v[192:195], v[26:29]
	v_mfma_f32_16x16x32_bf16 v[26:29], v[164:167], v[196:199], v[26:29]
	v_mfma_f32_16x16x32_bf16 v[18:21], v[168:171], v[192:195], v[18:21]
	v_mfma_f32_16x16x32_bf16 v[18:21], v[172:175], v[196:199], v[18:21]
	v_mfma_f32_16x16x32_bf16 v[2:5], v[168:171], v[200:203], v[2:5]
	v_mfma_f32_16x16x32_bf16 v[2:5], v[172:175], v[204:207], v[2:5]
	v_mfma_f32_16x16x32_bf16 v[10:13], v[160:163], v[200:203], v[10:13]
	v_mfma_f32_16x16x32_bf16 v[10:13], v[164:167], v[204:207], v[10:13]
	v_mfma_f32_16x16x32_bf16 v[6:9], v[152:155], v[200:203], v[6:9]
	v_mfma_f32_16x16x32_bf16 v[6:9], v[156:159], v[204:207], v[6:9]
	v_mfma_f32_16x16x32_bf16 v[14:17], v[144:147], v[200:203], v[14:17]
	v_mfma_f32_16x16x32_bf16 v[14:17], v[148:151], v[204:207], v[14:17]
	s_setprio 0
	s_barrier
	s_add_i32 s76, s76, 2
	s_addk_i32 s74, 0x100
	s_addk_i32 s75, 0x100
	s_cmp_ge_i32 s76, s27
	s_cbranch_scc0 .LBB0_1382
	s_and_b64 vcc, exec, s[42:43]
	s_cbranch_vccz .LBB0_1385

.LBB0_1402:
	ds_read_b128 v[146:149], v138
	ds_read_b128 v[150:153], v138 offset:1024
	ds_read_b128 v[154:157], v138 offset:2048
	ds_read_b128 v[158:161], v138 offset:3072
	ds_read_b128 v[162:165], v139
	ds_read_b128 v[166:169], v139 offset:1024
	ds_read_b128 v[170:173], v139 offset:2048
	ds_read_b128 v[174:177], v139 offset:3072
	s_add_i32 s22, s75, 0xffe80080
	s_cmp_eq_u32 s62, s77
	s_cselect_b32 s78, s73, s22
	s_cselect_b32 s80, s74, s76
	s_or_b32 s79, s78, 0x80
	s_add_i32 s22, s75, 0xfff80000
	s_mov_b32 m0, s63
	s_nop 0
	buffer_load_dwordx4 v136, s[16:19], s22 offen lds
	ds_read_b128 v[178:181], v140
	ds_read_b128 v[182:185], v140 offset:1024
	ds_read_b128 v[186:189], v140 offset:2048
	ds_read_b128 v[190:193], v140 offset:3072
	ds_read_b128 v[194:197], v140 offset:4096
	ds_read_b128 v[198:201], v140 offset:5120
	ds_read_b128 v[202:205], v140 offset:6144
	ds_read_b128 v[206:209], v140 offset:7168
	s_mov_b32 m0, s64
	s_nop 0
	buffer_load_dwordx4 v136, s[16:19], s75 offen lds
	s_waitcnt vmcnt(8)
	s_waitcnt lgkmcnt(0)
	s_setprio 1
	v_mfma_f32_16x16x32_bf16 v[118:121], v[146:149], v[178:181], v[118:121]
	s_barrier
	v_mfma_f32_16x16x32_bf16 v[118:121], v[150:153], v[182:185], v[118:121]
	v_mfma_f32_16x16x32_bf16 v[114:117], v[154:157], v[178:181], v[114:117]
	v_mfma_f32_16x16x32_bf16 v[114:117], v[158:161], v[182:185], v[114:117]
	v_mfma_f32_16x16x32_bf16 v[126:129], v[162:165], v[178:181], v[126:129]
	v_mfma_f32_16x16x32_bf16 v[126:129], v[166:169], v[182:185], v[126:129]
	v_mfma_f32_16x16x32_bf16 v[122:125], v[170:173], v[178:181], v[122:125]
	v_mfma_f32_16x16x32_bf16 v[122:125], v[174:177], v[182:185], v[122:125]
	v_mfma_f32_16x16x32_bf16 v[98:101], v[170:173], v[186:189], v[98:101]
	v_mfma_f32_16x16x32_bf16 v[98:101], v[174:177], v[190:193], v[98:101]
	v_mfma_f32_16x16x32_bf16 v[106:109], v[162:165], v[186:189], v[106:109]
	v_mfma_f32_16x16x32_bf16 v[106:109], v[166:169], v[190:193], v[106:109]
	v_mfma_f32_16x16x32_bf16 v[102:105], v[154:157], v[186:189], v[102:105]
	v_mfma_f32_16x16x32_bf16 v[102:105], v[158:161], v[190:193], v[102:105]
	v_mfma_f32_16x16x32_bf16 v[110:113], v[146:149], v[186:189], v[110:113]
	v_mfma_f32_16x16x32_bf16 v[110:113], v[150:153], v[190:193], v[110:113]
	v_mfma_f32_16x16x32_bf16 v[94:97], v[146:149], v[194:197], v[94:97]
	v_mfma_f32_16x16x32_bf16 v[94:97], v[150:153], v[198:201], v[94:97]
	v_mfma_f32_16x16x32_bf16 v[86:89], v[154:157], v[194:197], v[86:89]
	v_mfma_f32_16x16x32_bf16 v[86:89], v[158:161], v[198:201], v[86:89]
	v_mfma_f32_16x16x32_bf16 v[90:93], v[162:165], v[194:197], v[90:93]
	v_mfma_f32_16x16x32_bf16 v[90:93], v[166:169], v[198:201], v[90:93]
	v_mfma_f32_16x16x32_bf16 v[82:85], v[170:173], v[194:197], v[82:85]
	v_mfma_f32_16x16x32_bf16 v[82:85], v[174:177], v[198:201], v[82:85]
	v_mfma_f32_16x16x32_bf16 v[70:73], v[170:173], v[202:205], v[70:73]
	v_mfma_f32_16x16x32_bf16 v[70:73], v[174:177], v[206:209], v[70:73]
	v_mfma_f32_16x16x32_bf16 v[74:77], v[162:165], v[202:205], v[74:77]
	v_mfma_f32_16x16x32_bf16 v[74:77], v[166:169], v[206:209], v[74:77]
	v_mfma_f32_16x16x32_bf16 v[66:69], v[154:157], v[202:205], v[66:69]
	v_mfma_f32_16x16x32_bf16 v[66:69], v[158:161], v[206:209], v[66:69]
	v_mfma_f32_16x16x32_bf16 v[78:81], v[146:149], v[202:205], v[78:81]
	v_mfma_f32_16x16x32_bf16 v[78:81], v[150:153], v[206:209], v[78:81]
	s_setprio 0
	s_barrier
	s_mov_b32 m0, s31
	s_mov_b32 s22, s18
	s_mov_b32 s23, s19
	buffer_load_dwordx4 v137, s[20:23], s80 offen lds
	ds_read_b128 v[178:181], v140 offset:16384
	ds_read_b128 v[182:185], v140 offset:17408
	ds_read_b128 v[186:189], v140 offset:18432
	ds_read_b128 v[190:193], v140 offset:19456
	ds_read_b128 v[194:197], v140 offset:20480
	ds_read_b128 v[198:201], v140 offset:21504
	ds_read_b128 v[202:205], v140 offset:22528
	ds_read_b128 v[206:209], v140 offset:23552
	s_add_i32 s81, s80, 0x80000
	s_mov_b32 m0, s48
	s_nop 0
	buffer_load_dwordx4 v137, s[20:23], s81 offen lds
	s_add_i32 s81, s80, 0x100000
	s_mov_b32 m0, s49
	s_nop 0
	buffer_load_dwordx4 v137, s[20:23], s81 offen lds
	s_add_i32 s81, s80, 0x180000
	s_mov_b32 m0, s50
	s_nop 0
	buffer_load_dwordx4 v137, s[20:23], s81 offen lds
	s_mov_b32 m0, s30
	s_add_i32 s81, s78, 0x80000
	buffer_load_dwordx4 v136, s[16:19], s78 offen lds
	s_mov_b32 m0, s51
	s_nop 0
	buffer_load_dwordx4 v136, s[16:19], s81 offen lds
	s_waitcnt vmcnt(8)
	s_waitcnt lgkmcnt(0)
	s_setprio 1
	v_mfma_f32_16x16x32_bf16 v[62:65], v[146:149], v[178:181], v[62:65]
	s_barrier
	v_mfma_f32_16x16x32_bf16 v[62:65], v[150:153], v[182:185], v[62:65]
	v_mfma_f32_16x16x32_bf16 v[54:57], v[154:157], v[178:181], v[54:57]
	v_mfma_f32_16x16x32_bf16 v[54:57], v[158:161], v[182:185], v[54:57]
	v_mfma_f32_16x16x32_bf16 v[58:61], v[162:165], v[178:181], v[58:61]
	v_mfma_f32_16x16x32_bf16 v[58:61], v[166:169], v[182:185], v[58:61]
	v_mfma_f32_16x16x32_bf16 v[50:53], v[170:173], v[178:181], v[50:53]
	v_mfma_f32_16x16x32_bf16 v[50:53], v[174:177], v[182:185], v[50:53]
	v_mfma_f32_16x16x32_bf16 v[34:37], v[170:173], v[186:189], v[34:37]
	v_mfma_f32_16x16x32_bf16 v[34:37], v[174:177], v[190:193], v[34:37]
	v_mfma_f32_16x16x32_bf16 v[42:45], v[162:165], v[186:189], v[42:45]
	v_mfma_f32_16x16x32_bf16 v[42:45], v[166:169], v[190:193], v[42:45]
	v_mfma_f32_16x16x32_bf16 v[38:41], v[154:157], v[186:189], v[38:41]
	v_mfma_f32_16x16x32_bf16 v[38:41], v[158:161], v[190:193], v[38:41]
	v_mfma_f32_16x16x32_bf16 v[46:49], v[146:149], v[186:189], v[46:49]
	v_mfma_f32_16x16x32_bf16 v[46:49], v[150:153], v[190:193], v[46:49]
	v_mfma_f32_16x16x32_bf16 v[30:33], v[146:149], v[194:197], v[30:33]
	v_mfma_f32_16x16x32_bf16 v[30:33], v[150:153], v[198:201], v[30:33]
	v_mfma_f32_16x16x32_bf16 v[22:25], v[154:157], v[194:197], v[22:25]
	v_mfma_f32_16x16x32_bf16 v[22:25], v[158:161], v[198:201], v[22:25]
	v_mfma_f32_16x16x32_bf16 v[26:29], v[162:165], v[194:197], v[26:29]
	v_mfma_f32_16x16x32_bf16 v[26:29], v[166:169], v[198:201], v[26:29]
	v_mfma_f32_16x16x32_bf16 v[18:21], v[170:173], v[194:197], v[18:21]
	v_mfma_f32_16x16x32_bf16 v[18:21], v[174:177], v[198:201], v[18:21]
	v_mfma_f32_16x16x32_bf16 v[2:5], v[170:173], v[202:205], v[2:5]
	v_mfma_f32_16x16x32_bf16 v[2:5], v[174:177], v[206:209], v[2:5]
	v_mfma_f32_16x16x32_bf16 v[10:13], v[162:165], v[202:205], v[10:13]
	v_mfma_f32_16x16x32_bf16 v[10:13], v[166:169], v[206:209], v[10:13]
	v_mfma_f32_16x16x32_bf16 v[6:9], v[154:157], v[202:205], v[6:9]
	v_mfma_f32_16x16x32_bf16 v[6:9], v[158:161], v[206:209], v[6:9]
	v_mfma_f32_16x16x32_bf16 v[14:17], v[146:149], v[202:205], v[14:17]
	v_mfma_f32_16x16x32_bf16 v[14:17], v[150:153], v[206:209], v[14:17]
	s_setprio 0
	s_barrier
	ds_read_b128 v[146:149], v141
	ds_read_b128 v[150:153], v141 offset:1024
	ds_read_b128 v[154:157], v141 offset:2048
	ds_read_b128 v[158:161], v141 offset:3072
	ds_read_b128 v[162:165], v142
	ds_read_b128 v[166:169], v142 offset:1024
	ds_read_b128 v[170:173], v142 offset:2048
	ds_read_b128 v[174:177], v142 offset:3072
	s_mov_b32 m0, s52
	s_add_i32 s81, s78, 0x100000
	buffer_load_dwordx4 v136, s[16:19], s81 offen lds
	ds_read_b128 v[178:181], v140 offset:32768
	ds_read_b128 v[182:185], v140 offset:33792
	ds_read_b128 v[186:189], v140 offset:34816
	ds_read_b128 v[190:193], v140 offset:35840
	ds_read_b128 v[194:197], v140 offset:36864
	ds_read_b128 v[198:201], v140 offset:37888
	ds_read_b128 v[202:205], v140 offset:38912
	ds_read_b128 v[206:209], v140 offset:39936
	s_add_i32 s81, s78, 0x180000
	s_mov_b32 m0, s53
	s_nop 0
	buffer_load_dwordx4 v136, s[16:19], s81 offen lds
	s_waitcnt vmcnt(8)
	s_waitcnt lgkmcnt(0)
	s_setprio 1
	v_mfma_f32_16x16x32_bf16 v[118:121], v[146:149], v[178:181], v[118:121]
	s_barrier
	v_mfma_f32_16x16x32_bf16 v[118:121], v[150:153], v[182:185], v[118:121]
	v_mfma_f32_16x16x32_bf16 v[114:117], v[154:157], v[178:181], v[114:117]
	v_mfma_f32_16x16x32_bf16 v[114:117], v[158:161], v[182:185], v[114:117]
	v_mfma_f32_16x16x32_bf16 v[126:129], v[162:165], v[178:181], v[126:129]
	v_mfma_f32_16x16x32_bf16 v[126:129], v[166:169], v[182:185], v[126:129]
	v_mfma_f32_16x16x32_bf16 v[122:125], v[170:173], v[178:181], v[122:125]
	v_mfma_f32_16x16x32_bf16 v[122:125], v[174:177], v[182:185], v[122:125]
	v_mfma_f32_16x16x32_bf16 v[98:101], v[170:173], v[186:189], v[98:101]
	v_mfma_f32_16x16x32_bf16 v[98:101], v[174:177], v[190:193], v[98:101]
	v_mfma_f32_16x16x32_bf16 v[106:109], v[162:165], v[186:189], v[106:109]
	v_mfma_f32_16x16x32_bf16 v[106:109], v[166:169], v[190:193], v[106:109]
	v_mfma_f32_16x16x32_bf16 v[102:105], v[154:157], v[186:189], v[102:105]
	v_mfma_f32_16x16x32_bf16 v[102:105], v[158:161], v[190:193], v[102:105]
	v_mfma_f32_16x16x32_bf16 v[110:113], v[146:149], v[186:189], v[110:113]
	v_mfma_f32_16x16x32_bf16 v[110:113], v[150:153], v[190:193], v[110:113]
	v_mfma_f32_16x16x32_bf16 v[94:97], v[146:149], v[194:197], v[94:97]
	v_mfma_f32_16x16x32_bf16 v[94:97], v[150:153], v[198:201], v[94:97]
	v_mfma_f32_16x16x32_bf16 v[86:89], v[154:157], v[194:197], v[86:89]
	v_mfma_f32_16x16x32_bf16 v[86:89], v[158:161], v[198:201], v[86:89]
	v_mfma_f32_16x16x32_bf16 v[90:93], v[162:165], v[194:197], v[90:93]
	v_mfma_f32_16x16x32_bf16 v[90:93], v[166:169], v[198:201], v[90:93]
	v_mfma_f32_16x16x32_bf16 v[82:85], v[170:173], v[194:197], v[82:85]
	v_mfma_f32_16x16x32_bf16 v[82:85], v[174:177], v[198:201], v[82:85]
	v_mfma_f32_16x16x32_bf16 v[70:73], v[170:173], v[202:205], v[70:73]
	v_mfma_f32_16x16x32_bf16 v[70:73], v[174:177], v[206:209], v[70:73]
	v_mfma_f32_16x16x32_bf16 v[74:77], v[162:165], v[202:205], v[74:77]
	v_mfma_f32_16x16x32_bf16 v[74:77], v[166:169], v[206:209], v[74:77]
	v_mfma_f32_16x16x32_bf16 v[66:69], v[154:157], v[202:205], v[66:69]
	v_mfma_f32_16x16x32_bf16 v[66:69], v[158:161], v[206:209], v[66:69]
	v_mfma_f32_16x16x32_bf16 v[78:81], v[146:149], v[202:205], v[78:81]
	v_mfma_f32_16x16x32_bf16 v[78:81], v[150:153], v[206:209], v[78:81]
	s_setprio 0
	s_barrier
	s_mov_b32 m0, s54
	s_or_b32 s81, s80, 0x80
	buffer_load_dwordx4 v137, s[20:23], s81 offen lds
	ds_read_b128 v[178:181], v140 offset:49152
	ds_read_b128 v[182:185], v140 offset:50176
	ds_read_b128 v[186:189], v140 offset:51200
	ds_read_b128 v[190:193], v140 offset:52224
	ds_read_b128 v[194:197], v140 offset:53248
	ds_read_b128 v[198:201], v140 offset:54272
	ds_read_b128 v[202:205], v140 offset:55296
	ds_read_b128 v[206:209], v140 offset:56320
	s_add_i32 s81, s80, 0x80080
	s_mov_b32 m0, s55
	s_add_i32 s78, s78, 0x80080
	buffer_load_dwordx4 v137, s[20:23], s81 offen lds
	s_add_i32 s81, s80, 0x100080
	s_mov_b32 m0, s58
	s_add_i32 s80, s80, 0x180080
	buffer_load_dwordx4 v137, s[20:23], s81 offen lds
	s_mov_b32 m0, s59
	s_nop 0
	buffer_load_dwordx4 v137, s[20:23], s80 offen lds
	s_mov_b32 m0, s56
	s_nop 0
	buffer_load_dwordx4 v136, s[16:19], s79 offen lds
	s_mov_b32 m0, s57
	s_nop 0
	buffer_load_dwordx4 v136, s[16:19], s78 offen lds
	s_waitcnt vmcnt(8)
	s_waitcnt lgkmcnt(0)
	s_setprio 1
	v_mfma_f32_16x16x32_bf16 v[62:65], v[146:149], v[178:181], v[62:65]
	s_barrier
	v_mfma_f32_16x16x32_bf16 v[62:65], v[150:153], v[182:185], v[62:65]
	v_mfma_f32_16x16x32_bf16 v[54:57], v[154:157], v[178:181], v[54:57]
	v_mfma_f32_16x16x32_bf16 v[54:57], v[158:161], v[182:185], v[54:57]
	v_mfma_f32_16x16x32_bf16 v[58:61], v[162:165], v[178:181], v[58:61]
	v_mfma_f32_16x16x32_bf16 v[58:61], v[166:169], v[182:185], v[58:61]
	v_mfma_f32_16x16x32_bf16 v[50:53], v[170:173], v[178:181], v[50:53]
	v_mfma_f32_16x16x32_bf16 v[50:53], v[174:177], v[182:185], v[50:53]
	v_mfma_f32_16x16x32_bf16 v[34:37], v[170:173], v[186:189], v[34:37]
	v_mfma_f32_16x16x32_bf16 v[34:37], v[174:177], v[190:193], v[34:37]
	v_mfma_f32_16x16x32_bf16 v[42:45], v[162:165], v[186:189], v[42:45]
	v_mfma_f32_16x16x32_bf16 v[42:45], v[166:169], v[190:193], v[42:45]
	v_mfma_f32_16x16x32_bf16 v[38:41], v[154:157], v[186:189], v[38:41]
	v_mfma_f32_16x16x32_bf16 v[38:41], v[158:161], v[190:193], v[38:41]
	v_mfma_f32_16x16x32_bf16 v[46:49], v[146:149], v[186:189], v[46:49]
	v_mfma_f32_16x16x32_bf16 v[46:49], v[150:153], v[190:193], v[46:49]
	v_mfma_f32_16x16x32_bf16 v[30:33], v[146:149], v[194:197], v[30:33]
	v_mfma_f32_16x16x32_bf16 v[30:33], v[150:153], v[198:201], v[30:33]
	v_mfma_f32_16x16x32_bf16 v[22:25], v[154:157], v[194:197], v[22:25]
	v_mfma_f32_16x16x32_bf16 v[22:25], v[158:161], v[198:201], v[22:25]
	v_mfma_f32_16x16x32_bf16 v[26:29], v[162:165], v[194:197], v[26:29]
	v_mfma_f32_16x16x32_bf16 v[26:29], v[166:169], v[198:201], v[26:29]
	v_mfma_f32_16x16x32_bf16 v[18:21], v[170:173], v[194:197], v[18:21]
	v_mfma_f32_16x16x32_bf16 v[18:21], v[174:177], v[198:201], v[18:21]
	v_mfma_f32_16x16x32_bf16 v[2:5], v[170:173], v[202:205], v[2:5]
	v_mfma_f32_16x16x32_bf16 v[2:5], v[174:177], v[206:209], v[2:5]
	v_mfma_f32_16x16x32_bf16 v[10:13], v[162:165], v[202:205], v[10:13]
	v_mfma_f32_16x16x32_bf16 v[10:13], v[166:169], v[206:209], v[10:13]
	v_mfma_f32_16x16x32_bf16 v[6:9], v[154:157], v[202:205], v[6:9]
	v_mfma_f32_16x16x32_bf16 v[6:9], v[158:161], v[206:209], v[6:9]
	v_mfma_f32_16x16x32_bf16 v[14:17], v[146:149], v[202:205], v[14:17]
	v_mfma_f32_16x16x32_bf16 v[14:17], v[150:153], v[206:209], v[14:17]
	s_setprio 0
	s_barrier
	s_add_i32 s77, s77, 2
	s_addk_i32 s75, 0x100
	s_addk_i32 s76, 0x100
	s_cmp_ge_i32 s77, s13
	s_cbranch_scc0 .LBB0_1402
	s_and_b64 vcc, exec, s[46:47]
	s_cbranch_vccz .LBB0_1405

.LBB0_1519:
	ds_read_b128 v[134:137], v208
	ds_read_b128 v[138:141], v208 offset:1024
	ds_read_b128 v[142:145], v208 offset:2048
	ds_read_b128 v[146:149], v208 offset:3072
	ds_read_b128 v[150:153], v209
	ds_read_b128 v[154:157], v209 offset:1024
	ds_read_b128 v[158:161], v209 offset:2048
	ds_read_b128 v[162:165], v209 offset:3072
	s_add_i32 s18, s80, 0xffbf8080
	s_cmp_eq_u32 s65, s82
	s_cselect_b32 s83, s6, s18
	s_cselect_b32 s85, s7, s81
	s_or_b32 s84, s83, 0x80
	s_add_i32 s18, s80, 0xffea8000
	s_mov_b32 m0, s66
	s_nop 0
	buffer_load_dwordx4 v206, s[12:15], s18 offen lds
	ds_read_b128 v[166:169], v210
	ds_read_b128 v[170:173], v210 offset:1024
	ds_read_b128 v[174:177], v210 offset:2048
	ds_read_b128 v[178:181], v210 offset:3072
	ds_read_b128 v[182:185], v210 offset:4096
	ds_read_b128 v[186:189], v210 offset:5120
	ds_read_b128 v[190:193], v210 offset:6144
	ds_read_b128 v[194:197], v210 offset:7168
	s_mov_b32 m0, s69
	s_nop 0
	buffer_load_dwordx4 v206, s[12:15], s80 offen lds
	s_waitcnt vmcnt(8)
	s_waitcnt lgkmcnt(0)
	s_setprio 1
	v_mfma_f32_16x16x32_bf16 v[126:129], v[134:137], v[166:169], v[126:129]
	s_barrier
	v_mfma_f32_16x16x32_bf16 v[126:129], v[138:141], v[170:173], v[126:129]
	v_mfma_f32_16x16x32_bf16 v[122:125], v[142:145], v[166:169], v[122:125]
	v_mfma_f32_16x16x32_bf16 v[122:125], v[146:149], v[170:173], v[122:125]
	v_mfma_f32_16x16x32_bf16 v[110:113], v[150:153], v[166:169], v[110:113]
	v_mfma_f32_16x16x32_bf16 v[110:113], v[154:157], v[170:173], v[110:113]
	v_mfma_f32_16x16x32_bf16 v[102:105], v[158:161], v[166:169], v[102:105]
	v_mfma_f32_16x16x32_bf16 v[102:105], v[162:165], v[170:173], v[102:105]
	v_mfma_f32_16x16x32_bf16 v[86:89], v[158:161], v[174:177], v[86:89]
	v_mfma_f32_16x16x32_bf16 v[86:89], v[162:165], v[178:181], v[86:89]
	v_mfma_f32_16x16x32_bf16 v[94:97], v[150:153], v[174:177], v[94:97]
	v_mfma_f32_16x16x32_bf16 v[94:97], v[154:157], v[178:181], v[94:97]
	v_mfma_f32_16x16x32_bf16 v[114:117], v[142:145], v[174:177], v[114:117]
	v_mfma_f32_16x16x32_bf16 v[114:117], v[146:149], v[178:181], v[114:117]
	v_mfma_f32_16x16x32_bf16 v[118:121], v[134:137], v[174:177], v[118:121]
	v_mfma_f32_16x16x32_bf16 v[118:121], v[138:141], v[178:181], v[118:121]
	v_mfma_f32_16x16x32_bf16 v[106:109], v[134:137], v[182:185], v[106:109]
	v_mfma_f32_16x16x32_bf16 v[106:109], v[138:141], v[186:189], v[106:109]
	v_mfma_f32_16x16x32_bf16 v[98:101], v[142:145], v[182:185], v[98:101]
	v_mfma_f32_16x16x32_bf16 v[98:101], v[146:149], v[186:189], v[98:101]
	v_mfma_f32_16x16x32_bf16 v[78:81], v[150:153], v[182:185], v[78:81]
	v_mfma_f32_16x16x32_bf16 v[78:81], v[154:157], v[186:189], v[78:81]
	v_mfma_f32_16x16x32_bf16 v[74:77], v[158:161], v[182:185], v[74:77]
	v_mfma_f32_16x16x32_bf16 v[74:77], v[162:165], v[186:189], v[74:77]
	v_mfma_f32_16x16x32_bf16 v[66:69], v[158:161], v[190:193], v[66:69]
	v_mfma_f32_16x16x32_bf16 v[66:69], v[162:165], v[194:197], v[66:69]
	v_mfma_f32_16x16x32_bf16 v[70:73], v[150:153], v[190:193], v[70:73]
	v_mfma_f32_16x16x32_bf16 v[70:73], v[154:157], v[194:197], v[70:73]
	v_mfma_f32_16x16x32_bf16 v[82:85], v[142:145], v[190:193], v[82:85]
	v_mfma_f32_16x16x32_bf16 v[82:85], v[146:149], v[194:197], v[82:85]
	v_mfma_f32_16x16x32_bf16 v[90:93], v[134:137], v[190:193], v[90:93]
	v_mfma_f32_16x16x32_bf16 v[90:93], v[138:141], v[194:197], v[90:93]
	s_setprio 0
	s_barrier
	s_mov_b32 m0, s27
	s_mov_b32 s18, s14
	s_mov_b32 s19, s15
	buffer_load_dwordx4 v207, s[16:19], s85 offen lds
	ds_read_b128 v[166:169], v210 offset:16384
	ds_read_b128 v[170:173], v210 offset:17408
	ds_read_b128 v[174:177], v210 offset:18432
	ds_read_b128 v[178:181], v210 offset:19456
	ds_read_b128 v[182:185], v210 offset:20480
	ds_read_b128 v[186:189], v210 offset:21504
	ds_read_b128 v[190:193], v210 offset:22528
	ds_read_b128 v[194:197], v210 offset:23552
	s_add_i32 s86, s85, 0x158000
	s_mov_b32 m0, s30
	s_nop 0
	buffer_load_dwordx4 v207, s[16:19], s86 offen lds
	s_add_i32 s86, s85, 0x2b0000
	s_mov_b32 m0, s31
	s_nop 0
	buffer_load_dwordx4 v207, s[16:19], s86 offen lds
	s_add_i32 s86, s85, 0x408000
	s_mov_b32 m0, s50
	s_nop 0
	buffer_load_dwordx4 v207, s[16:19], s86 offen lds
	s_mov_b32 m0, s25
	s_add_i32 s86, s83, 0x158000
	buffer_load_dwordx4 v206, s[12:15], s83 offen lds
	s_mov_b32 m0, s51
	s_nop 0
	buffer_load_dwordx4 v206, s[12:15], s86 offen lds
	s_waitcnt vmcnt(8)
	s_waitcnt lgkmcnt(0)
	s_setprio 1
	v_mfma_f32_16x16x32_bf16 v[62:65], v[134:137], v[166:169], v[62:65]
	s_barrier
	v_mfma_f32_16x16x32_bf16 v[62:65], v[138:141], v[170:173], v[62:65]
	v_mfma_f32_16x16x32_bf16 v[58:61], v[142:145], v[166:169], v[58:61]
	v_mfma_f32_16x16x32_bf16 v[58:61], v[146:149], v[170:173], v[58:61]
	v_mfma_f32_16x16x32_bf16 v[46:49], v[150:153], v[166:169], v[46:49]
	v_mfma_f32_16x16x32_bf16 v[46:49], v[154:157], v[170:173], v[46:49]
	v_mfma_f32_16x16x32_bf16 v[38:41], v[158:161], v[166:169], v[38:41]
	v_mfma_f32_16x16x32_bf16 v[38:41], v[162:165], v[170:173], v[38:41]
	v_mfma_f32_16x16x32_bf16 v[22:25], v[158:161], v[174:177], v[22:25]
	v_mfma_f32_16x16x32_bf16 v[22:25], v[162:165], v[178:181], v[22:25]
	v_mfma_f32_16x16x32_bf16 v[30:33], v[150:153], v[174:177], v[30:33]
	v_mfma_f32_16x16x32_bf16 v[30:33], v[154:157], v[178:181], v[30:33]
	v_mfma_f32_16x16x32_bf16 v[50:53], v[142:145], v[174:177], v[50:53]
	v_mfma_f32_16x16x32_bf16 v[50:53], v[146:149], v[178:181], v[50:53]
	v_mfma_f32_16x16x32_bf16 v[54:57], v[134:137], v[174:177], v[54:57]
	v_mfma_f32_16x16x32_bf16 v[54:57], v[138:141], v[178:181], v[54:57]
	v_mfma_f32_16x16x32_bf16 v[42:45], v[134:137], v[182:185], v[42:45]
	v_mfma_f32_16x16x32_bf16 v[42:45], v[138:141], v[186:189], v[42:45]
	v_mfma_f32_16x16x32_bf16 v[34:37], v[142:145], v[182:185], v[34:37]
	v_mfma_f32_16x16x32_bf16 v[34:37], v[146:149], v[186:189], v[34:37]
	v_mfma_f32_16x16x32_bf16 v[14:17], v[150:153], v[182:185], v[14:17]
	v_mfma_f32_16x16x32_bf16 v[14:17], v[154:157], v[186:189], v[14:17]
	v_mfma_f32_16x16x32_bf16 v[10:13], v[158:161], v[182:185], v[10:13]
	v_mfma_f32_16x16x32_bf16 v[10:13], v[162:165], v[186:189], v[10:13]
	v_mfma_f32_16x16x32_bf16 v[2:5], v[158:161], v[190:193], v[2:5]
	v_mfma_f32_16x16x32_bf16 v[2:5], v[162:165], v[194:197], v[2:5]
	v_mfma_f32_16x16x32_bf16 v[6:9], v[150:153], v[190:193], v[6:9]
	v_mfma_f32_16x16x32_bf16 v[6:9], v[154:157], v[194:197], v[6:9]
	v_mfma_f32_16x16x32_bf16 v[18:21], v[142:145], v[190:193], v[18:21]
	v_mfma_f32_16x16x32_bf16 v[18:21], v[146:149], v[194:197], v[18:21]
	v_mfma_f32_16x16x32_bf16 v[26:29], v[134:137], v[190:193], v[26:29]
	v_mfma_f32_16x16x32_bf16 v[26:29], v[138:141], v[194:197], v[26:29]
	s_setprio 0
	s_barrier
	ds_read_b128 v[134:137], v211
	ds_read_b128 v[138:141], v211 offset:1024
	ds_read_b128 v[142:145], v211 offset:2048
	ds_read_b128 v[146:149], v211 offset:3072
	ds_read_b128 v[150:153], v212
	ds_read_b128 v[154:157], v212 offset:1024
	ds_read_b128 v[158:161], v212 offset:2048
	ds_read_b128 v[162:165], v212 offset:3072
	s_mov_b32 m0, s52
	s_add_i32 s86, s83, 0x2b0000
	buffer_load_dwordx4 v206, s[12:15], s86 offen lds
	ds_read_b128 v[166:169], v210 offset:32768
	ds_read_b128 v[170:173], v210 offset:33792
	ds_read_b128 v[174:177], v210 offset:34816
	ds_read_b128 v[178:181], v210 offset:35840
	ds_read_b128 v[182:185], v210 offset:36864
	ds_read_b128 v[186:189], v210 offset:37888
	ds_read_b128 v[190:193], v210 offset:38912
	ds_read_b128 v[194:197], v210 offset:39936
	s_add_i32 s86, s83, 0x408000
	s_mov_b32 m0, s53
	s_nop 0
	buffer_load_dwordx4 v206, s[12:15], s86 offen lds
	s_waitcnt vmcnt(8)
	s_waitcnt lgkmcnt(0)
	s_setprio 1
	v_mfma_f32_16x16x32_bf16 v[126:129], v[134:137], v[166:169], v[126:129]
	s_barrier
	v_mfma_f32_16x16x32_bf16 v[126:129], v[138:141], v[170:173], v[126:129]
	v_mfma_f32_16x16x32_bf16 v[122:125], v[142:145], v[166:169], v[122:125]
	v_mfma_f32_16x16x32_bf16 v[122:125], v[146:149], v[170:173], v[122:125]
	v_mfma_f32_16x16x32_bf16 v[110:113], v[150:153], v[166:169], v[110:113]
	v_mfma_f32_16x16x32_bf16 v[110:113], v[154:157], v[170:173], v[110:113]
	v_mfma_f32_16x16x32_bf16 v[102:105], v[158:161], v[166:169], v[102:105]
	v_mfma_f32_16x16x32_bf16 v[102:105], v[162:165], v[170:173], v[102:105]
	v_mfma_f32_16x16x32_bf16 v[86:89], v[158:161], v[174:177], v[86:89]
	v_mfma_f32_16x16x32_bf16 v[86:89], v[162:165], v[178:181], v[86:89]
	v_mfma_f32_16x16x32_bf16 v[94:97], v[150:153], v[174:177], v[94:97]
	v_mfma_f32_16x16x32_bf16 v[94:97], v[154:157], v[178:181], v[94:97]
	v_mfma_f32_16x16x32_bf16 v[114:117], v[142:145], v[174:177], v[114:117]
	v_mfma_f32_16x16x32_bf16 v[114:117], v[146:149], v[178:181], v[114:117]
	v_mfma_f32_16x16x32_bf16 v[118:121], v[134:137], v[174:177], v[118:121]
	v_mfma_f32_16x16x32_bf16 v[118:121], v[138:141], v[178:181], v[118:121]
	v_mfma_f32_16x16x32_bf16 v[106:109], v[134:137], v[182:185], v[106:109]
	v_mfma_f32_16x16x32_bf16 v[106:109], v[138:141], v[186:189], v[106:109]
	v_mfma_f32_16x16x32_bf16 v[98:101], v[142:145], v[182:185], v[98:101]
	v_mfma_f32_16x16x32_bf16 v[98:101], v[146:149], v[186:189], v[98:101]
	v_mfma_f32_16x16x32_bf16 v[78:81], v[150:153], v[182:185], v[78:81]
	v_mfma_f32_16x16x32_bf16 v[78:81], v[154:157], v[186:189], v[78:81]
	v_mfma_f32_16x16x32_bf16 v[74:77], v[158:161], v[182:185], v[74:77]
	v_mfma_f32_16x16x32_bf16 v[74:77], v[162:165], v[186:189], v[74:77]
	v_mfma_f32_16x16x32_bf16 v[66:69], v[158:161], v[190:193], v[66:69]
	v_mfma_f32_16x16x32_bf16 v[66:69], v[162:165], v[194:197], v[66:69]
	v_mfma_f32_16x16x32_bf16 v[70:73], v[150:153], v[190:193], v[70:73]
	v_mfma_f32_16x16x32_bf16 v[70:73], v[154:157], v[194:197], v[70:73]
	v_mfma_f32_16x16x32_bf16 v[82:85], v[142:145], v[190:193], v[82:85]
	v_mfma_f32_16x16x32_bf16 v[82:85], v[146:149], v[194:197], v[82:85]
	v_mfma_f32_16x16x32_bf16 v[90:93], v[134:137], v[190:193], v[90:93]
	v_mfma_f32_16x16x32_bf16 v[90:93], v[138:141], v[194:197], v[90:93]
	s_setprio 0
	s_barrier
	s_mov_b32 m0, s57
	s_or_b32 s86, s85, 0x80
	buffer_load_dwordx4 v207, s[16:19], s86 offen lds
	ds_read_b128 v[166:169], v210 offset:49152
	ds_read_b128 v[170:173], v210 offset:50176
	ds_read_b128 v[174:177], v210 offset:51200
	ds_read_b128 v[178:181], v210 offset:52224
	ds_read_b128 v[182:185], v210 offset:53248
	ds_read_b128 v[186:189], v210 offset:54272
	ds_read_b128 v[190:193], v210 offset:55296
	ds_read_b128 v[194:197], v210 offset:56320
	s_add_i32 s86, s85, 0x158080
	s_mov_b32 m0, s58
	s_add_i32 s83, s83, 0x158080
	buffer_load_dwordx4 v207, s[16:19], s86 offen lds
	s_add_i32 s86, s85, 0x2b0080
	s_mov_b32 m0, s61
	s_add_i32 s85, s85, 0x408080
	buffer_load_dwordx4 v207, s[16:19], s86 offen lds
	s_mov_b32 m0, s62
	s_nop 0
	buffer_load_dwordx4 v207, s[16:19], s85 offen lds
	s_mov_b32 m0, s59
	s_nop 0
	buffer_load_dwordx4 v206, s[12:15], s84 offen lds
	s_mov_b32 m0, s60
	s_nop 0
	buffer_load_dwordx4 v206, s[12:15], s83 offen lds
	s_waitcnt vmcnt(8)
	s_waitcnt lgkmcnt(0)
	s_setprio 1
	v_mfma_f32_16x16x32_bf16 v[62:65], v[134:137], v[166:169], v[62:65]
	s_barrier
	v_mfma_f32_16x16x32_bf16 v[62:65], v[138:141], v[170:173], v[62:65]
	v_mfma_f32_16x16x32_bf16 v[58:61], v[142:145], v[166:169], v[58:61]
	v_mfma_f32_16x16x32_bf16 v[58:61], v[146:149], v[170:173], v[58:61]
	v_mfma_f32_16x16x32_bf16 v[46:49], v[150:153], v[166:169], v[46:49]
	v_mfma_f32_16x16x32_bf16 v[46:49], v[154:157], v[170:173], v[46:49]
	v_mfma_f32_16x16x32_bf16 v[38:41], v[158:161], v[166:169], v[38:41]
	v_mfma_f32_16x16x32_bf16 v[38:41], v[162:165], v[170:173], v[38:41]
	v_mfma_f32_16x16x32_bf16 v[22:25], v[158:161], v[174:177], v[22:25]
	v_mfma_f32_16x16x32_bf16 v[22:25], v[162:165], v[178:181], v[22:25]
	v_mfma_f32_16x16x32_bf16 v[30:33], v[150:153], v[174:177], v[30:33]
	v_mfma_f32_16x16x32_bf16 v[30:33], v[154:157], v[178:181], v[30:33]
	v_mfma_f32_16x16x32_bf16 v[50:53], v[142:145], v[174:177], v[50:53]
	v_mfma_f32_16x16x32_bf16 v[50:53], v[146:149], v[178:181], v[50:53]
	v_mfma_f32_16x16x32_bf16 v[54:57], v[134:137], v[174:177], v[54:57]
	v_mfma_f32_16x16x32_bf16 v[54:57], v[138:141], v[178:181], v[54:57]
	v_mfma_f32_16x16x32_bf16 v[42:45], v[134:137], v[182:185], v[42:45]
	v_mfma_f32_16x16x32_bf16 v[42:45], v[138:141], v[186:189], v[42:45]
	v_mfma_f32_16x16x32_bf16 v[34:37], v[142:145], v[182:185], v[34:37]
	v_mfma_f32_16x16x32_bf16 v[34:37], v[146:149], v[186:189], v[34:37]
	v_mfma_f32_16x16x32_bf16 v[14:17], v[150:153], v[182:185], v[14:17]
	v_mfma_f32_16x16x32_bf16 v[14:17], v[154:157], v[186:189], v[14:17]
	v_mfma_f32_16x16x32_bf16 v[10:13], v[158:161], v[182:185], v[10:13]
	v_mfma_f32_16x16x32_bf16 v[10:13], v[162:165], v[186:189], v[10:13]
	v_mfma_f32_16x16x32_bf16 v[2:5], v[158:161], v[190:193], v[2:5]
	v_mfma_f32_16x16x32_bf16 v[2:5], v[162:165], v[194:197], v[2:5]
	v_mfma_f32_16x16x32_bf16 v[6:9], v[150:153], v[190:193], v[6:9]
	v_mfma_f32_16x16x32_bf16 v[6:9], v[154:157], v[194:197], v[6:9]
	v_mfma_f32_16x16x32_bf16 v[18:21], v[142:145], v[190:193], v[18:21]
	v_mfma_f32_16x16x32_bf16 v[18:21], v[146:149], v[194:197], v[18:21]
	v_mfma_f32_16x16x32_bf16 v[26:29], v[134:137], v[190:193], v[26:29]
	v_mfma_f32_16x16x32_bf16 v[26:29], v[138:141], v[194:197], v[26:29]
	s_setprio 0
	s_barrier
	s_add_i32 s82, s82, 2
	s_addk_i32 s80, 0x100
	s_addk_i32 s81, 0x100
	s_cmp_ge_i32 s82, s3
	s_cbranch_scc0 .LBB0_1519
	v_pk_mul_f32 v[182:183], v[128:129], 0.5 op_sel_hi:[1,0]
	v_pk_mul_f32 v[184:185], v[126:127], 0.5 op_sel_hi:[1,0]
	v_pk_mul_f32 v[186:187], v[124:125], 0.5 op_sel_hi:[1,0]
	v_pk_mul_f32 v[188:189], v[122:123], 0.5 op_sel_hi:[1,0]
	v_pk_mul_f32 v[196:197], v[112:113], 0.5 op_sel_hi:[1,0]
	v_pk_mul_f32 v[194:195], v[110:111], 0.5 op_sel_hi:[1,0]
	v_pk_mul_f32 v[192:193], v[104:105], 0.5 op_sel_hi:[1,0]
	v_pk_mul_f32 v[190:191], v[102:103], 0.5 op_sel_hi:[1,0]
	v_pk_mul_f32 v[180:181], v[120:121], 0.5 op_sel_hi:[1,0]
	v_pk_mul_f32 v[178:179], v[118:119], 0.5 op_sel_hi:[1,0]
	v_pk_mul_f32 v[176:177], v[116:117], 0.5 op_sel_hi:[1,0]
	v_pk_mul_f32 v[174:175], v[114:115], 0.5 op_sel_hi:[1,0]
	v_pk_mul_f32 v[170:171], v[96:97], 0.5 op_sel_hi:[1,0]
	v_pk_mul_f32 v[168:169], v[94:95], 0.5 op_sel_hi:[1,0]
	v_pk_mul_f32 v[166:167], v[88:89], 0.5 op_sel_hi:[1,0]
	v_pk_mul_f32 v[164:165], v[86:87], 0.5 op_sel_hi:[1,0]
	v_pk_mul_f32 v[162:163], v[108:109], 0.5 op_sel_hi:[1,0]
	v_pk_mul_f32 v[160:161], v[106:107], 0.5 op_sel_hi:[1,0]
	v_pk_mul_f32 v[158:159], v[100:101], 0.5 op_sel_hi:[1,0]
	v_pk_mul_f32 v[156:157], v[98:99], 0.5 op_sel_hi:[1,0]
	v_pk_mul_f32 v[154:155], v[80:81], 0.5 op_sel_hi:[1,0]
	v_pk_mul_f32 v[152:153], v[78:79], 0.5 op_sel_hi:[1,0]
	v_pk_mul_f32 v[150:151], v[76:77], 0.5 op_sel_hi:[1,0]
	v_pk_mul_f32 v[148:149], v[74:75], 0.5 op_sel_hi:[1,0]
	v_pk_mul_f32 v[144:145], v[92:93], 0.5 op_sel_hi:[1,0]
	v_pk_mul_f32 v[142:143], v[90:91], 0.5 op_sel_hi:[1,0]
	v_pk_mul_f32 v[140:141], v[84:85], 0.5 op_sel_hi:[1,0]
	v_pk_mul_f32 v[138:139], v[82:83], 0.5 op_sel_hi:[1,0]
	v_pk_mul_f32 v[136:137], v[72:73], 0.5 op_sel_hi:[1,0]
	v_pk_mul_f32 v[134:135], v[70:71], 0.5 op_sel_hi:[1,0]
	v_pk_mul_f32 v[128:129], v[68:69], 0.5 op_sel_hi:[1,0]
	v_pk_mul_f32 v[126:127], v[66:67], 0.5 op_sel_hi:[1,0]
	v_pk_mul_f32 v[122:123], v[64:65], 0.5 op_sel_hi:[1,0]
	v_pk_mul_f32 v[120:121], v[62:63], 0.5 op_sel_hi:[1,0]
	v_pk_mul_f32 v[118:119], v[60:61], 0.5 op_sel_hi:[1,0]
	v_pk_mul_f32 v[116:117], v[58:59], 0.5 op_sel_hi:[1,0]
	v_pk_mul_f32 v[112:113], v[48:49], 0.5 op_sel_hi:[1,0]
	v_pk_mul_f32 v[110:111], v[46:47], 0.5 op_sel_hi:[1,0]
	v_pk_mul_f32 v[108:109], v[40:41], 0.5 op_sel_hi:[1,0]
	v_pk_mul_f32 v[106:107], v[38:39], 0.5 op_sel_hi:[1,0]
	v_pk_mul_f32 v[104:105], v[56:57], 0.5 op_sel_hi:[1,0]
	v_pk_mul_f32 v[102:103], v[54:55], 0.5 op_sel_hi:[1,0]
	v_pk_mul_f32 v[100:101], v[52:53], 0.5 op_sel_hi:[1,0]
	v_pk_mul_f32 v[98:99], v[50:51], 0.5 op_sel_hi:[1,0]
	v_pk_mul_f32 v[96:97], v[32:33], 0.5 op_sel_hi:[1,0]
	v_pk_mul_f32 v[94:95], v[30:31], 0.5 op_sel_hi:[1,0]
	v_pk_mul_f32 v[92:93], v[24:25], 0.5 op_sel_hi:[1,0]
	v_pk_mul_f32 v[90:91], v[22:23], 0.5 op_sel_hi:[1,0]
	v_pk_mul_f32 v[88:89], v[44:45], 0.5 op_sel_hi:[1,0]
	v_pk_mul_f32 v[86:87], v[42:43], 0.5 op_sel_hi:[1,0]
	v_pk_mul_f32 v[84:85], v[36:37], 0.5 op_sel_hi:[1,0]
	v_pk_mul_f32 v[82:83], v[34:35], 0.5 op_sel_hi:[1,0]
	v_pk_mul_f32 v[80:81], v[16:17], 0.5 op_sel_hi:[1,0]
	v_pk_mul_f32 v[78:79], v[14:15], 0.5 op_sel_hi:[1,0]
	v_pk_mul_f32 v[76:77], v[12:13], 0.5 op_sel_hi:[1,0]
	v_pk_mul_f32 v[74:75], v[10:11], 0.5 op_sel_hi:[1,0]
	v_pk_mul_f32 v[72:73], v[28:29], 0.5 op_sel_hi:[1,0]
	v_pk_mul_f32 v[70:71], v[26:27], 0.5 op_sel_hi:[1,0]
	v_pk_mul_f32 v[68:69], v[20:21], 0.5 op_sel_hi:[1,0]
	v_pk_mul_f32 v[66:67], v[18:19], 0.5 op_sel_hi:[1,0]
	v_pk_mul_f32 v[64:65], v[8:9], 0.5 op_sel_hi:[1,0]
	v_pk_mul_f32 v[62:63], v[6:7], 0.5 op_sel_hi:[1,0]
	v_pk_mul_f32 v[60:61], v[4:5], 0.5 op_sel_hi:[1,0]
	v_pk_mul_f32 v[58:59], v[2:3], 0.5 op_sel_hi:[1,0]
	s_and_b64 vcc, exec, s[40:41]
	s_cbranch_vccz .LBB0_1522
